# speedup vs baseline: 1.0187x; 1.0187x over previous
; template <int EPI, int PN>
; __device__ void gemm_phase(const Params& p, const u16* __restrict__ A, const u16* __restrict__ Bt, int nNt, char* smem) {
;     ...
;   for (int q = jb;; q += NJ) {
;     const int pl = q / (4 * PN), w = q % (4 * PN);
;     const int gp = pl * 8 + xcd;
;     if (gp >= npatch) break;
;     const int mt = (gp / npn) * 4 + (w & 3), nt = (gp % npn) * PN + (w >> 2);
;     const int gch = sch ^ ((srow >> 1) & 7);
;     const u16* Ag0 = A + (size_t)(mt * 256 + srow) * LDK + gch * 8;
;     const u16* Bg0 = Bt + (size_t)(nt * 256 + srow) * LDK + gch * 8;
;     f32x16 acc[4][2];
; #pragma unroll
;     for (int i = 0; i < 4; ++i)
; #pragma unroll
;       for (int j = 0; j < 2; ++j) acc[i][j] = zero16();
;     asm volatile("s_waitcnt vmcnt(0)" ::: "memory");
; #pragma unroll
;     for (int i = 0; i < 4; ++i) {
;       glds16(Ag0 + (size_t)i * 64 * LDK, ring + (srow + 64 * i) * 64 + sch * 8);
;       glds16(Bg0 + (size_t)i * 64 * LDK, ring + 16384 + (srow + 64 * i) * 64 + sch * 8);
;     }
;     ...
;           if (pre && (i & 1) == 0) {
;             const int pi = ks * 2 + (i >> 1);
;             if (pi < 4) glds16(Ag0 + (size_t)pi * 64 * LDK + (kt + 1) * 64, st + (srow + 64 * pi) * 64 + sch * 8);
;             else glds16(Bg0 + (size_t)(pi - 4) * 64 * LDK + (kt + 1) * 64, st + 16384 + (srow + 64 * (pi - 4)) * 64 + sch * 8);
;             __builtin_amdgcn_sched_barrier(0);
.LBB0_128:
	s_mul_hi_i32 s10, s19, 0xb21642c9
	s_add_i32 s10, s10, s19
	s_lshr_b32 s11, s10, 31
	s_ashr_i32 s10, s10, 6
	s_add_i32 s10, s10, s11
	s_mulk_i32 s10, 0x5c
	s_sub_i32 s11, s19, s10
	s_lshl_b32 s10, s12, 2
	s_and_b32 s13, s11, 3
	s_or_b32 s10, s13, s10
	s_ashr_i32 s11, s11, 2
	v_lshl_add_u32 v0, s10, 8, v141
	v_lshl_add_u32 v6, s11, 8, v141
	v_mad_i64_i32 v[0:1], s[20:21], v0, s0, v[130:131]
	v_mad_i64_i32 v[2:3], s[20:21], v6, s0, v[132:133]
	s_waitcnt vmcnt(0)
	v_readfirstlane_b32 s20, v136
	s_mov_b32 s21, m0
	s_mov_b32 m0, s20
	s_nop 0
	global_load_lds_dwordx4 v[0:1], off
	s_mov_b32 m0, s21
	v_readfirstlane_b32 s20, v138
	s_mov_b32 s21, m0
	s_mov_b32 m0, s20
	s_nop 0
	global_load_lds_dwordx4 v[2:3], off
	s_mov_b32 m0, s21
	v_lshl_add_u64 v[4:5], v[0:1], 0, s[2:3]
	v_readfirstlane_b32 s20, v140
	s_mov_b32 s21, m0
	s_mov_b32 m0, s20
	s_nop 0
	global_load_lds_dwordx4 v[4:5], off
	s_mov_b32 m0, s21
	v_lshl_add_u64 v[4:5], v[2:3], 0, s[2:3]
	v_readfirstlane_b32 s20, v142
	s_mov_b32 s21, m0
	s_mov_b32 m0, s20
	s_nop 0
	global_load_lds_dwordx4 v[4:5], off
	s_mov_b32 m0, s21
	v_lshl_add_u64 v[4:5], v[0:1], 0, s[4:5]
	v_readfirstlane_b32 s20, v144
	s_mov_b32 s21, m0
	s_mov_b32 m0, s20
	s_nop 0
	global_load_lds_dwordx4 v[4:5], off
	s_mov_b32 m0, s21
	v_lshl_add_u64 v[4:5], v[2:3], 0, s[4:5]
	v_readfirstlane_b32 s20, v146
	s_mov_b32 s21, m0
	s_mov_b32 m0, s20
	s_nop 0
	global_load_lds_dwordx4 v[4:5], off
	s_mov_b32 m0, s21
	v_lshl_add_u64 v[0:1], v[0:1], 0, s[6:7]
	s_lshl_b32 s12, s12, 10
	s_lshl_b32 s13, s13, 8
	v_readfirstlane_b32 s20, v148
	s_mov_b32 s21, m0
	s_mov_b32 m0, s20
	s_nop 0
	global_load_lds_dwordx4 v[0:1], off
	s_mov_b32 m0, s21
	v_lshl_add_u64 v[0:1], v[2:3], 0, s[6:7]
	s_or_b32 s12, s13, s12
	v_readfirstlane_b32 s20, v150
	s_mov_b32 s21, m0
	s_mov_b32 m0, s20
	s_nop 0
	global_load_lds_dwordx4 v[0:1], off
	s_mov_b32 m0, s21
	v_add_u32_e32 v0, s12, v141
	v_mad_i64_i32 v[158:159], s[12:13], v0, s0, v[152:153]
	v_mad_i64_i32 v[160:161], s[12:13], v6, s0, v[154:155]
	s_mov_b32 s12, 0x8000
	v_mov_b32_e32 v48, 0
	v_mov_b32_e32 v49, v129
	v_mov_b32_e32 v50, v129
	v_mov_b32_e32 v51, v129
	v_mov_b32_e32 v52, v129
	v_mov_b32_e32 v53, v129
	v_mov_b32_e32 v54, v129
	v_mov_b32_e32 v55, v129
	v_mov_b32_e32 v56, v129
	v_mov_b32_e32 v57, v129
	v_mov_b32_e32 v58, v129
	v_mov_b32_e32 v59, v129
	v_mov_b32_e32 v60, v129
	v_mov_b32_e32 v61, v129
	v_mov_b32_e32 v62, v129
	v_mov_b32_e32 v63, v129
	v_mov_b32_e32 v0, 0
	v_mov_b32_e32 v1, v129
	v_mov_b32_e32 v2, v129
	v_mov_b32_e32 v3, v129
	v_mov_b32_e32 v4, v129
	v_mov_b32_e32 v5, v129
	v_mov_b32_e32 v6, v129
	v_mov_b32_e32 v7, v129
	v_mov_b32_e32 v8, v129
	v_mov_b32_e32 v9, v129
	v_mov_b32_e32 v10, v129
	v_mov_b32_e32 v11, v129
	v_mov_b32_e32 v12, v129
	v_mov_b32_e32 v13, v129
	v_mov_b32_e32 v14, v129
	v_mov_b32_e32 v15, v129
	v_mov_b32_e32 v80, 0
	v_mov_b32_e32 v81, v129
	v_mov_b32_e32 v82, v129
	v_mov_b32_e32 v83, v129
	v_mov_b32_e32 v84, v129
	v_mov_b32_e32 v85, v129
	v_mov_b32_e32 v86, v129
	v_mov_b32_e32 v87, v129
	v_mov_b32_e32 v88, v129
	v_mov_b32_e32 v89, v129
	v_mov_b32_e32 v90, v129
	v_mov_b32_e32 v91, v129
	v_mov_b32_e32 v92, v129
	v_mov_b32_e32 v93, v129
	v_mov_b32_e32 v94, v129
	v_mov_b32_e32 v95, v129
	v_mov_b32_e32 v16, 0
	v_mov_b32_e32 v17, v129
	v_mov_b32_e32 v18, v129
	v_mov_b32_e32 v19, v129
	v_mov_b32_e32 v20, v129
	v_mov_b32_e32 v21, v129
	v_mov_b32_e32 v22, v129
	v_mov_b32_e32 v23, v129
	v_mov_b32_e32 v24, v129
	v_mov_b32_e32 v25, v129
	v_mov_b32_e32 v26, v129
	v_mov_b32_e32 v27, v129
	v_mov_b32_e32 v28, v129
	v_mov_b32_e32 v29, v129
	v_mov_b32_e32 v30, v129
	v_mov_b32_e32 v31, v129
	v_mov_b32_e32 v96, 0
	v_mov_b32_e32 v97, v129
	v_mov_b32_e32 v98, v129
	v_mov_b32_e32 v99, v129
	v_mov_b32_e32 v100, v129
	v_mov_b32_e32 v101, v129
	v_mov_b32_e32 v102, v129
	v_mov_b32_e32 v103, v129
	v_mov_b32_e32 v104, v129
	v_mov_b32_e32 v105, v129
	v_mov_b32_e32 v106, v129
	v_mov_b32_e32 v107, v129
	v_mov_b32_e32 v108, v129
	v_mov_b32_e32 v109, v129
	v_mov_b32_e32 v110, v129
	v_mov_b32_e32 v111, v129
	v_mov_b32_e32 v32, 0
	v_mov_b32_e32 v33, v129
	v_mov_b32_e32 v34, v129
	v_mov_b32_e32 v35, v129
	v_mov_b32_e32 v36, v129
	v_mov_b32_e32 v37, v129
	v_mov_b32_e32 v38, v129
	v_mov_b32_e32 v39, v129
	v_mov_b32_e32 v40, v129
	v_mov_b32_e32 v41, v129
	v_mov_b32_e32 v42, v129
	v_mov_b32_e32 v43, v129
	v_mov_b32_e32 v44, v129
	v_mov_b32_e32 v45, v129
	v_mov_b32_e32 v46, v129
	v_mov_b32_e32 v47, v129
	v_mov_b32_e32 v112, 0
	v_mov_b32_e32 v113, v129
	v_mov_b32_e32 v114, v129
	v_mov_b32_e32 v115, v129
	v_mov_b32_e32 v116, v129
	v_mov_b32_e32 v117, v129
	v_mov_b32_e32 v118, v129
	v_mov_b32_e32 v119, v129
	v_mov_b32_e32 v120, v129
	v_mov_b32_e32 v121, v129
	v_mov_b32_e32 v122, v129
	v_mov_b32_e32 v123, v129
	v_mov_b32_e32 v124, v129
	v_mov_b32_e32 v125, v129
	v_mov_b32_e32 v126, v129
	v_mov_b32_e32 v127, v129
	v_mov_b32_e32 v64, 0
	v_mov_b32_e32 v65, v129
	v_mov_b32_e32 v66, v129
	v_mov_b32_e32 v67, v129
	v_mov_b32_e32 v68, v129
	v_mov_b32_e32 v69, v129
	v_mov_b32_e32 v70, v129
	v_mov_b32_e32 v71, v129
	v_mov_b32_e32 v72, v129
	v_mov_b32_e32 v73, v129
	v_mov_b32_e32 v74, v129
	v_mov_b32_e32 v75, v129
	v_mov_b32_e32 v76, v129
	v_mov_b32_e32 v77, v129
	v_mov_b32_e32 v78, v129
	v_mov_b32_e32 v79, v129
	v_readfirstlane_b32 s99, v136
	s_add_i32 s99, s99, 0x10000
	s_mov_b32 s20, m0
	s_mov_b32 m0, s99
	s_nop 0
	global_load_lds_dwordx4 v[158:159], off
	v_lshl_add_u64 v[232:233], v[158:159], 0, s[2:3]
	s_add_i32 m0, s99, 0x2000
	s_nop 0
	global_load_lds_dwordx4 v[232:233], off
	v_lshl_add_u64 v[234:235], v[158:159], 0, s[4:5]
	s_add_i32 m0, s99, 0x4000
	s_nop 0
	global_load_lds_dwordx4 v[234:235], off
	v_lshl_add_u64 v[232:233], v[158:159], 0, s[6:7]
	s_add_i32 m0, s99, 0x6000
	s_nop 0
	global_load_lds_dwordx4 v[232:233], off
	s_add_i32 m0, s99, 0x8000
	s_nop 0
	global_load_lds_dwordx4 v[160:161], off
	v_lshl_add_u64 v[234:235], v[160:161], 0, s[2:3]
	s_add_i32 m0, s99, 0xa000
	s_nop 0
	global_load_lds_dwordx4 v[234:235], off
	v_lshl_add_u64 v[232:233], v[160:161], 0, s[4:5]
	s_add_i32 m0, s99, 0xc000
	s_nop 0
	global_load_lds_dwordx4 v[232:233], off
	v_lshl_add_u64 v[234:235], v[160:161], 0, s[6:7]
	s_add_i32 m0, s99, 0xe000
	s_nop 0
	global_load_lds_dwordx4 v[234:235], off
	s_mov_b32 m0, s20
	v_lshl_add_u64 v[158:159], v[158:159], 0, s[8:9]
	v_lshl_add_u64 v[160:161], v[160:161], 0, s[8:9]
	s_waitcnt vmcnt(0)
	s_barrier
; template <int EPI, int PN>
; __device__ void gemm_phase(const Params& p, const u16* __restrict__ A, const u16* __restrict__ Bt, int nNt, char* smem) {
;     ...
;     for (int kt = 0; kt < 32; ++kt) {
;       asm volatile("s_waitcnt vmcnt(0)" ::: "memory");
;       __builtin_amdgcn_s_barrier();
;       const u16* Ab = ring + (kt & 1) * STG;
;       const u16* Bb = Ab + 16384;
;       u16* st = ring + ((kt + 1) & 1) * STG;
;       const bool pre = (kt + 1 < 32);
;       s16x8 af[2][4], bf[2][2];
;       auto ldfrag = [&](int ks, int slot) {
; #pragma unroll
;         for (int i = 0; i < 4; ++i) {
;           const int row = wr * 128 + i * 32 + lr;
;           af[slot][i] = *(const s16x8*)(Ab + row * 64 + (((ks * 2 + lh) ^ ((row >> 1) & 7)) * 8));
;         }
; #pragma unroll
;         for (int j = 0; j < 2; ++j) {
;           const int rowb = nh * 128 + wc * 64 + j * 32 + lr;
;           bf[slot][j] = *(const s16x8*)(Bb + rowb * 64 + (((ks * 2 + lh) ^ ((rowb >> 1) & 7)) * 8));
;         }
;       };
;       ldfrag(0, 0);
;       ldfrag(1, 1);
;       __builtin_amdgcn_sched_barrier(0);
; #pragma unroll
;       for (int ks = 0; ks < 4; ++ks) {
;         const int slot = ks & 1;
; #pragma unroll
;         for (int i = 0; i < 4; ++i) {
;           acc[i][0] = mfma32(af[slot][i], bf[slot][0], acc[i][0]);
;           acc[i][1] = mfma32(af[slot][i], bf[slot][1], acc[i][1]);
;           __builtin_amdgcn_sched_barrier(0);
;           if (pre && (i & 1) == 0) {
;             const int pi = ks * 2 + (i >> 1);
;             if (pi < 4) glds16(Ag0 + (size_t)pi * 64 * LDK + (kt + 1) * 64, st + (srow + 64 * pi) * 64 + sch * 8);
;             else glds16(Bg0 + (size_t)(pi - 4) * 64 * LDK + (kt + 1) * 64, st + 16384 + (srow + 64 * (pi - 4)) * 64 + sch * 8);
;             __builtin_amdgcn_sched_barrier(0);
;           }
;         }
;         if (ks + 2 < 4) { ldfrag(ks + 2, slot); __builtin_amdgcn_sched_barrier(0); }
;       }
	v_lshlrev_b32_e32 v227, 1, v143
	v_lshlrev_b32_e32 v229, 1, v147
	v_add_u32_e32 v228, v227, v173
	v_add_u32_e32 v230, v229, v173
	ds_read_b128 v[178:181], v228
	ds_read_b128 v[182:185], v228 offset:4096
	ds_read_b128 v[186:189], v228 offset:8192
	ds_read_b128 v[190:193], v228 offset:12288
	ds_read_b128 v[194:197], v230 offset:32768
	ds_read_b128 v[198:201], v230 offset:36864
	v_add_u32_e32 v228, v227, v174
	v_add_u32_e32 v230, v229, v174
	ds_read_b128 v[202:205], v228
	ds_read_b128 v[206:209], v228 offset:4096
	ds_read_b128 v[210:213], v228 offset:8192
	ds_read_b128 v[214:217], v228 offset:12288
	ds_read_b128 v[218:221], v230 offset:32768
	ds_read_b128 v[222:225], v230 offset:36864
.Lrot129_loop:
	s_add_i32 s13, s12, 0xffff8000
	s_and_b32 s13, s13, 0x8000
	s_lshl_b32 s13, s13, 1
	v_lshl_or_b32 v128, v143, 1, s13
	v_lshl_add_u32 v149, v147, 1, s13
	s_waitcnt lgkmcnt(7)
	v_mfma_f32_32x32x16_bf16 v[64:79], v[178:181], v[194:197], v[64:79]
	s_waitcnt lgkmcnt(6)
	v_mfma_f32_32x32x16_bf16 v[112:127], v[178:181], v[198:201], v[112:127]
	v_mfma_f32_32x32x16_bf16 v[32:47], v[182:185], v[194:197], v[32:47]
	v_mfma_f32_32x32x16_bf16 v[96:111], v[182:185], v[198:201], v[96:111]
	v_mfma_f32_32x32x16_bf16 v[16:31], v[186:189], v[194:197], v[16:31]
	v_mfma_f32_32x32x16_bf16 v[80:95], v[186:189], v[198:201], v[80:95]
	v_mfma_f32_32x32x16_bf16 v[0:15], v[190:193], v[194:197], v[0:15]
	v_mfma_f32_32x32x16_bf16 v[48:63], v[190:193], v[198:201], v[48:63]
	v_add_u32_e32 v177, v128, v175
	ds_read_b128 v[178:181], v177
	ds_read_b128 v[182:185], v177 offset:4096
	ds_read_b128 v[186:189], v177 offset:8192
	ds_read_b128 v[190:193], v177 offset:12288
	v_add_u32_e32 v177, v149, v175
	ds_read_b128 v[194:197], v177 offset:32768
	ds_read_b128 v[198:201], v177 offset:36864
	s_waitcnt lgkmcnt(7)
	v_mfma_f32_32x32x16_bf16 v[64:79], v[202:205], v[218:221], v[64:79]
	s_waitcnt lgkmcnt(6)
	v_mfma_f32_32x32x16_bf16 v[112:127], v[202:205], v[222:225], v[112:127]
	v_mfma_f32_32x32x16_bf16 v[32:47], v[206:209], v[218:221], v[32:47]
	v_mfma_f32_32x32x16_bf16 v[96:111], v[206:209], v[222:225], v[96:111]
	v_mfma_f32_32x32x16_bf16 v[16:31], v[210:213], v[218:221], v[16:31]
	v_mfma_f32_32x32x16_bf16 v[80:95], v[210:213], v[222:225], v[80:95]
	v_mfma_f32_32x32x16_bf16 v[0:15], v[214:217], v[218:221], v[0:15]
	v_mfma_f32_32x32x16_bf16 v[48:63], v[214:217], v[222:225], v[48:63]
	v_add_u32_e32 v128, v128, v176
	ds_read_b128 v[202:205], v128
	ds_read_b128 v[206:209], v128 offset:4096
	ds_read_b128 v[210:213], v128 offset:8192
	ds_read_b128 v[214:217], v128 offset:12288
	v_add_u32_e32 v128, v149, v176
	ds_read_b128 v[218:221], v128 offset:32768
	ds_read_b128 v[222:225], v128 offset:36864
	s_waitcnt lgkmcnt(7)
	v_mfma_f32_32x32x16_bf16 v[64:79], v[178:181], v[194:197], v[64:79]
	s_waitcnt lgkmcnt(6)
	v_mfma_f32_32x32x16_bf16 v[112:127], v[178:181], v[198:201], v[112:127]
	v_mfma_f32_32x32x16_bf16 v[32:47], v[182:185], v[194:197], v[32:47]
	v_mfma_f32_32x32x16_bf16 v[96:111], v[182:185], v[198:201], v[96:111]
	v_mfma_f32_32x32x16_bf16 v[16:31], v[186:189], v[194:197], v[16:31]
	v_mfma_f32_32x32x16_bf16 v[80:95], v[186:189], v[198:201], v[80:95]
	v_mfma_f32_32x32x16_bf16 v[0:15], v[190:193], v[194:197], v[0:15]
	v_mfma_f32_32x32x16_bf16 v[48:63], v[190:193], v[198:201], v[48:63]
	s_waitcnt vmcnt(0) lgkmcnt(0)
	s_barrier
	s_and_b32 s98, s12, 0x8000
	s_lshl_b32 s98, s98, 1
	v_lshl_or_b32 v227, v143, 1, s98
	v_lshl_add_u32 v229, v147, 1, s98
	v_add_u32_e32 v228, v227, v173
	v_add_u32_e32 v230, v229, v173
	ds_read_b128 v[178:181], v228
	ds_read_b128 v[182:185], v228 offset:4096
	ds_read_b128 v[186:189], v228 offset:8192
	ds_read_b128 v[190:193], v228 offset:12288
	ds_read_b128 v[194:197], v230 offset:32768
	ds_read_b128 v[198:201], v230 offset:36864
	v_add3_u32 v226, s13, v162, v156
	v_mfma_f32_32x32x16_bf16 v[64:79], v[202:205], v[218:221], v[64:79]
	v_readfirstlane_b32 s99, v226
	s_mov_b32 s20, m0
	s_mov_b32 m0, s99
	s_nop 0
	global_load_lds_dwordx4 v[158:159], off
	v_mfma_f32_32x32x16_bf16 v[112:127], v[202:205], v[222:225], v[112:127]
	v_lshl_add_u64 v[232:233], v[158:159], 0, s[2:3]
	s_add_i32 m0, s99, 0x2000
	s_nop 0
	global_load_lds_dwordx4 v[232:233], off
	v_mfma_f32_32x32x16_bf16 v[32:47], v[206:209], v[218:221], v[32:47]
	v_lshl_add_u64 v[234:235], v[158:159], 0, s[4:5]
	s_add_i32 m0, s99, 0x4000
	s_nop 0
	global_load_lds_dwordx4 v[234:235], off
	v_mfma_f32_32x32x16_bf16 v[96:111], v[206:209], v[222:225], v[96:111]
	v_lshl_add_u64 v[232:233], v[158:159], 0, s[6:7]
	s_add_i32 m0, s99, 0x6000
	s_nop 0
	global_load_lds_dwordx4 v[232:233], off
	v_mfma_f32_32x32x16_bf16 v[16:31], v[210:213], v[218:221], v[16:31]
	s_add_i32 m0, s99, 0x8000
	s_nop 0
	global_load_lds_dwordx4 v[160:161], off
	v_mfma_f32_32x32x16_bf16 v[80:95], v[210:213], v[222:225], v[80:95]
	v_lshl_add_u64 v[234:235], v[160:161], 0, s[2:3]
	s_add_i32 m0, s99, 0xa000
	s_nop 0
	global_load_lds_dwordx4 v[234:235], off
	v_mfma_f32_32x32x16_bf16 v[0:15], v[214:217], v[218:221], v[0:15]
	v_lshl_add_u64 v[232:233], v[160:161], 0, s[4:5]
	s_add_i32 m0, s99, 0xc000
	s_nop 0
	global_load_lds_dwordx4 v[232:233], off
	v_mfma_f32_32x32x16_bf16 v[48:63], v[214:217], v[222:225], v[48:63]
	v_lshl_add_u64 v[234:235], v[160:161], 0, s[6:7]
	s_add_i32 m0, s99, 0xe000
	s_nop 0
	global_load_lds_dwordx4 v[234:235], off
	s_mov_b32 m0, s20
	v_add_u32_e32 v228, v227, v174
	v_add_u32_e32 v230, v229, v174
	ds_read_b128 v[202:205], v228
	ds_read_b128 v[206:209], v228 offset:4096
	ds_read_b128 v[210:213], v228 offset:8192
	ds_read_b128 v[214:217], v228 offset:12288
	ds_read_b128 v[218:221], v230 offset:32768
	ds_read_b128 v[222:225], v230 offset:36864
	s_add_i32 s12, s12, 0x8000
	v_lshl_add_u64 v[158:159], v[158:159], 0, s[8:9]
	s_cmp_eq_u32 s12, 0xf8000
	v_lshl_add_u64 v[160:161], v[160:161], 0, s[8:9]
	s_cbranch_scc0 .Lrot129_loop
; template <int EPI, int PN>
; __device__ void gemm_phase(const Params& p, const u16* __restrict__ A, const u16* __restrict__ Bt, int nNt, char* smem) {
;     ...
;       for (int ks = 0; ks < 4; ++ks) {
;         const int slot = ks & 1;
; #pragma unroll
;         for (int i = 0; i < 4; ++i) {
;           acc[i][0] = mfma32(af[slot][i], bf[slot][0], acc[i][0]);
;           acc[i][1] = mfma32(af[slot][i], bf[slot][1], acc[i][1]);
;           __builtin_amdgcn_sched_barrier(0);
;           if (pre && (i & 1) == 0) {
;             const int pi = ks * 2 + (i >> 1);
;             if (pi < 4) glds16(Ag0 + (size_t)pi * 64 * LDK + (kt + 1) * 64, st + (srow + 64 * pi) * 64 + sch * 8);
;             else glds16(Bg0 + (size_t)(pi - 4) * 64 * LDK + (kt + 1) * 64, st + 16384 + (srow + 64 * (pi - 4)) * 64 + sch * 8);
;             __builtin_amdgcn_sched_barrier(0);
;           }
;         }
;         if (ks + 2 < 4) { ldfrag(ks + 2, slot); __builtin_amdgcn_sched_barrier(0); }
;       }
;     }
;     __syncthreads();
	s_add_i32 s13, s12, 0xffff8000
	s_and_b32 s13, s13, 0x8000
	s_lshl_b32 s13, s13, 1
	v_lshl_or_b32 v128, v143, 1, s13
	v_lshl_add_u32 v149, v147, 1, s13
	s_waitcnt lgkmcnt(7)
	v_mfma_f32_32x32x16_bf16 v[64:79], v[178:181], v[194:197], v[64:79]
	s_waitcnt lgkmcnt(6)
	v_mfma_f32_32x32x16_bf16 v[112:127], v[178:181], v[198:201], v[112:127]
	v_mfma_f32_32x32x16_bf16 v[32:47], v[182:185], v[194:197], v[32:47]
	v_mfma_f32_32x32x16_bf16 v[96:111], v[182:185], v[198:201], v[96:111]
	v_mfma_f32_32x32x16_bf16 v[16:31], v[186:189], v[194:197], v[16:31]
	v_mfma_f32_32x32x16_bf16 v[80:95], v[186:189], v[198:201], v[80:95]
	v_mfma_f32_32x32x16_bf16 v[0:15], v[190:193], v[194:197], v[0:15]
	v_mfma_f32_32x32x16_bf16 v[48:63], v[190:193], v[198:201], v[48:63]
	v_add_u32_e32 v177, v128, v175
	ds_read_b128 v[178:181], v177
	ds_read_b128 v[182:185], v177 offset:4096
	ds_read_b128 v[186:189], v177 offset:8192
	ds_read_b128 v[190:193], v177 offset:12288
	v_add_u32_e32 v177, v149, v175
	ds_read_b128 v[194:197], v177 offset:32768
	ds_read_b128 v[198:201], v177 offset:36864
	s_waitcnt lgkmcnt(7)
	v_mfma_f32_32x32x16_bf16 v[64:79], v[202:205], v[218:221], v[64:79]
	s_waitcnt lgkmcnt(6)
	v_mfma_f32_32x32x16_bf16 v[112:127], v[202:205], v[222:225], v[112:127]
	v_mfma_f32_32x32x16_bf16 v[32:47], v[206:209], v[218:221], v[32:47]
	v_mfma_f32_32x32x16_bf16 v[96:111], v[206:209], v[222:225], v[96:111]
	v_mfma_f32_32x32x16_bf16 v[16:31], v[210:213], v[218:221], v[16:31]
	v_mfma_f32_32x32x16_bf16 v[80:95], v[210:213], v[222:225], v[80:95]
	v_mfma_f32_32x32x16_bf16 v[0:15], v[214:217], v[218:221], v[0:15]
	v_mfma_f32_32x32x16_bf16 v[48:63], v[214:217], v[222:225], v[48:63]
	v_add_u32_e32 v128, v128, v176
	ds_read_b128 v[202:205], v128
	ds_read_b128 v[206:209], v128 offset:4096
	ds_read_b128 v[210:213], v128 offset:8192
	ds_read_b128 v[214:217], v128 offset:12288
	v_add_u32_e32 v128, v149, v176
	ds_read_b128 v[218:221], v128 offset:32768
	ds_read_b128 v[222:225], v128 offset:36864
	s_waitcnt lgkmcnt(7)
	v_mfma_f32_32x32x16_bf16 v[64:79], v[178:181], v[194:197], v[64:79]
	s_waitcnt lgkmcnt(6)
	v_mfma_f32_32x32x16_bf16 v[112:127], v[178:181], v[198:201], v[112:127]
	v_mfma_f32_32x32x16_bf16 v[32:47], v[182:185], v[194:197], v[32:47]
	v_mfma_f32_32x32x16_bf16 v[96:111], v[182:185], v[198:201], v[96:111]
	v_mfma_f32_32x32x16_bf16 v[16:31], v[186:189], v[194:197], v[16:31]
	v_mfma_f32_32x32x16_bf16 v[80:95], v[186:189], v[198:201], v[80:95]
	v_mfma_f32_32x32x16_bf16 v[0:15], v[190:193], v[194:197], v[0:15]
	v_mfma_f32_32x32x16_bf16 v[48:63], v[190:193], v[198:201], v[48:63]
	s_waitcnt lgkmcnt(1)
	v_mfma_f32_32x32x16_bf16 v[64:79], v[202:205], v[218:221], v[64:79]
	s_waitcnt lgkmcnt(0)
	v_mfma_f32_32x32x16_bf16 v[112:127], v[202:205], v[222:225], v[112:127]
	v_mfma_f32_32x32x16_bf16 v[32:47], v[206:209], v[218:221], v[32:47]
	v_mfma_f32_32x32x16_bf16 v[96:111], v[206:209], v[222:225], v[96:111]
	v_mfma_f32_32x32x16_bf16 v[16:31], v[210:213], v[218:221], v[16:31]
	v_mfma_f32_32x32x16_bf16 v[80:95], v[210:213], v[222:225], v[80:95]
	v_mfma_f32_32x32x16_bf16 v[0:15], v[214:217], v[218:221], v[0:15]
	v_mfma_f32_32x32x16_bf16 v[48:63], v[214:217], v[222:225], v[48:63]
	s_waitcnt vmcnt(0)
	s_barrier
	ds_read_b128 v[158:161], v164
	ds_read_b128 v[178:181], v164 offset:4096
	ds_read_b128 v[182:185], v164 offset:8192
	ds_read_b128 v[186:189], v164 offset:12288
	ds_read_b128 v[190:193], v165
	ds_read_b128 v[194:197], v165 offset:4096
	ds_read_b128 v[198:201], v166
	ds_read_b128 v[202:205], v166 offset:4096
	ds_read_b128 v[206:209], v166 offset:8192
	ds_read_b128 v[210:213], v166 offset:12288
	ds_read_b128 v[214:217], v168
	ds_read_b128 v[218:221], v168 offset:4096
	s_waitcnt lgkmcnt(7)
	v_mfma_f32_32x32x16_bf16 v[64:79], v[158:161], v[190:193], v[64:79]
	s_waitcnt lgkmcnt(6)
	v_mfma_f32_32x32x16_bf16 v[112:127], v[158:161], v[194:197], v[112:127]
	v_mfma_f32_32x32x16_bf16 v[32:47], v[178:181], v[190:193], v[32:47]
	v_mfma_f32_32x32x16_bf16 v[96:111], v[178:181], v[194:197], v[96:111]
	v_mfma_f32_32x32x16_bf16 v[16:31], v[182:185], v[190:193], v[16:31]
	v_mfma_f32_32x32x16_bf16 v[80:95], v[182:185], v[194:197], v[80:95]
	v_mfma_f32_32x32x16_bf16 v[0:15], v[186:189], v[190:193], v[0:15]
	v_mfma_f32_32x32x16_bf16 v[48:63], v[186:189], v[194:197], v[48:63]
	ds_read_b128 v[158:161], v169
	ds_read_b128 v[178:181], v169 offset:4096
	ds_read_b128 v[182:185], v169 offset:8192
	ds_read_b128 v[186:189], v169 offset:12288
	ds_read_b128 v[190:193], v170
	ds_read_b128 v[194:197], v170 offset:4096
	s_waitcnt lgkmcnt(7)
	v_mfma_f32_32x32x16_bf16 v[64:79], v[198:201], v[214:217], v[64:79]
	s_waitcnt lgkmcnt(6)
	v_mfma_f32_32x32x16_bf16 v[112:127], v[198:201], v[218:221], v[112:127]
	v_mfma_f32_32x32x16_bf16 v[32:47], v[202:205], v[214:217], v[32:47]
	v_mfma_f32_32x32x16_bf16 v[96:111], v[202:205], v[218:221], v[96:111]
	v_mfma_f32_32x32x16_bf16 v[16:31], v[206:209], v[214:217], v[16:31]
	v_mfma_f32_32x32x16_bf16 v[80:95], v[206:209], v[218:221], v[80:95]
	v_mfma_f32_32x32x16_bf16 v[0:15], v[210:213], v[214:217], v[0:15]
	v_mfma_f32_32x32x16_bf16 v[48:63], v[210:213], v[218:221], v[48:63]
	ds_read_b128 v[198:201], v171
	ds_read_b128 v[202:205], v171 offset:4096
	ds_read_b128 v[206:209], v171 offset:8192
	ds_read_b128 v[210:213], v171 offset:12288
	ds_read_b128 v[214:217], v172
	ds_read_b128 v[218:221], v172 offset:4096
	s_waitcnt lgkmcnt(7)
	v_mfma_f32_32x32x16_bf16 v[64:79], v[158:161], v[190:193], v[64:79]
	s_waitcnt lgkmcnt(6)
	v_mfma_f32_32x32x16_bf16 v[112:127], v[158:161], v[194:197], v[112:127]
	v_mfma_f32_32x32x16_bf16 v[32:47], v[178:181], v[190:193], v[32:47]
	v_mfma_f32_32x32x16_bf16 v[96:111], v[178:181], v[194:197], v[96:111]
	v_mfma_f32_32x32x16_bf16 v[16:31], v[182:185], v[190:193], v[16:31]
	v_mfma_f32_32x32x16_bf16 v[80:95], v[182:185], v[194:197], v[80:95]
	v_mfma_f32_32x32x16_bf16 v[0:15], v[186:189], v[190:193], v[0:15]
	v_mfma_f32_32x32x16_bf16 v[48:63], v[186:189], v[194:197], v[48:63]
	s_waitcnt lgkmcnt(1)
	v_mfma_f32_32x32x16_bf16 v[64:79], v[198:201], v[214:217], v[64:79]
	s_waitcnt lgkmcnt(0)
	v_mfma_f32_32x32x16_bf16 v[112:127], v[198:201], v[218:221], v[112:127]
	v_mfma_f32_32x32x16_bf16 v[32:47], v[202:205], v[214:217], v[32:47]
	v_mfma_f32_32x32x16_bf16 v[96:111], v[202:205], v[218:221], v[96:111]
	v_mfma_f32_32x32x16_bf16 v[16:31], v[206:209], v[214:217], v[16:31]
	v_mfma_f32_32x32x16_bf16 v[80:95], v[206:209], v[218:221], v[80:95]
	v_mfma_f32_32x32x16_bf16 v[0:15], v[210:213], v[214:217], v[0:15]
	v_mfma_f32_32x32x16_bf16 v[48:63], v[210:213], v[218:221], v[48:63]
	v_mov_b32_e32 v128, v139
	v_mov_b32_e32 v161, v137
	v_mov_b32_e32 v177, v135
	s_barrier
; __device__ __forceinline__ int accrow(int reg, int lh) { return (reg & 3) + 8 * (reg >> 2) + 4 * lh; }
; template <int EPI, int PN>
; __device__ void gemm_phase(const Params& p, const u16* __restrict__ A, const u16* __restrict__ Bt, int nNt, char* smem) {
;     ...
;     } else if (EPI == 0 && col0 >= NPROJ) {
; #pragma unroll
;       for (int i = 0; i < 4; ++i)
; #pragma unroll
;         for (int r = 0; r < 16; ++r) {
;           const size_t row = row0 + i * 32 + accrow(r, lhE);
;           const int col = col0 + lrE;
;           if (col < NIN) p.dtraw[row * 16 + (col - NPROJ)] = acc[i][0][r];
;         }
;     } else {
; #pragma unroll
;       for (int i = 0; i < 4; ++i)
; #pragma unroll
;         for (int j = 0; j < 2; ++j)
; #pragma unroll
;           for (int r = 0; r < 16; ++r) *(u16*)(et + (i * 32 + accrow(r, lhE)) * 144 + (j * 32 + lrE) * 2) = f2bf(acc[i][j][r]);
	s_nop 0
	v_lshl_add_u32 v160, s11, 8, v145
	s_ashr_i32 s11, s10, 31
	s_lshl_b64 s[10:11], s[10:11], 8
	v_mov_b32_e32 v159, s11
	v_or_b32_e32 v158, s10, v134
	v_cmp_gt_i32_e32 vcc, s14, v160
	s_and_saveexec_b64 s[10:11], vcc
	s_xor_b64 s[10:11], exec, s[10:11]
	s_cbranch_execz .LBB0_132
	v_lshlrev_b32_e32 v149, 1, v161
	v_mul_lo_u32 v128, v128, s15
	v_add3_u32 v128, v163, v149, v128
	v_cvt_pk_bf16_f32 v0, v0, s0
	v_cvt_pk_bf16_f32 v64, v64, s0
	v_cvt_pk_bf16_f32 v32, v32, s0
	v_cvt_pk_bf16_f32 v16, v16, s0
	ds_write_b16 v128, v0 offset:13824
	v_cvt_pk_bf16_f32 v0, v1, s0
	ds_write_b16 v128, v64
	v_cvt_pk_bf16_f32 v64, v65, s0
	ds_write_b16 v128, v32 offset:4608
	v_cvt_pk_bf16_f32 v32, v33, s0
	ds_write_b16 v128, v16 offset:9216
	v_cvt_pk_bf16_f32 v16, v17, s0
	ds_write_b16 v128, v0 offset:13968
	v_cvt_pk_bf16_f32 v0, v2, s0
	ds_write_b16 v128, v64 offset:144
	v_cvt_pk_bf16_f32 v64, v66, s0
	ds_write_b16 v128, v32 offset:4752
	v_cvt_pk_bf16_f32 v32, v34, s0
	ds_write_b16 v128, v16 offset:9360
	v_cvt_pk_bf16_f32 v16, v18, s0
	ds_write_b16 v128, v0 offset:14112
	v_cvt_pk_bf16_f32 v0, v3, s0
	ds_write_b16 v128, v64 offset:288
	v_cvt_pk_bf16_f32 v64, v67, s0
	ds_write_b16 v128, v32 offset:4896
	v_cvt_pk_bf16_f32 v32, v35, s0
	ds_write_b16 v128, v16 offset:9504
	v_cvt_pk_bf16_f32 v16, v19, s0
	ds_write_b16 v128, v0 offset:14256
	v_cvt_pk_bf16_f32 v0, v4, s0
	ds_write_b16 v128, v64 offset:432
	v_cvt_pk_bf16_f32 v64, v68, s0
	ds_write_b16 v128, v32 offset:5040
	v_cvt_pk_bf16_f32 v32, v36, s0
	ds_write_b16 v128, v16 offset:9648
	v_cvt_pk_bf16_f32 v16, v20, s0
	ds_write_b16 v128, v0 offset:14976
	v_cvt_pk_bf16_f32 v0, v5, s0
	ds_write_b16 v128, v64 offset:1152
	v_cvt_pk_bf16_f32 v64, v69, s0
	ds_write_b16 v128, v32 offset:5760
	v_cvt_pk_bf16_f32 v32, v37, s0
	ds_write_b16 v128, v16 offset:10368
	v_cvt_pk_bf16_f32 v16, v21, s0
	ds_write_b16 v128, v0 offset:15120
	v_cvt_pk_bf16_f32 v0, v6, s0
	ds_write_b16 v128, v64 offset:1296
	v_cvt_pk_bf16_f32 v64, v70, s0
	ds_write_b16 v128, v32 offset:5904
	v_cvt_pk_bf16_f32 v32, v38, s0
	ds_write_b16 v128, v16 offset:10512
	v_cvt_pk_bf16_f32 v16, v22, s0
	ds_write_b16 v128, v0 offset:15264
	v_cvt_pk_bf16_f32 v0, v7, s0
	ds_write_b16 v128, v64 offset:1440
	v_cvt_pk_bf16_f32 v64, v71, s0
	ds_write_b16 v128, v32 offset:6048
	v_cvt_pk_bf16_f32 v32, v39, s0
	ds_write_b16 v128, v16 offset:10656
	v_cvt_pk_bf16_f32 v16, v23, s0
	ds_write_b16 v128, v0 offset:15408
	v_cvt_pk_bf16_f32 v0, v8, s0
	ds_write_b16 v128, v64 offset:1584
	v_cvt_pk_bf16_f32 v64, v72, s0
	ds_write_b16 v128, v32 offset:6192
	v_cvt_pk_bf16_f32 v32, v40, s0
	ds_write_b16 v128, v16 offset:10800
	v_cvt_pk_bf16_f32 v16, v24, s0
	ds_write_b16 v128, v0 offset:16128
	v_cvt_pk_bf16_f32 v0, v9, s0
	ds_write_b16 v128, v64 offset:2304
	v_cvt_pk_bf16_f32 v64, v73, s0
	ds_write_b16 v128, v32 offset:6912
	v_cvt_pk_bf16_f32 v32, v41, s0
	ds_write_b16 v128, v16 offset:11520
	v_cvt_pk_bf16_f32 v16, v25, s0
	ds_write_b16 v128, v0 offset:16272
	v_cvt_pk_bf16_f32 v0, v10, s0
	ds_write_b16 v128, v64 offset:2448
	v_cvt_pk_bf16_f32 v64, v74, s0
	ds_write_b16 v128, v32 offset:7056
	v_cvt_pk_bf16_f32 v32, v42, s0
	ds_write_b16 v128, v16 offset:11664
	v_cvt_pk_bf16_f32 v16, v26, s0
	ds_write_b16 v128, v0 offset:16416
	v_cvt_pk_bf16_f32 v0, v11, s0
	ds_write_b16 v128, v64 offset:2592
	v_cvt_pk_bf16_f32 v64, v75, s0
	ds_write_b16 v128, v32 offset:7200
	v_cvt_pk_bf16_f32 v32, v43, s0
	ds_write_b16 v128, v16 offset:11808
	v_cvt_pk_bf16_f32 v16, v27, s0
	ds_write_b16 v128, v0 offset:16560
	v_cvt_pk_bf16_f32 v0, v12, s0
	ds_write_b16 v128, v64 offset:2736
	v_cvt_pk_bf16_f32 v64, v76, s0
	ds_write_b16 v128, v32 offset:7344
	v_cvt_pk_bf16_f32 v32, v44, s0
	ds_write_b16 v128, v16 offset:11952
	v_cvt_pk_bf16_f32 v16, v28, s0
	ds_write_b16 v128, v0 offset:17280
	v_cvt_pk_bf16_f32 v0, v13, s0
	ds_write_b16 v128, v64 offset:3456
	v_cvt_pk_bf16_f32 v64, v77, s0
	ds_write_b16 v128, v32 offset:8064
	v_cvt_pk_bf16_f32 v32, v45, s0
	ds_write_b16 v128, v16 offset:12672
	v_cvt_pk_bf16_f32 v16, v29, s0
	ds_write_b16 v128, v0 offset:17424
	v_cvt_pk_bf16_f32 v0, v14, s0
	ds_write_b16 v128, v64 offset:3600
	v_cvt_pk_bf16_f32 v64, v78, s0
	ds_write_b16 v128, v32 offset:8208
	v_cvt_pk_bf16_f32 v32, v46, s0
	ds_write_b16 v128, v16 offset:12816
	v_cvt_pk_bf16_f32 v16, v30, s0
	ds_write_b16 v128, v0 offset:17568
	v_cvt_pk_bf16_f32 v0, v15, s0
	ds_write_b16 v128, v64 offset:3744
	v_cvt_pk_bf16_f32 v64, v79, s0
	ds_write_b16 v128, v32 offset:8352
	v_cvt_pk_bf16_f32 v32, v47, s0
	ds_write_b16 v128, v16 offset:12960
	v_cvt_pk_bf16_f32 v16, v31, s0
	ds_write_b16 v128, v0 offset:17712
	v_cvt_pk_bf16_f32 v0, v48, s0
	ds_write_b16 v128, v64 offset:3888
	v_cvt_pk_bf16_f32 v64, v112, s0
	ds_write_b16 v128, v32 offset:8496
	v_cvt_pk_bf16_f32 v32, v96, s0
	ds_write_b16 v128, v16 offset:13104
	v_cvt_pk_bf16_f32 v16, v80, s0
	ds_write_b16 v128, v0 offset:13888
	v_cvt_pk_bf16_f32 v0, v49, s0
	ds_write_b16 v128, v64 offset:64
	v_cvt_pk_bf16_f32 v64, v113, s0
	ds_write_b16 v128, v32 offset:4672
	v_cvt_pk_bf16_f32 v32, v97, s0
	ds_write_b16 v128, v16 offset:9280
	v_cvt_pk_bf16_f32 v16, v81, s0
	ds_write_b16 v128, v0 offset:14032
	v_cvt_pk_bf16_f32 v0, v50, s0
	ds_write_b16 v128, v64 offset:208
	v_cvt_pk_bf16_f32 v64, v114, s0
	ds_write_b16 v128, v32 offset:4816
	v_cvt_pk_bf16_f32 v32, v98, s0
	ds_write_b16 v128, v16 offset:9424
	v_cvt_pk_bf16_f32 v16, v82, s0
	ds_write_b16 v128, v0 offset:14176
	v_cvt_pk_bf16_f32 v0, v51, s0
	ds_write_b16 v128, v64 offset:352
	v_cvt_pk_bf16_f32 v64, v115, s0
	ds_write_b16 v128, v32 offset:4960
	v_cvt_pk_bf16_f32 v32, v99, s0
	ds_write_b16 v128, v16 offset:9568
	v_cvt_pk_bf16_f32 v16, v83, s0
; __device__ __forceinline__ int accrow(int reg, int lh) { return (reg & 3) + 8 * (reg >> 2) + 4 * lh; }
; template <int EPI, int PN>
; __device__ void gemm_phase(const Params& p, const u16* __restrict__ A, const u16* __restrict__ Bt, int nNt, char* smem) {
;     ...
;           for (int r = 0; r < 16; ++r) *(u16*)(et + (i * 32 + accrow(r, lhE)) * 144 + (j * 32 + lrE) * 2) = f2bf(acc[i][j][r]);
; #pragma unroll
;       for (int it = 0; it < 16; ++it) {
;         const int c = it * 64 + laneE, row = c >> 3, seg = c & 7;
;         const uint4 v = *(const uint4*)(et + row * 144 + seg * 16);
;         if (EPI == 0) *(uint4*)(p.proj + (row0 + row) * NPROJ + col0 + seg * 8) = v;
;         else *(uint4*)(p.qp + (row0 + row) * DM + col0 + seg * 8) = v;
;       }
	ds_write_b16 v128, v0 offset:14320
	v_cvt_pk_bf16_f32 v0, v52, s0
	ds_write_b16 v128, v64 offset:496
	v_cvt_pk_bf16_f32 v64, v116, s0
	ds_write_b16 v128, v32 offset:5104
	v_cvt_pk_bf16_f32 v32, v100, s0
	ds_write_b16 v128, v16 offset:9712
	v_cvt_pk_bf16_f32 v16, v84, s0
	ds_write_b16 v128, v0 offset:15040
	v_cvt_pk_bf16_f32 v0, v53, s0
	ds_write_b16 v128, v64 offset:1216
	v_cvt_pk_bf16_f32 v64, v117, s0
	ds_write_b16 v128, v32 offset:5824
	v_cvt_pk_bf16_f32 v32, v101, s0
	ds_write_b16 v128, v16 offset:10432
	v_cvt_pk_bf16_f32 v16, v85, s0
	ds_write_b16 v128, v0 offset:15184
	v_cvt_pk_bf16_f32 v0, v54, s0
	ds_write_b16 v128, v64 offset:1360
	v_cvt_pk_bf16_f32 v64, v118, s0
	ds_write_b16 v128, v32 offset:5968
	v_cvt_pk_bf16_f32 v32, v102, s0
	ds_write_b16 v128, v16 offset:10576
	v_cvt_pk_bf16_f32 v16, v86, s0
	ds_write_b16 v128, v0 offset:15328
	v_cvt_pk_bf16_f32 v0, v55, s0
	ds_write_b16 v128, v64 offset:1504
	v_cvt_pk_bf16_f32 v64, v119, s0
	ds_write_b16 v128, v32 offset:6112
	v_cvt_pk_bf16_f32 v32, v103, s0
	ds_write_b16 v128, v16 offset:10720
	v_cvt_pk_bf16_f32 v16, v87, s0
	ds_write_b16 v128, v0 offset:15472
	v_cvt_pk_bf16_f32 v0, v56, s0
	ds_write_b16 v128, v64 offset:1648
	v_cvt_pk_bf16_f32 v64, v120, s0
	ds_write_b16 v128, v32 offset:6256
	v_cvt_pk_bf16_f32 v32, v104, s0
	ds_write_b16 v128, v16 offset:10864
	v_cvt_pk_bf16_f32 v16, v88, s0
	ds_write_b16 v128, v0 offset:16192
	v_cvt_pk_bf16_f32 v0, v57, s0
	ds_write_b16 v128, v64 offset:2368
	v_cvt_pk_bf16_f32 v64, v121, s0
	ds_write_b16 v128, v32 offset:6976
	v_cvt_pk_bf16_f32 v32, v105, s0
	ds_write_b16 v128, v16 offset:11584
	v_cvt_pk_bf16_f32 v16, v89, s0
	ds_write_b16 v128, v0 offset:16336
	v_cvt_pk_bf16_f32 v0, v58, s0
	ds_write_b16 v128, v64 offset:2512
	v_cvt_pk_bf16_f32 v64, v122, s0
	ds_write_b16 v128, v32 offset:7120
	v_cvt_pk_bf16_f32 v32, v106, s0
	ds_write_b16 v128, v16 offset:11728
	v_cvt_pk_bf16_f32 v16, v90, s0
	ds_write_b16 v128, v0 offset:16480
	v_cvt_pk_bf16_f32 v0, v59, s0
	ds_write_b16 v128, v64 offset:2656
	v_cvt_pk_bf16_f32 v64, v123, s0
	ds_write_b16 v128, v32 offset:7264
	v_cvt_pk_bf16_f32 v32, v107, s0
	ds_write_b16 v128, v16 offset:11872
	v_cvt_pk_bf16_f32 v16, v91, s0
	ds_write_b16 v128, v0 offset:16624
	v_cvt_pk_bf16_f32 v0, v60, s0
	ds_write_b16 v128, v64 offset:2800
	v_cvt_pk_bf16_f32 v64, v124, s0
	ds_write_b16 v128, v32 offset:7408
	v_cvt_pk_bf16_f32 v32, v108, s0
	ds_write_b16 v128, v16 offset:12016
	v_cvt_pk_bf16_f32 v16, v92, s0
	ds_write_b16 v128, v0 offset:17344
	v_cvt_pk_bf16_f32 v0, v61, s0
	ds_write_b16 v128, v64 offset:3520
	v_cvt_pk_bf16_f32 v64, v125, s0
	ds_write_b16 v128, v32 offset:8128
	v_cvt_pk_bf16_f32 v32, v109, s0
	ds_write_b16 v128, v16 offset:12736
	v_cvt_pk_bf16_f32 v16, v93, s0
	ds_write_b16 v128, v0 offset:17488
	v_cvt_pk_bf16_f32 v0, v62, s0
	ds_write_b16 v128, v64 offset:3664
	v_cvt_pk_bf16_f32 v64, v126, s0
	ds_write_b16 v128, v32 offset:8272
	v_cvt_pk_bf16_f32 v32, v110, s0
	ds_write_b16 v128, v16 offset:12880
	v_cvt_pk_bf16_f32 v16, v94, s0
	ds_write_b16 v128, v0 offset:17632
	v_cvt_pk_bf16_f32 v0, v63, s0
	ds_write_b16 v128, v64 offset:3808
	v_cvt_pk_bf16_f32 v64, v127, s0
	ds_write_b16 v128, v32 offset:8416
	v_cvt_pk_bf16_f32 v32, v111, s0
	ds_write_b16 v128, v16 offset:13024
	v_cvt_pk_bf16_f32 v16, v95, s0
	ds_write_b16 v128, v0 offset:17776
	v_lshlrev_b32_e32 v0, 4, v177
	ds_write_b16 v128, v64 offset:3952
	ds_write_b16 v128, v32 offset:8560
	ds_write_b16 v128, v16 offset:13168
	v_and_b32_e32 v128, 0x70, v0
	v_add_u32_e32 v0, v163, v128
	v_ashrrev_i32_e32 v6, 3, v177
	v_readlane_b32 s36, v253, 39
	v_mad_u64_u32 v[2:3], s[12:13], v6, s16, v[0:1]
	v_ashrrev_i32_e32 v7, 31, v6
	v_readlane_b32 s40, v253, 43
	v_readlane_b32 s41, v253, 44
	ds_read_b128 v[2:5], v2
	v_lshl_add_u64 v[6:7], v[158:159], 0, v[6:7]
	v_mov_b64_e32 v[10:11], s[40:41]
	v_ashrrev_i32_e32 v161, 31, v160
	v_mad_u64_u32 v[8:9], s[12:13], v6, s17, v[10:11]
	v_mad_i32_i24 v9, v7, s17, v9
	v_lshlrev_b64 v[12:13], 1, v[160:161]
	v_add_u32_e32 v1, 64, v177
	v_lshl_add_u64 v[6:7], v[8:9], 0, v[12:13]
	v_ashrrev_i32_e32 v16, 3, v1
	v_lshl_add_u64 v[14:15], v[6:7], 0, v[128:129]
	v_mad_u64_u32 v[6:7], s[12:13], v16, s16, v[0:1]
	v_ashrrev_i32_e32 v17, 31, v16
	ds_read_b128 v[6:9], v6
	s_waitcnt lgkmcnt(1)
	global_store_dwordx4 v[14:15], v[2:5], off
	v_add_u32_e32 v1, 0x80, v177
	v_readlane_b32 s37, v253, 40
	v_lshl_add_u64 v[2:3], v[158:159], 0, v[16:17]
	v_mad_u64_u32 v[4:5], s[12:13], v2, s17, v[10:11]
	v_mad_i32_i24 v5, v3, s17, v5
	v_lshl_add_u64 v[2:3], v[4:5], 0, v[12:13]
	v_lshl_add_u64 v[2:3], v[2:3], 0, v[128:129]
	s_waitcnt lgkmcnt(0)
	global_store_dwordx4 v[2:3], v[6:9], off
	v_readlane_b32 s38, v253, 41
	v_readlane_b32 s39, v253, 42
	v_ashrrev_i32_e32 v6, 3, v1
	v_mad_u64_u32 v[2:3], s[12:13], v6, s16, v[0:1]
	v_ashrrev_i32_e32 v7, 31, v6
	ds_read_b128 v[2:5], v2
	v_lshl_add_u64 v[6:7], v[158:159], 0, v[6:7]
	v_mad_u64_u32 v[8:9], s[12:13], v6, s17, v[10:11]
	v_mad_i32_i24 v9, v7, s17, v9
	v_add_u32_e32 v1, 0xc0, v177
	v_lshl_add_u64 v[6:7], v[8:9], 0, v[12:13]
	v_ashrrev_i32_e32 v16, 3, v1
	v_lshl_add_u64 v[14:15], v[6:7], 0, v[128:129]
	v_mad_u64_u32 v[6:7], s[12:13], v16, s16, v[0:1]
	v_ashrrev_i32_e32 v17, 31, v16
	ds_read_b128 v[6:9], v6
	s_waitcnt lgkmcnt(1)
	global_store_dwordx4 v[14:15], v[2:5], off
	v_add_u32_e32 v1, 0x100, v177
	v_readlane_b32 s42, v253, 45
	v_lshl_add_u64 v[2:3], v[158:159], 0, v[16:17]
	v_mad_u64_u32 v[4:5], s[12:13], v2, s17, v[10:11]
	v_mad_i32_i24 v5, v3, s17, v5
	v_lshl_add_u64 v[2:3], v[4:5], 0, v[12:13]
	v_lshl_add_u64 v[2:3], v[2:3], 0, v[128:129]
	s_waitcnt lgkmcnt(0)
; template <int EPI, int PN>
; __device__ void gemm_phase(const Params& p, const u16* __restrict__ A, const u16* __restrict__ Bt, int nNt, char* smem) {
;     ...
;       for (int it = 0; it < 16; ++it) {
;         const int c = it * 64 + laneE, row = c >> 3, seg = c & 7;
;         const uint4 v = *(const uint4*)(et + row * 144 + seg * 16);
;         if (EPI == 0) *(uint4*)(p.proj + (row0 + row) * NPROJ + col0 + seg * 8) = v;
;         else *(uint4*)(p.qp + (row0 + row) * DM + col0 + seg * 8) = v;
;       }
	global_store_dwordx4 v[2:3], v[6:9], off
	v_readlane_b32 s43, v253, 46
	v_readlane_b32 s44, v253, 47
	v_ashrrev_i32_e32 v6, 3, v1
	v_mad_u64_u32 v[2:3], s[12:13], v6, s16, v[0:1]
	v_ashrrev_i32_e32 v7, 31, v6
	ds_read_b128 v[2:5], v2
	v_lshl_add_u64 v[6:7], v[158:159], 0, v[6:7]
	v_mad_u64_u32 v[8:9], s[12:13], v6, s17, v[10:11]
	v_mad_i32_i24 v9, v7, s17, v9
	v_add_u32_e32 v1, 0x140, v177
	v_lshl_add_u64 v[6:7], v[8:9], 0, v[12:13]
	v_ashrrev_i32_e32 v16, 3, v1
	v_lshl_add_u64 v[14:15], v[6:7], 0, v[128:129]
	v_mad_u64_u32 v[6:7], s[12:13], v16, s16, v[0:1]
	v_ashrrev_i32_e32 v17, 31, v16
	ds_read_b128 v[6:9], v6
	s_waitcnt lgkmcnt(1)
	global_store_dwordx4 v[14:15], v[2:5], off
	v_add_u32_e32 v1, 0x180, v177
	v_readlane_b32 s45, v253, 48
	v_lshl_add_u64 v[2:3], v[158:159], 0, v[16:17]
	v_mad_u64_u32 v[4:5], s[12:13], v2, s17, v[10:11]
	v_mad_i32_i24 v5, v3, s17, v5
	v_lshl_add_u64 v[2:3], v[4:5], 0, v[12:13]
	v_lshl_add_u64 v[2:3], v[2:3], 0, v[128:129]
	s_waitcnt lgkmcnt(0)
	global_store_dwordx4 v[2:3], v[6:9], off
	v_readlane_b32 s46, v253, 49
	v_readlane_b32 s47, v253, 50
	v_ashrrev_i32_e32 v6, 3, v1
	v_mad_u64_u32 v[2:3], s[12:13], v6, s16, v[0:1]
	v_ashrrev_i32_e32 v7, 31, v6
	ds_read_b128 v[2:5], v2
	v_lshl_add_u64 v[6:7], v[158:159], 0, v[6:7]
	v_mad_u64_u32 v[8:9], s[12:13], v6, s17, v[10:11]
	v_mad_i32_i24 v9, v7, s17, v9
	v_add_u32_e32 v1, 0x1c0, v177
	v_lshl_add_u64 v[6:7], v[8:9], 0, v[12:13]
	v_ashrrev_i32_e32 v16, 3, v1
	v_lshl_add_u64 v[14:15], v[6:7], 0, v[128:129]
	v_mad_u64_u32 v[6:7], s[12:13], v16, s16, v[0:1]
	v_ashrrev_i32_e32 v17, 31, v16
	ds_read_b128 v[6:9], v6
	s_waitcnt lgkmcnt(1)
	global_store_dwordx4 v[14:15], v[2:5], off
	v_add_u32_e32 v1, 0x200, v177
	v_readlane_b32 s48, v253, 51
	v_lshl_add_u64 v[2:3], v[158:159], 0, v[16:17]
	v_mad_u64_u32 v[4:5], s[12:13], v2, s17, v[10:11]
	v_mad_i32_i24 v5, v3, s17, v5
	v_lshl_add_u64 v[2:3], v[4:5], 0, v[12:13]
	v_lshl_add_u64 v[2:3], v[2:3], 0, v[128:129]
	s_waitcnt lgkmcnt(0)
	global_store_dwordx4 v[2:3], v[6:9], off
	v_readlane_b32 s49, v253, 52
	v_readlane_b32 s50, v253, 53
	v_ashrrev_i32_e32 v6, 3, v1
	v_mad_u64_u32 v[2:3], s[12:13], v6, s16, v[0:1]
	v_ashrrev_i32_e32 v7, 31, v6
	ds_read_b128 v[2:5], v2
	v_lshl_add_u64 v[6:7], v[158:159], 0, v[6:7]
	v_mad_u64_u32 v[8:9], s[12:13], v6, s17, v[10:11]
	v_mad_i32_i24 v9, v7, s17, v9
	v_add_u32_e32 v1, 0x240, v177
	v_lshl_add_u64 v[6:7], v[8:9], 0, v[12:13]
	v_ashrrev_i32_e32 v16, 3, v1
	v_lshl_add_u64 v[14:15], v[6:7], 0, v[128:129]
	v_mad_u64_u32 v[6:7], s[12:13], v16, s16, v[0:1]
	v_ashrrev_i32_e32 v17, 31, v16
	ds_read_b128 v[6:9], v6
	s_waitcnt lgkmcnt(1)
	global_store_dwordx4 v[14:15], v[2:5], off
	v_add_u32_e32 v1, 0x280, v177
	v_readlane_b32 s51, v253, 54
	v_lshl_add_u64 v[2:3], v[158:159], 0, v[16:17]
	v_mad_u64_u32 v[4:5], s[12:13], v2, s17, v[10:11]
	v_mad_i32_i24 v5, v3, s17, v5
	v_lshl_add_u64 v[2:3], v[4:5], 0, v[12:13]
	v_lshl_add_u64 v[2:3], v[2:3], 0, v[128:129]
	s_waitcnt lgkmcnt(0)
	global_store_dwordx4 v[2:3], v[6:9], off
	s_nop 1
	v_ashrrev_i32_e32 v6, 3, v1
	v_mad_u64_u32 v[2:3], s[12:13], v6, s16, v[0:1]
	v_ashrrev_i32_e32 v7, 31, v6
	ds_read_b128 v[2:5], v2
	v_lshl_add_u64 v[6:7], v[158:159], 0, v[6:7]
	v_mad_u64_u32 v[8:9], s[12:13], v6, s17, v[10:11]
	v_mad_i32_i24 v9, v7, s17, v9
	v_add_u32_e32 v1, 0x2c0, v177
	v_lshl_add_u64 v[6:7], v[8:9], 0, v[12:13]
	v_ashrrev_i32_e32 v16, 3, v1
	v_lshl_add_u64 v[14:15], v[6:7], 0, v[128:129]
	v_mad_u64_u32 v[6:7], s[12:13], v16, s16, v[0:1]
	v_ashrrev_i32_e32 v17, 31, v16
	ds_read_b128 v[6:9], v6
	s_waitcnt lgkmcnt(1)
	global_store_dwordx4 v[14:15], v[2:5], off
	v_add_u32_e32 v1, 0x300, v177
	s_nop 0
	v_lshl_add_u64 v[2:3], v[158:159], 0, v[16:17]
	v_mad_u64_u32 v[4:5], s[12:13], v2, s17, v[10:11]
	v_mad_i32_i24 v5, v3, s17, v5
	v_lshl_add_u64 v[2:3], v[4:5], 0, v[12:13]
	v_lshl_add_u64 v[2:3], v[2:3], 0, v[128:129]
	s_waitcnt lgkmcnt(0)
	global_store_dwordx4 v[2:3], v[6:9], off
	s_nop 1
	v_ashrrev_i32_e32 v6, 3, v1
	v_mad_u64_u32 v[2:3], s[12:13], v6, s16, v[0:1]
	v_ashrrev_i32_e32 v7, 31, v6
	ds_read_b128 v[2:5], v2
	v_lshl_add_u64 v[6:7], v[158:159], 0, v[6:7]
	v_mad_u64_u32 v[8:9], s[12:13], v6, s17, v[10:11]
	v_mad_i32_i24 v9, v7, s17, v9
	v_add_u32_e32 v1, 0x340, v177
	v_lshl_add_u64 v[6:7], v[8:9], 0, v[12:13]
	v_ashrrev_i32_e32 v16, 3, v1
	v_lshl_add_u64 v[14:15], v[6:7], 0, v[128:129]
	v_mad_u64_u32 v[6:7], s[12:13], v16, s16, v[0:1]
	v_ashrrev_i32_e32 v17, 31, v16
	ds_read_b128 v[6:9], v6
	s_waitcnt lgkmcnt(1)
	global_store_dwordx4 v[14:15], v[2:5], off
	v_add_u32_e32 v1, 0x380, v177
	s_nop 0
	v_lshl_add_u64 v[2:3], v[158:159], 0, v[16:17]
	v_mad_u64_u32 v[4:5], s[12:13], v2, s17, v[10:11]
	v_mad_i32_i24 v5, v3, s17, v5
	v_lshl_add_u64 v[2:3], v[4:5], 0, v[12:13]
	v_lshl_add_u64 v[2:3], v[2:3], 0, v[128:129]
	s_waitcnt lgkmcnt(0)
	global_store_dwordx4 v[2:3], v[6:9], off
	s_nop 1
	v_ashrrev_i32_e32 v6, 3, v1
	v_mad_u64_u32 v[2:3], s[12:13], v6, s16, v[0:1]
	v_ashrrev_i32_e32 v7, 31, v6
	ds_read_b128 v[2:5], v2
	v_lshl_add_u64 v[6:7], v[158:159], 0, v[6:7]
	v_mad_u64_u32 v[8:9], s[12:13], v6, s17, v[10:11]
	v_add_u32_e32 v1, 0x3c0, v177
	v_mad_i32_i24 v9, v7, s17, v9
	v_ashrrev_i32_e32 v16, 3, v1
	v_lshl_add_u64 v[6:7], v[8:9], 0, v[12:13]
	v_mad_u64_u32 v[0:1], s[12:13], v16, s16, v[0:1]
	v_ashrrev_i32_e32 v17, 31, v16
	v_lshl_add_u64 v[14:15], v[6:7], 0, v[128:129]
	ds_read_b128 v[6:9], v0
	v_lshl_add_u64 v[0:1], v[158:159], 0, v[16:17]
	s_waitcnt lgkmcnt(1)
	global_store_dwordx4 v[14:15], v[2:5], off
	s_nop 1
	v_mad_u64_u32 v[2:3], s[12:13], v0, s17, v[10:11]
	v_mad_i32_i24 v3, v1, s17, v3
	v_lshl_add_u64 v[0:1], v[2:3], 0, v[12:13]
	v_lshl_add_u64 v[0:1], v[0:1], 0, v[128:129]
	s_waitcnt lgkmcnt(0)
	global_store_dwordx4 v[0:1], v[6:9], off

; template <int EPI, int PN>
; __device__ void gemm_phase(const Params& p, const u16* __restrict__ A, const u16* __restrict__ Bt, int nNt, char* smem) {
;     ...
;   for (int q = jb;; q += NJ) {
;     const int pl = q / (4 * PN), w = q % (4 * PN);
;     const int gp = pl * 8 + xcd;
;     if (gp >= npatch) break;
;     const int mt = (gp / npn) * 4 + (w & 3), nt = (gp % npn) * PN + (w >> 2);
;     const int gch = sch ^ ((srow >> 1) & 7);
;     const u16* Ag0 = A + (size_t)(mt * 256 + srow) * LDK + gch * 8;
;     const u16* Bg0 = Bt + (size_t)(nt * 256 + srow) * LDK + gch * 8;
;     f32x16 acc[4][2];
; #pragma unroll
;     for (int i = 0; i < 4; ++i)
; #pragma unroll
;       for (int j = 0; j < 2; ++j) acc[i][j] = zero16();
;     asm volatile("s_waitcnt vmcnt(0)" ::: "memory");
; #pragma unroll
;     for (int i = 0; i < 4; ++i) {
;       glds16(Ag0 + (size_t)i * 64 * LDK, ring + (srow + 64 * i) * 64 + sch * 8);
;       glds16(Bg0 + (size_t)i * 64 * LDK, ring + 16384 + (srow + 64 * i) * 64 + sch * 8);
;     }
;     ...
;           if (pre && (i & 1) == 0) {
;             const int pi = ks * 2 + (i >> 1);
;             if (pi < 4) glds16(Ag0 + (size_t)pi * 64 * LDK + (kt + 1) * 64, st + (srow + 64 * pi) * 64 + sch * 8);
;             else glds16(Bg0 + (size_t)(pi - 4) * 64 * LDK + (kt + 1) * 64, st + 16384 + (srow + 64 * (pi - 4)) * 64 + sch * 8);
;             __builtin_amdgcn_sched_barrier(0);
.LBB0_665:
	s_ashr_i32 s12, s16, 31
	s_lshr_b32 s12, s12, 27
	s_add_i32 s12, s16, s12
	s_andn2_b32 s12, s12, 31
	s_sub_i32 s13, s16, s12
	s_lshl_b32 s12, s17, 2
	s_and_b32 s20, s13, 3
	s_or_b32 s12, s20, s12
	s_ashr_i32 s13, s13, 2
	v_lshl_add_u32 v0, s12, 8, v141
	v_lshl_add_u32 v6, s13, 8, v141
	v_mad_i64_i32 v[0:1], s[18:19], v0, s2, v[130:131]
	v_mad_i64_i32 v[2:3], s[18:19], v6, s2, v[132:133]
	s_waitcnt vmcnt(0)
	v_readfirstlane_b32 s18, v136
	s_mov_b32 s19, m0
	s_mov_b32 m0, s18
	s_nop 0
	global_load_lds_dwordx4 v[0:1], off
	s_mov_b32 m0, s19
	v_readfirstlane_b32 s18, v138
	s_mov_b32 s19, m0
	s_mov_b32 m0, s18
	s_nop 0
	global_load_lds_dwordx4 v[2:3], off
	s_mov_b32 m0, s19
	v_lshl_add_u64 v[4:5], v[0:1], 0, s[4:5]
	v_readfirstlane_b32 s18, v140
	s_mov_b32 s19, m0
	s_mov_b32 m0, s18
	s_nop 0
	global_load_lds_dwordx4 v[4:5], off
	s_mov_b32 m0, s19
	v_lshl_add_u64 v[4:5], v[2:3], 0, s[4:5]
	v_readfirstlane_b32 s18, v142
	s_mov_b32 s19, m0
	s_mov_b32 m0, s18
	s_nop 0
	global_load_lds_dwordx4 v[4:5], off
	s_mov_b32 m0, s19
	v_lshl_add_u64 v[4:5], v[0:1], 0, s[6:7]
	v_readfirstlane_b32 s18, v144
	s_mov_b32 s19, m0
	s_mov_b32 m0, s18
	s_nop 0
	global_load_lds_dwordx4 v[4:5], off
	s_mov_b32 m0, s19
	v_lshl_add_u64 v[4:5], v[2:3], 0, s[6:7]
	v_readfirstlane_b32 s18, v146
	s_mov_b32 s19, m0
	s_mov_b32 m0, s18
	s_nop 0
	global_load_lds_dwordx4 v[4:5], off
	s_mov_b32 m0, s19
	v_add_u32_e32 v4, 0x6000, v136
	v_lshl_add_u64 v[0:1], v[0:1], 0, s[8:9]
	v_readfirstlane_b32 s18, v4
	s_mov_b32 s19, m0
	s_mov_b32 m0, s18
	s_nop 0
	global_load_lds_dwordx4 v[0:1], off
	s_mov_b32 m0, s19
	v_readfirstlane_b32 s18, v150
	v_lshl_add_u64 v[0:1], v[2:3], 0, s[8:9]
	s_mov_b32 s19, m0
	s_mov_b32 m0, s18
	s_nop 0
	global_load_lds_dwordx4 v[0:1], off
	s_mov_b32 m0, s19
	s_lshl_b32 s17, s17, 10
	s_lshl_b32 s18, s20, 8
	s_or_b32 s17, s18, s17
	v_add_u32_e32 v0, s17, v141
	v_mad_i64_i32 v[158:159], s[18:19], v0, s2, v[152:153]
	v_mad_i64_i32 v[160:161], s[18:19], v6, s2, v[154:155]
	s_mov_b32 s17, 0x8000
	v_mov_b32_e32 v0, 0
	v_mov_b32_e32 v1, v129
	v_mov_b32_e32 v2, v129
	v_mov_b32_e32 v3, v129
	v_mov_b32_e32 v4, v129
	v_mov_b32_e32 v5, v129
	v_mov_b32_e32 v6, v129
	v_mov_b32_e32 v7, v129
	v_mov_b32_e32 v8, v129
	v_mov_b32_e32 v9, v129
	v_mov_b32_e32 v10, v129
	v_mov_b32_e32 v11, v129
	v_mov_b32_e32 v12, v129
	v_mov_b32_e32 v13, v129
	v_mov_b32_e32 v14, v129
	v_mov_b32_e32 v15, v129
	v_mov_b32_e32 v64, 0
	v_mov_b32_e32 v65, v129
	v_mov_b32_e32 v66, v129
	v_mov_b32_e32 v67, v129
	v_mov_b32_e32 v68, v129
	v_mov_b32_e32 v69, v129
	v_mov_b32_e32 v70, v129
	v_mov_b32_e32 v71, v129
	v_mov_b32_e32 v72, v129
	v_mov_b32_e32 v73, v129
	v_mov_b32_e32 v74, v129
	v_mov_b32_e32 v75, v129
	v_mov_b32_e32 v76, v129
	v_mov_b32_e32 v77, v129
	v_mov_b32_e32 v78, v129
	v_mov_b32_e32 v79, v129
	v_mov_b32_e32 v16, 0
	v_mov_b32_e32 v17, v129
	v_mov_b32_e32 v18, v129
	v_mov_b32_e32 v19, v129
	v_mov_b32_e32 v20, v129
	v_mov_b32_e32 v21, v129
	v_mov_b32_e32 v22, v129
	v_mov_b32_e32 v23, v129
	v_mov_b32_e32 v24, v129
	v_mov_b32_e32 v25, v129
	v_mov_b32_e32 v26, v129
	v_mov_b32_e32 v27, v129
	v_mov_b32_e32 v28, v129
	v_mov_b32_e32 v29, v129
	v_mov_b32_e32 v30, v129
	v_mov_b32_e32 v31, v129
	v_mov_b32_e32 v80, 0
	v_mov_b32_e32 v81, v129
	v_mov_b32_e32 v82, v129
	v_mov_b32_e32 v83, v129
	v_mov_b32_e32 v84, v129
	v_mov_b32_e32 v85, v129
	v_mov_b32_e32 v86, v129
	v_mov_b32_e32 v87, v129
	v_mov_b32_e32 v88, v129
	v_mov_b32_e32 v89, v129
	v_mov_b32_e32 v90, v129
	v_mov_b32_e32 v91, v129
	v_mov_b32_e32 v92, v129
	v_mov_b32_e32 v93, v129
	v_mov_b32_e32 v94, v129
	v_mov_b32_e32 v95, v129
	v_mov_b32_e32 v32, 0
	v_mov_b32_e32 v33, v129
	v_mov_b32_e32 v34, v129
	v_mov_b32_e32 v35, v129
	v_mov_b32_e32 v36, v129
	v_mov_b32_e32 v37, v129
	v_mov_b32_e32 v38, v129
	v_mov_b32_e32 v39, v129
	v_mov_b32_e32 v40, v129
	v_mov_b32_e32 v41, v129
	v_mov_b32_e32 v42, v129
	v_mov_b32_e32 v43, v129
	v_mov_b32_e32 v44, v129
	v_mov_b32_e32 v45, v129
	v_mov_b32_e32 v46, v129
	v_mov_b32_e32 v47, v129
	v_mov_b32_e32 v96, 0
	v_mov_b32_e32 v97, v129
	v_mov_b32_e32 v98, v129
	v_mov_b32_e32 v99, v129
	v_mov_b32_e32 v100, v129
	v_mov_b32_e32 v101, v129
	v_mov_b32_e32 v102, v129
	v_mov_b32_e32 v103, v129
	v_mov_b32_e32 v104, v129
	v_mov_b32_e32 v105, v129
	v_mov_b32_e32 v106, v129
	v_mov_b32_e32 v107, v129
	v_mov_b32_e32 v108, v129
	v_mov_b32_e32 v109, v129
	v_mov_b32_e32 v110, v129
	v_mov_b32_e32 v111, v129
	v_mov_b32_e32 v48, 0
	v_mov_b32_e32 v49, v129
	v_mov_b32_e32 v50, v129
	v_mov_b32_e32 v51, v129
	v_mov_b32_e32 v52, v129
	v_mov_b32_e32 v53, v129
	v_mov_b32_e32 v54, v129
	v_mov_b32_e32 v55, v129
	v_mov_b32_e32 v56, v129
	v_mov_b32_e32 v57, v129
	v_mov_b32_e32 v58, v129
	v_mov_b32_e32 v59, v129
	v_mov_b32_e32 v60, v129
	v_mov_b32_e32 v61, v129
	v_mov_b32_e32 v62, v129
	v_mov_b32_e32 v63, v129
	v_mov_b32_e32 v112, 0
	v_mov_b32_e32 v113, v129
	v_mov_b32_e32 v114, v129
	v_mov_b32_e32 v115, v129
	v_mov_b32_e32 v116, v129
	v_mov_b32_e32 v117, v129
	v_mov_b32_e32 v118, v129
	v_mov_b32_e32 v119, v129
	v_mov_b32_e32 v120, v129
	v_mov_b32_e32 v121, v129
	v_mov_b32_e32 v122, v129
	v_mov_b32_e32 v123, v129
	v_mov_b32_e32 v124, v129
	v_mov_b32_e32 v125, v129
	v_mov_b32_e32 v126, v129
	v_mov_b32_e32 v127, v129
	v_readfirstlane_b32 s99, v136
	s_add_i32 s99, s99, 0x10000
	s_mov_b32 s19, m0
	s_mov_b32 m0, s99
	s_nop 0
	global_load_lds_dwordx4 v[158:159], off
	v_lshl_add_u64 v[188:189], v[158:159], 0, s[4:5]
	s_add_i32 m0, s99, 0x2000
	s_nop 0
	global_load_lds_dwordx4 v[188:189], off
	v_lshl_add_u64 v[190:191], v[158:159], 0, s[6:7]
	s_add_i32 m0, s99, 0x4000
	s_nop 0
	global_load_lds_dwordx4 v[190:191], off
	v_lshl_add_u64 v[188:189], v[158:159], 0, s[8:9]
	s_add_i32 m0, s99, 0x6000
	s_nop 0
	global_load_lds_dwordx4 v[188:189], off
	s_add_i32 m0, s99, 0x8000
	s_nop 0
	global_load_lds_dwordx4 v[160:161], off
	v_lshl_add_u64 v[190:191], v[160:161], 0, s[4:5]
	s_add_i32 m0, s99, 0xa000
	s_nop 0
	global_load_lds_dwordx4 v[190:191], off
	v_lshl_add_u64 v[188:189], v[160:161], 0, s[6:7]
	s_add_i32 m0, s99, 0xc000
	s_nop 0
	global_load_lds_dwordx4 v[188:189], off
	v_lshl_add_u64 v[190:191], v[160:161], 0, s[8:9]
	s_add_i32 m0, s99, 0xe000
	s_nop 0
	global_load_lds_dwordx4 v[190:191], off
	s_mov_b32 m0, s19
	v_lshl_add_u64 v[158:159], v[158:159], 0, s[10:11]
	v_lshl_add_u64 v[160:161], v[160:161], 0, s[10:11]
	s_waitcnt vmcnt(0)
	s_barrier
	v_lshlrev_b32_e32 v212, 1, v143
	v_lshlrev_b32_e32 v213, 1, v147
	v_add_u32_e32 v149, v212, v234
	v_add_u32_e32 v148, v213, v234
	ds_read_b128 v[162:165], v149
	ds_read_b128 v[168:171], v149 offset:4096
	ds_read_b128 v[172:175], v149 offset:8192
	ds_read_b128 v[176:179], v149 offset:12288
	ds_read_b128 v[180:183], v148 offset:32768
	ds_read_b128 v[184:187], v148 offset:36864
	v_add_u32_e32 v149, v212, v235
	v_add_u32_e32 v148, v213, v235
	ds_read_b128 v[188:191], v149
	ds_read_b128 v[192:195], v149 offset:4096
	ds_read_b128 v[196:199], v149 offset:8192
	ds_read_b128 v[200:203], v149 offset:12288
	ds_read_b128 v[204:207], v148 offset:32768
	ds_read_b128 v[208:211], v148 offset:36864
; template <int EPI, int PN>
; __device__ void gemm_phase(const Params& p, const u16* __restrict__ A, const u16* __restrict__ Bt, int nNt, char* smem) {
;     ...
;     for (int kt = 0; kt < 32; ++kt) {
;       asm volatile("s_waitcnt vmcnt(0)" ::: "memory");
;       __builtin_amdgcn_s_barrier();
;       const u16* Ab = ring + (kt & 1) * STG;
;       const u16* Bb = Ab + 16384;
;       u16* st = ring + ((kt + 1) & 1) * STG;
;       const bool pre = (kt + 1 < 32);
;       s16x8 af[2][4], bf[2][2];
;       auto ldfrag = [&](int ks, int slot) {
; #pragma unroll
;         for (int i = 0; i < 4; ++i) {
;           const int row = wr * 128 + i * 32 + lr;
;           af[slot][i] = *(const s16x8*)(Ab + row * 64 + (((ks * 2 + lh) ^ ((row >> 1) & 7)) * 8));
;         }
; #pragma unroll
;         for (int j = 0; j < 2; ++j) {
;           const int rowb = nh * 128 + wc * 64 + j * 32 + lr;
;           bf[slot][j] = *(const s16x8*)(Bb + rowb * 64 + (((ks * 2 + lh) ^ ((rowb >> 1) & 7)) * 8));
;         }
;       };
;       ldfrag(0, 0);
;       ldfrag(1, 1);
;       __builtin_amdgcn_sched_barrier(0);
; #pragma unroll
;       for (int ks = 0; ks < 4; ++ks) {
;         const int slot = ks & 1;
; #pragma unroll
;         for (int i = 0; i < 4; ++i) {
;           acc[i][0] = mfma32(af[slot][i], bf[slot][0], acc[i][0]);
;           acc[i][1] = mfma32(af[slot][i], bf[slot][1], acc[i][1]);
;           __builtin_amdgcn_sched_barrier(0);
;           if (pre && (i & 1) == 0) {
;             const int pi = ks * 2 + (i >> 1);
;             if (pi < 4) glds16(Ag0 + (size_t)pi * 64 * LDK + (kt + 1) * 64, st + (srow + 64 * pi) * 64 + sch * 8);
;             else glds16(Bg0 + (size_t)(pi - 4) * 64 * LDK + (kt + 1) * 64, st + 16384 + (srow + 64 * (pi - 4)) * 64 + sch * 8);
;             __builtin_amdgcn_sched_barrier(0);
;           }
;         }
;         if (ks + 2 < 4) { ldfrag(ks + 2, slot); __builtin_amdgcn_sched_barrier(0); }
;       }
.Lrot666_loop:
	s_add_i32 s18, s17, 0xffff8000
	s_and_b32 s18, s18, 0x8000
	s_lshl_b32 s18, s18, 1
	v_lshl_or_b32 v128, v143, 1, s18
	v_lshl_add_u32 v166, v147, 1, s18
	s_waitcnt lgkmcnt(7)
	v_mfma_f32_32x32x16_bf16 v[112:127], v[162:165], v[180:183], v[112:127]
	s_waitcnt lgkmcnt(6)
	v_mfma_f32_32x32x16_bf16 v[48:63], v[162:165], v[184:187], v[48:63]
	v_mfma_f32_32x32x16_bf16 v[96:111], v[168:171], v[180:183], v[96:111]
	v_mfma_f32_32x32x16_bf16 v[32:47], v[168:171], v[184:187], v[32:47]
	v_mfma_f32_32x32x16_bf16 v[80:95], v[172:175], v[180:183], v[80:95]
	v_mfma_f32_32x32x16_bf16 v[16:31], v[172:175], v[184:187], v[16:31]
	v_mfma_f32_32x32x16_bf16 v[64:79], v[176:179], v[180:183], v[64:79]
	v_mfma_f32_32x32x16_bf16 v[0:15], v[176:179], v[184:187], v[0:15]
	v_add_u32_e32 v176, v128, v236
	ds_read_b128 v[162:165], v176
	ds_read_b128 v[168:171], v176 offset:4096
	ds_read_b128 v[172:175], v176 offset:8192
	ds_read_b128 v[176:179], v176 offset:12288
	v_add_u32_e32 v184, v166, v236
	ds_read_b128 v[180:183], v184 offset:32768
	ds_read_b128 v[184:187], v184 offset:36864
	s_waitcnt lgkmcnt(7)
	v_mfma_f32_32x32x16_bf16 v[112:127], v[188:191], v[204:207], v[112:127]
	s_waitcnt lgkmcnt(6)
	v_mfma_f32_32x32x16_bf16 v[48:63], v[188:191], v[208:211], v[48:63]
	v_mfma_f32_32x32x16_bf16 v[96:111], v[192:195], v[204:207], v[96:111]
	v_mfma_f32_32x32x16_bf16 v[32:47], v[192:195], v[208:211], v[32:47]
	v_mfma_f32_32x32x16_bf16 v[80:95], v[196:199], v[204:207], v[80:95]
	v_mfma_f32_32x32x16_bf16 v[16:31], v[196:199], v[208:211], v[16:31]
	v_mfma_f32_32x32x16_bf16 v[64:79], v[200:203], v[204:207], v[64:79]
	v_mfma_f32_32x32x16_bf16 v[0:15], v[200:203], v[208:211], v[0:15]
	v_add_u32_e32 v128, v128, v237
	ds_read_b128 v[188:191], v128
	ds_read_b128 v[192:195], v128 offset:4096
	ds_read_b128 v[196:199], v128 offset:8192
	ds_read_b128 v[200:203], v128 offset:12288
	v_add_u32_e32 v128, v166, v237
	ds_read_b128 v[204:207], v128 offset:32768
	ds_read_b128 v[208:211], v128 offset:36864
	s_waitcnt lgkmcnt(7)
	v_mfma_f32_32x32x16_bf16 v[112:127], v[162:165], v[180:183], v[112:127]
	s_waitcnt lgkmcnt(6)
	v_mfma_f32_32x32x16_bf16 v[48:63], v[162:165], v[184:187], v[48:63]
	v_mfma_f32_32x32x16_bf16 v[96:111], v[168:171], v[180:183], v[96:111]
	v_mfma_f32_32x32x16_bf16 v[32:47], v[168:171], v[184:187], v[32:47]
	v_mfma_f32_32x32x16_bf16 v[80:95], v[172:175], v[180:183], v[80:95]
	v_mfma_f32_32x32x16_bf16 v[16:31], v[172:175], v[184:187], v[16:31]
	v_mfma_f32_32x32x16_bf16 v[64:79], v[176:179], v[180:183], v[64:79]
	v_mfma_f32_32x32x16_bf16 v[0:15], v[176:179], v[184:187], v[0:15]
	s_waitcnt vmcnt(0) lgkmcnt(0)
	s_barrier
	s_and_b32 s98, s17, 0x8000
	s_lshl_b32 s98, s98, 1
	v_lshl_or_b32 v212, v143, 1, s98
	v_lshl_add_u32 v213, v147, 1, s98
	v_add_u32_e32 v149, v212, v234
	v_add_u32_e32 v148, v213, v234
	ds_read_b128 v[162:165], v149
	ds_read_b128 v[168:171], v149 offset:4096
	ds_read_b128 v[172:175], v149 offset:8192
	ds_read_b128 v[176:179], v149 offset:12288
	ds_read_b128 v[180:183], v148 offset:32768
	ds_read_b128 v[184:187], v148 offset:36864
	v_add3_u32 v148, s18, v224, v156
	v_mfma_f32_32x32x16_bf16 v[112:127], v[188:191], v[204:207], v[112:127]
	v_readfirstlane_b32 s99, v148
	s_mov_b32 s19, m0
	s_mov_b32 m0, s99
	s_nop 0
	global_load_lds_dwordx4 v[158:159], off
	v_mfma_f32_32x32x16_bf16 v[48:63], v[188:191], v[208:211], v[48:63]
	v_lshl_add_u64 v[188:189], v[158:159], 0, s[4:5]
	s_add_i32 m0, s99, 0x2000
	s_nop 0
	global_load_lds_dwordx4 v[188:189], off
	v_mfma_f32_32x32x16_bf16 v[96:111], v[192:195], v[204:207], v[96:111]
	v_lshl_add_u64 v[190:191], v[158:159], 0, s[6:7]
	s_add_i32 m0, s99, 0x4000
	s_nop 0
	global_load_lds_dwordx4 v[190:191], off
	v_mfma_f32_32x32x16_bf16 v[32:47], v[192:195], v[208:211], v[32:47]
	v_lshl_add_u64 v[188:189], v[158:159], 0, s[8:9]
	s_add_i32 m0, s99, 0x6000
	s_nop 0
	global_load_lds_dwordx4 v[188:189], off
	v_mfma_f32_32x32x16_bf16 v[80:95], v[196:199], v[204:207], v[80:95]
	s_add_i32 m0, s99, 0x8000
	s_nop 0
	global_load_lds_dwordx4 v[160:161], off
	v_mfma_f32_32x32x16_bf16 v[16:31], v[196:199], v[208:211], v[16:31]
	v_lshl_add_u64 v[190:191], v[160:161], 0, s[4:5]
	s_add_i32 m0, s99, 0xa000
	s_nop 0
	global_load_lds_dwordx4 v[190:191], off
	v_mfma_f32_32x32x16_bf16 v[64:79], v[200:203], v[204:207], v[64:79]
	v_lshl_add_u64 v[188:189], v[160:161], 0, s[6:7]
	s_add_i32 m0, s99, 0xc000
	s_nop 0
	global_load_lds_dwordx4 v[188:189], off
	v_mfma_f32_32x32x16_bf16 v[0:15], v[200:203], v[208:211], v[0:15]
	v_lshl_add_u64 v[190:191], v[160:161], 0, s[8:9]
	s_add_i32 m0, s99, 0xe000
	s_nop 0
	global_load_lds_dwordx4 v[190:191], off
	s_mov_b32 m0, s19
	v_add_u32_e32 v149, v212, v235
	v_add_u32_e32 v148, v213, v235
	ds_read_b128 v[188:191], v149
	ds_read_b128 v[192:195], v149 offset:4096
	ds_read_b128 v[196:199], v149 offset:8192
	ds_read_b128 v[200:203], v149 offset:12288
	ds_read_b128 v[204:207], v148 offset:32768
	ds_read_b128 v[208:211], v148 offset:36864
	s_add_i32 s17, s17, 0x8000
	v_lshl_add_u64 v[158:159], v[158:159], 0, s[10:11]
	s_cmp_eq_u32 s17, 0xf8000
	v_lshl_add_u64 v[160:161], v[160:161], 0, s[10:11]
	s_cbranch_scc0 .Lrot666_loop
; template <int EPI, int PN>
; __device__ void gemm_phase(const Params& p, const u16* __restrict__ A, const u16* __restrict__ Bt, int nNt, char* smem) {
;     ...
;       for (int ks = 0; ks < 4; ++ks) {
;         const int slot = ks & 1;
; #pragma unroll
;         for (int i = 0; i < 4; ++i) {
;           acc[i][0] = mfma32(af[slot][i], bf[slot][0], acc[i][0]);
;           acc[i][1] = mfma32(af[slot][i], bf[slot][1], acc[i][1]);
;           __builtin_amdgcn_sched_barrier(0);
;           if (pre && (i & 1) == 0) {
;             const int pi = ks * 2 + (i >> 1);
;             if (pi < 4) glds16(Ag0 + (size_t)pi * 64 * LDK + (kt + 1) * 64, st + (srow + 64 * pi) * 64 + sch * 8);
;             else glds16(Bg0 + (size_t)(pi - 4) * 64 * LDK + (kt + 1) * 64, st + 16384 + (srow + 64 * (pi - 4)) * 64 + sch * 8);
;             __builtin_amdgcn_sched_barrier(0);
;           }
;         }
;         if (ks + 2 < 4) { ldfrag(ks + 2, slot); __builtin_amdgcn_sched_barrier(0); }
;       }
;     }
;     __syncthreads();
	s_add_i32 s18, s17, 0xffff8000
	s_and_b32 s18, s18, 0x8000
	s_lshl_b32 s18, s18, 1
	v_lshl_or_b32 v128, v143, 1, s18
	v_lshl_add_u32 v166, v147, 1, s18
	s_waitcnt lgkmcnt(7)
	v_mfma_f32_32x32x16_bf16 v[112:127], v[162:165], v[180:183], v[112:127]
	s_waitcnt lgkmcnt(6)
	v_mfma_f32_32x32x16_bf16 v[48:63], v[162:165], v[184:187], v[48:63]
	v_mfma_f32_32x32x16_bf16 v[96:111], v[168:171], v[180:183], v[96:111]
	v_mfma_f32_32x32x16_bf16 v[32:47], v[168:171], v[184:187], v[32:47]
	v_mfma_f32_32x32x16_bf16 v[80:95], v[172:175], v[180:183], v[80:95]
	v_mfma_f32_32x32x16_bf16 v[16:31], v[172:175], v[184:187], v[16:31]
	v_mfma_f32_32x32x16_bf16 v[64:79], v[176:179], v[180:183], v[64:79]
	v_mfma_f32_32x32x16_bf16 v[0:15], v[176:179], v[184:187], v[0:15]
	v_add_u32_e32 v176, v128, v236
	ds_read_b128 v[162:165], v176
	ds_read_b128 v[168:171], v176 offset:4096
	ds_read_b128 v[172:175], v176 offset:8192
	ds_read_b128 v[176:179], v176 offset:12288
	v_add_u32_e32 v184, v166, v236
	ds_read_b128 v[180:183], v184 offset:32768
	ds_read_b128 v[184:187], v184 offset:36864
	s_waitcnt lgkmcnt(7)
	v_mfma_f32_32x32x16_bf16 v[112:127], v[188:191], v[204:207], v[112:127]
	s_waitcnt lgkmcnt(6)
	v_mfma_f32_32x32x16_bf16 v[48:63], v[188:191], v[208:211], v[48:63]
	v_mfma_f32_32x32x16_bf16 v[96:111], v[192:195], v[204:207], v[96:111]
	v_mfma_f32_32x32x16_bf16 v[32:47], v[192:195], v[208:211], v[32:47]
	v_mfma_f32_32x32x16_bf16 v[80:95], v[196:199], v[204:207], v[80:95]
	v_mfma_f32_32x32x16_bf16 v[16:31], v[196:199], v[208:211], v[16:31]
	v_mfma_f32_32x32x16_bf16 v[64:79], v[200:203], v[204:207], v[64:79]
	v_mfma_f32_32x32x16_bf16 v[0:15], v[200:203], v[208:211], v[0:15]
	v_add_u32_e32 v128, v128, v237
	ds_read_b128 v[188:191], v128
	ds_read_b128 v[192:195], v128 offset:4096
	ds_read_b128 v[196:199], v128 offset:8192
	ds_read_b128 v[200:203], v128 offset:12288
	v_add_u32_e32 v128, v166, v237
	ds_read_b128 v[204:207], v128 offset:32768
	ds_read_b128 v[208:211], v128 offset:36864
	s_waitcnt lgkmcnt(7)
	v_mfma_f32_32x32x16_bf16 v[112:127], v[162:165], v[180:183], v[112:127]
	s_waitcnt lgkmcnt(6)
	v_mfma_f32_32x32x16_bf16 v[48:63], v[162:165], v[184:187], v[48:63]
	v_mfma_f32_32x32x16_bf16 v[96:111], v[168:171], v[180:183], v[96:111]
	v_mfma_f32_32x32x16_bf16 v[32:47], v[168:171], v[184:187], v[32:47]
	v_mfma_f32_32x32x16_bf16 v[80:95], v[172:175], v[180:183], v[80:95]
	v_mfma_f32_32x32x16_bf16 v[16:31], v[172:175], v[184:187], v[16:31]
	v_mfma_f32_32x32x16_bf16 v[64:79], v[176:179], v[180:183], v[64:79]
	v_mfma_f32_32x32x16_bf16 v[0:15], v[176:179], v[184:187], v[0:15]
	s_waitcnt lgkmcnt(1)
	v_mfma_f32_32x32x16_bf16 v[112:127], v[188:191], v[204:207], v[112:127]
	s_waitcnt lgkmcnt(0)
	v_mfma_f32_32x32x16_bf16 v[48:63], v[188:191], v[208:211], v[48:63]
	v_mfma_f32_32x32x16_bf16 v[96:111], v[192:195], v[204:207], v[96:111]
	v_mfma_f32_32x32x16_bf16 v[32:47], v[192:195], v[208:211], v[32:47]
	v_mfma_f32_32x32x16_bf16 v[80:95], v[196:199], v[204:207], v[80:95]
	v_mfma_f32_32x32x16_bf16 v[16:31], v[196:199], v[208:211], v[16:31]
	v_mfma_f32_32x32x16_bf16 v[64:79], v[200:203], v[204:207], v[64:79]
	v_mfma_f32_32x32x16_bf16 v[0:15], v[200:203], v[208:211], v[0:15]
	s_waitcnt vmcnt(0)
	s_barrier
	ds_read_b128 v[158:161], v226
	ds_read_b128 v[162:165], v226 offset:4096
	ds_read_b128 v[168:171], v226 offset:8192
	ds_read_b128 v[172:175], v226 offset:12288
	ds_read_b128 v[176:179], v227
	ds_read_b128 v[180:183], v227 offset:4096
	ds_read_b128 v[184:187], v228
	ds_read_b128 v[188:191], v228 offset:4096
	ds_read_b128 v[192:195], v228 offset:8192
	ds_read_b128 v[196:199], v228 offset:12288
	ds_read_b128 v[200:203], v229
	ds_read_b128 v[204:207], v229 offset:4096
	s_waitcnt lgkmcnt(7)
	v_mfma_f32_32x32x16_bf16 v[112:127], v[158:161], v[176:179], v[112:127]
	s_waitcnt lgkmcnt(6)
	v_mfma_f32_32x32x16_bf16 v[48:63], v[158:161], v[180:183], v[48:63]
	v_mfma_f32_32x32x16_bf16 v[96:111], v[162:165], v[176:179], v[96:111]
	v_mfma_f32_32x32x16_bf16 v[32:47], v[162:165], v[180:183], v[32:47]
	v_mfma_f32_32x32x16_bf16 v[80:95], v[168:171], v[176:179], v[80:95]
	v_mfma_f32_32x32x16_bf16 v[16:31], v[168:171], v[180:183], v[16:31]
	v_mfma_f32_32x32x16_bf16 v[64:79], v[172:175], v[176:179], v[64:79]
	v_mfma_f32_32x32x16_bf16 v[0:15], v[172:175], v[180:183], v[0:15]
	ds_read_b128 v[158:161], v230
	ds_read_b128 v[162:165], v230 offset:4096
	ds_read_b128 v[168:171], v230 offset:8192
	ds_read_b128 v[172:175], v230 offset:12288
	ds_read_b128 v[176:179], v231
	ds_read_b128 v[180:183], v231 offset:4096
	s_waitcnt lgkmcnt(7)
	v_mfma_f32_32x32x16_bf16 v[112:127], v[184:187], v[200:203], v[112:127]
	s_waitcnt lgkmcnt(6)
	v_mfma_f32_32x32x16_bf16 v[48:63], v[184:187], v[204:207], v[48:63]
	v_mfma_f32_32x32x16_bf16 v[96:111], v[188:191], v[200:203], v[96:111]
	v_mfma_f32_32x32x16_bf16 v[32:47], v[188:191], v[204:207], v[32:47]
	v_mfma_f32_32x32x16_bf16 v[80:95], v[192:195], v[200:203], v[80:95]
	v_mfma_f32_32x32x16_bf16 v[16:31], v[192:195], v[204:207], v[16:31]
	v_mfma_f32_32x32x16_bf16 v[64:79], v[196:199], v[200:203], v[64:79]
	v_mfma_f32_32x32x16_bf16 v[0:15], v[196:199], v[204:207], v[0:15]
	ds_read_b128 v[184:187], v232
	ds_read_b128 v[188:191], v232 offset:4096
	ds_read_b128 v[192:195], v232 offset:8192
	ds_read_b128 v[196:199], v232 offset:12288
	ds_read_b128 v[200:203], v233
	ds_read_b128 v[204:207], v233 offset:4096
	s_waitcnt lgkmcnt(7)
	v_mfma_f32_32x32x16_bf16 v[112:127], v[158:161], v[176:179], v[112:127]
	s_waitcnt lgkmcnt(6)
	v_mfma_f32_32x32x16_bf16 v[48:63], v[158:161], v[180:183], v[48:63]
	v_mfma_f32_32x32x16_bf16 v[96:111], v[162:165], v[176:179], v[96:111]
	v_mfma_f32_32x32x16_bf16 v[32:47], v[162:165], v[180:183], v[32:47]
	v_mfma_f32_32x32x16_bf16 v[80:95], v[168:171], v[176:179], v[80:95]
	v_mfma_f32_32x32x16_bf16 v[16:31], v[168:171], v[180:183], v[16:31]
	v_mfma_f32_32x32x16_bf16 v[64:79], v[172:175], v[176:179], v[64:79]
	v_mfma_f32_32x32x16_bf16 v[0:15], v[172:175], v[180:183], v[0:15]
	s_waitcnt lgkmcnt(1)
	v_mfma_f32_32x32x16_bf16 v[112:127], v[184:187], v[200:203], v[112:127]
	s_waitcnt lgkmcnt(0)
	v_mfma_f32_32x32x16_bf16 v[48:63], v[184:187], v[204:207], v[48:63]
	v_mfma_f32_32x32x16_bf16 v[96:111], v[188:191], v[200:203], v[96:111]
	v_mfma_f32_32x32x16_bf16 v[32:47], v[188:191], v[204:207], v[32:47]
	v_mfma_f32_32x32x16_bf16 v[80:95], v[192:195], v[200:203], v[80:95]
	v_mfma_f32_32x32x16_bf16 v[16:31], v[192:195], v[204:207], v[16:31]
	v_mfma_f32_32x32x16_bf16 v[64:79], v[196:199], v[200:203], v[64:79]
	v_mfma_f32_32x32x16_bf16 v[0:15], v[196:199], v[204:207], v[0:15]
	v_mov_b32_e32 v128, v139
	v_mov_b32_e32 v148, v137
	v_mov_b32_e32 v218, v135
	s_barrier
; __device__ __forceinline__ int accrow(int reg, int lh) { return (reg & 3) + 8 * (reg >> 2) + 4 * lh; }
; template <int EPI, int PN>
; __device__ void gemm_phase(const Params& p, const u16* __restrict__ A, const u16* __restrict__ Bt, int nNt, char* smem) {
;     ...
;     if (EPI == 1) {
; #pragma unroll
;       for (int j = 0; j < 2; ++j) {
; #pragma unroll
;         for (int i = 0; i < 4; ++i)
; #pragma unroll
;           for (int r = 0; r < 16; ++r) *(float*)(et + (i * 32 + accrow(r, lhE)) * 144 + lrE * 4) = acc[i][j][r];
; #pragma unroll
;         for (int it = 0; it < 16; ++it) {
;           const int c = it * 64 + laneE, row = c >> 3, seg = c & 7;
;           const float4 v = *(const float4*)(et + row * 144 + seg * 16);
;           const size_t g = (row0 + row) * DM + col0 + j * 32 + seg * 4;
;           const float4 xv = *(const float4*)(p.x + g);
	v_readlane_b32 s52, v253, 7
	v_lshl_add_u32 v172, s13, 8, v145
	s_ashr_i32 s13, s12, 31
	s_lshl_b64 s[12:13], s[12:13], 8
	v_ashrrev_i32_e32 v158, 3, v218
	v_mov_b32_e32 v163, s13
	v_or_b32_e32 v162, s12, v134
	v_ashrrev_i32_e32 v159, 31, v158
	v_and_b32_e32 v149, 7, v218
	v_ashrrev_i32_e32 v173, 31, v172
	v_lshl_add_u64 v[174:175], v[162:163], 0, v[158:159]
	v_lshl_or_b32 v164, v149, 2, v172
	v_mov_b32_e32 v165, v173
	v_lshlrev_b64 v[160:161], 11, v[174:175]
	v_lshl_add_u64 v[160:161], v[160:161], 0, v[164:165]
	v_lshlrev_b64 v[176:177], 2, v[160:161]
	v_readlane_b32 s53, v253, 8
	v_lshl_add_u32 v166, v149, 4, v225
	v_lshlrev_b32_e32 v148, 2, v148
	v_lshl_add_u64 v[160:161], s[52:53], 0, v[176:177]
	global_load_dwordx4 v[168:171], v[160:161], off
	v_mad_u64_u32 v[158:159], s[12:13], v158, s14, v[166:167]
	v_mul_lo_u32 v128, v128, s15
	v_add3_u32 v159, v225, v148, v128
	ds_write_b32 v159, v112
	ds_write_b32 v159, v113 offset:144
	ds_write_b32 v159, v114 offset:288
	ds_write_b32 v159, v115 offset:432
	ds_write_b32 v159, v116 offset:1152
	ds_write_b32 v159, v117 offset:1296
	ds_write_b32 v159, v118 offset:1440
	ds_write_b32 v159, v119 offset:1584
	ds_write_b32 v159, v120 offset:2304
	ds_write_b32 v159, v121 offset:2448
	ds_write_b32 v159, v122 offset:2592
	ds_write_b32 v159, v123 offset:2736
	ds_write_b32 v159, v124 offset:3456
	ds_write_b32 v159, v125 offset:3600
	ds_write_b32 v159, v126 offset:3744
	ds_write_b32 v159, v127 offset:3888
	ds_write_b32 v159, v96 offset:4608
	ds_write_b32 v159, v97 offset:4752
	ds_write_b32 v159, v98 offset:4896
	ds_write_b32 v159, v99 offset:5040
	ds_write_b32 v159, v100 offset:5760
	ds_write_b32 v159, v101 offset:5904
	ds_write_b32 v159, v102 offset:6048
	ds_write_b32 v159, v103 offset:6192
	ds_write_b32 v159, v104 offset:6912
	ds_write_b32 v159, v105 offset:7056
	ds_write_b32 v159, v106 offset:7200
	ds_write_b32 v159, v107 offset:7344
	ds_write_b32 v159, v108 offset:8064
	ds_write_b32 v159, v109 offset:8208
	ds_write_b32 v159, v110 offset:8352
	ds_write_b32 v159, v111 offset:8496
	ds_write_b32 v159, v80 offset:9216
	ds_write_b32 v159, v81 offset:9360
	ds_write_b32 v159, v82 offset:9504
	ds_write_b32 v159, v83 offset:9648
	ds_write_b32 v159, v84 offset:10368
	ds_write_b32 v159, v85 offset:10512
	ds_write_b32 v159, v86 offset:10656
	ds_write_b32 v159, v87 offset:10800
	ds_write_b32 v159, v88 offset:11520
	ds_write_b32 v159, v89 offset:11664
	ds_write_b32 v159, v90 offset:11808
	ds_write_b32 v159, v91 offset:11952
	ds_write_b32 v159, v92 offset:12672
	ds_write_b32 v159, v93 offset:12816
	ds_write_b32 v159, v94 offset:12960
	ds_write_b32 v159, v95 offset:13104
	ds_write_b32 v159, v64 offset:13824
	ds_write_b32 v159, v65 offset:13968
	ds_write_b32 v159, v66 offset:14112
	ds_write_b32 v159, v67 offset:14256
	ds_write_b32 v159, v68 offset:14976
	ds_write_b32 v159, v69 offset:15120
	ds_write_b32 v159, v70 offset:15264
	ds_write_b32 v159, v71 offset:15408
	ds_write_b32 v159, v72 offset:16128
	ds_write_b32 v159, v73 offset:16272
	ds_write_b32 v159, v74 offset:16416
	ds_write_b32 v159, v75 offset:16560
	ds_write_b32 v159, v76 offset:17280
	ds_write_b32 v159, v77 offset:17424
	ds_write_b32 v159, v78 offset:17568
	ds_write_b32 v159, v79 offset:17712
	ds_read_b128 v[66:69], v158
	v_readlane_b32 s36, v253, 23
	v_readlane_b32 s40, v253, 27
	v_readlane_b32 s41, v253, 28
	v_readlane_b32 s42, v253, 29
	v_readlane_b32 s43, v253, 30
	s_mov_b64 s[20:21], s[40:41]
	s_mov_b64 s[22:23], s[42:43]
	v_lshl_add_u64 v[64:65], s[20:21], 0, v[176:177]
	v_mov_b64_e32 v[102:103], s[22:23]
	v_lshlrev_b64 v[104:105], 1, v[172:173]
	v_lshlrev_b32_e32 v128, 3, v149
	v_readlane_b32 s54, v253, 9
	v_readlane_b32 s55, v253, 10
	v_readlane_b32 s56, v253, 11
	v_readlane_b32 s57, v253, 12
	v_readlane_b32 s58, v253, 13
	v_readlane_b32 s59, v253, 14
	v_readlane_b32 s60, v253, 15
	v_readlane_b32 s61, v253, 16
	v_readlane_b32 s62, v253, 17
	v_readlane_b32 s63, v253, 18
	v_readlane_b32 s64, v253, 19
	v_readlane_b32 s65, v253, 20
	v_readlane_b32 s66, v253, 21
	v_readlane_b32 s67, v253, 22
	v_readlane_b32 s37, v253, 24
	v_readlane_b32 s38, v253, 25
	v_readlane_b32 s39, v253, 26
	v_readlane_b32 s44, v253, 31
	v_readlane_b32 s45, v253, 32
	v_readlane_b32 s46, v253, 33
	v_readlane_b32 s47, v253, 34
	v_readlane_b32 s48, v253, 35
	v_readlane_b32 s49, v253, 36
	v_readlane_b32 s50, v253, 37
	v_readlane_b32 s51, v253, 38
	s_waitcnt vmcnt(0) lgkmcnt(0)
; template <int EPI, int PN>
; __device__ void gemm_phase(const Params& p, const u16* __restrict__ A, const u16* __restrict__ Bt, int nNt, char* smem) {
;     ...
;         for (int it = 0; it < 16; ++it) {
;           const int c = it * 64 + laneE, row = c >> 3, seg = c & 7;
;           const float4 v = *(const float4*)(et + row * 144 + seg * 16);
;           const size_t g = (row0 + row) * DM + col0 + j * 32 + seg * 4;
;           const float4 xv = *(const float4*)(p.x + g);
;           const float4 hv = make_float4(xv.x + v.x, xv.y + v.y, xv.z + v.z, xv.w + v.w);
;           *(float4*)(p.out + g) = hv;
;           uint2 hb; hb.x = pack2(hv.x, hv.y); hb.y = pack2(hv.z, hv.w);
;           *(uint2*)(p.xn + (row0 + row) * LDK + col0 + j * 32 + seg * 4) = hb;
;         }
	v_pk_add_f32 v[66:67], v[66:67], v[168:169]
	v_pk_add_f32 v[68:69], v[68:69], v[170:171]
	global_store_dwordx4 v[64:65], v[66:69], off
	v_cvt_pk_bf16_f32 v70, v66, v67
	v_cvt_pk_bf16_f32 v71, v68, v69
	v_mad_u64_u32 v[66:67], s[12:13], v174, s2, v[102:103]
	v_mad_i32_i24 v67, v175, s2, v67
	v_lshl_add_u64 v[66:67], v[66:67], 0, v[104:105]
	v_lshl_add_u64 v[66:67], v[66:67], 0, v[128:129]
	v_add_u32_e32 v68, 64, v218
	global_store_dwordx2 v[66:67], v[70:71], off
	v_ashrrev_i32_e32 v70, 3, v68
	v_ashrrev_i32_e32 v71, 31, v70
	v_lshl_add_u64 v[74:75], v[162:163], 0, v[70:71]
	v_lshlrev_b64 v[68:69], 11, v[74:75]
	v_lshl_add_u64 v[68:69], v[68:69], 0, v[164:165]
	v_lshlrev_b64 v[76:77], 2, v[68:69]
	v_lshl_add_u64 v[68:69], s[52:53], 0, v[76:77]
	global_load_dwordx4 v[78:81], v[68:69], off
	v_mad_u64_u32 v[72:73], s[12:13], v70, s14, v[166:167]
	v_add_u32_e32 v71, 0x80, v218
	ds_read_b128 v[82:85], v72
	v_ashrrev_i32_e32 v90, 3, v71
	v_ashrrev_i32_e32 v91, 31, v90
	v_lshl_add_u64 v[94:95], v[162:163], 0, v[90:91]
	v_mad_u64_u32 v[70:71], s[12:13], v74, s2, v[102:103]
	v_lshlrev_b64 v[86:87], 11, v[94:95]
	v_mad_i32_i24 v71, v75, s2, v71
	v_lshl_add_u64 v[74:75], v[86:87], 0, v[164:165]
	v_lshl_add_u64 v[70:71], v[70:71], 0, v[104:105]
	v_lshl_add_u64 v[76:77], s[20:21], 0, v[76:77]
	v_lshlrev_b64 v[96:97], 2, v[74:75]
	v_lshl_add_u64 v[74:75], v[70:71], 0, v[128:129]
	v_lshl_add_u64 v[70:71], s[52:53], 0, v[96:97]
	v_add_u32_e32 v73, 0xc0, v218
	v_ashrrev_i32_e32 v98, 3, v73
	v_ashrrev_i32_e32 v99, 31, v98
	v_lshl_add_u64 v[106:107], v[162:163], 0, v[98:99]
	v_add_u32_e32 v73, 0x100, v218
	v_ashrrev_i32_e32 v110, 3, v73
	v_ashrrev_i32_e32 v111, 31, v110
	v_lshl_add_u64 v[114:115], v[162:163], 0, v[110:111]
	v_add_u32_e32 v73, 0x140, v218
	v_ashrrev_i32_e32 v118, 3, v73
	v_ashrrev_i32_e32 v119, 31, v118
	v_lshl_add_u64 v[122:123], v[162:163], 0, v[118:119]
	v_add_u32_e32 v73, 0x180, v218
	v_ashrrev_i32_e32 v126, 3, v73
	v_ashrrev_i32_e32 v127, 31, v126
	v_lshl_add_u64 v[172:173], v[162:163], 0, v[126:127]
	v_add_u32_e32 v73, 0x1c0, v218
	v_ashrrev_i32_e32 v176, 3, v73
	v_ashrrev_i32_e32 v177, 31, v176
	v_add_u32_e32 v73, 0x200, v218
	v_ashrrev_i32_e32 v182, 3, v73
	v_ashrrev_i32_e32 v183, 31, v182
	v_lshl_add_u64 v[186:187], v[162:163], 0, v[182:183]
	v_add_u32_e32 v73, 0x240, v218
	v_ashrrev_i32_e32 v190, 3, v73
	v_ashrrev_i32_e32 v191, 31, v190
	v_lshl_add_u64 v[194:195], v[162:163], 0, v[190:191]
	v_add_u32_e32 v73, 0x280, v218
	v_ashrrev_i32_e32 v198, 3, v73
	v_ashrrev_i32_e32 v199, 31, v198
	v_lshl_add_u64 v[202:203], v[162:163], 0, v[198:199]
	v_add_u32_e32 v73, 0x2c0, v218
	v_ashrrev_i32_e32 v206, 3, v73
	v_ashrrev_i32_e32 v207, 31, v206
	v_lshl_add_u64 v[210:211], v[162:163], 0, v[206:207]
	v_add_u32_e32 v73, 0x300, v218
	v_ashrrev_i32_e32 v214, 3, v73
	v_ashrrev_i32_e32 v215, 31, v214
	v_lshl_add_u64 v[220:221], v[162:163], 0, v[214:215]
	v_add_u32_e32 v73, 0x340, v218
	v_ashrrev_i32_e32 v238, 3, v73
	v_ashrrev_i32_e32 v239, 31, v238
	v_lshl_add_u64 v[242:243], v[162:163], 0, v[238:239]
	v_add_u32_e32 v73, 0x380, v218
	v_ashrrev_i32_e32 v246, 3, v73
	v_ashrrev_i32_e32 v247, 31, v246
	v_lshl_add_u64 v[248:249], v[162:163], 0, v[246:247]
	v_add_u32_e32 v73, 0x3c0, v218
	v_mad_u64_u32 v[218:219], s[12:13], v246, s14, v[166:167]
	v_ashrrev_i32_e32 v148, 3, v73
	v_ashrrev_i32_e32 v149, 31, v148
	v_lshl_add_u64 v[246:247], v[162:163], 0, v[148:149]
	s_waitcnt vmcnt(0) lgkmcnt(0)
	v_pk_add_f32 v[78:79], v[82:83], v[78:79]
	v_pk_add_f32 v[80:81], v[84:85], v[80:81]
	global_store_dwordx4 v[76:77], v[78:81], off
	v_lshlrev_b64 v[82:83], 11, v[106:107]
	v_lshl_add_u64 v[82:83], v[82:83], 0, v[164:165]
	v_cvt_pk_bf16_f32 v78, v78, v79
	v_cvt_pk_bf16_f32 v79, v80, v81
	global_store_dwordx2 v[74:75], v[78:79], off
	global_load_dwordx4 v[86:89], v[70:71], off
	v_mad_u64_u32 v[80:81], s[12:13], v90, s14, v[166:167]
	ds_read_b128 v[90:93], v80
	v_mad_u64_u32 v[78:79], s[12:13], v94, s2, v[102:103]
	v_mad_i32_i24 v79, v95, s2, v79
	v_lshl_add_u64 v[78:79], v[78:79], 0, v[104:105]
	v_lshl_add_u64 v[84:85], s[20:21], 0, v[96:97]
	v_lshlrev_b64 v[108:109], 2, v[82:83]
	v_lshl_add_u64 v[82:83], v[78:79], 0, v[128:129]
	v_lshl_add_u64 v[78:79], s[52:53], 0, v[108:109]
	s_waitcnt vmcnt(0) lgkmcnt(0)
	v_pk_add_f32 v[86:87], v[90:91], v[86:87]
	v_pk_add_f32 v[88:89], v[92:93], v[88:89]
	global_store_dwordx4 v[84:85], v[86:89], off
	v_lshlrev_b64 v[90:91], 11, v[114:115]
	v_lshl_add_u64 v[90:91], v[90:91], 0, v[164:165]
	v_cvt_pk_bf16_f32 v86, v86, v87
	v_cvt_pk_bf16_f32 v87, v88, v89
	global_store_dwordx2 v[82:83], v[86:87], off
	global_load_dwordx4 v[94:97], v[78:79], off
	v_mad_u64_u32 v[88:89], s[12:13], v98, s14, v[166:167]
	ds_read_b128 v[98:101], v88
	v_mad_u64_u32 v[86:87], s[12:13], v106, s2, v[102:103]
	v_mad_i32_i24 v87, v107, s2, v87
	v_lshl_add_u64 v[86:87], v[86:87], 0, v[104:105]
	v_lshl_add_u64 v[92:93], s[20:21], 0, v[108:109]
	v_lshlrev_b64 v[116:117], 2, v[90:91]
	v_lshl_add_u64 v[90:91], v[86:87], 0, v[128:129]
	v_lshl_add_u64 v[86:87], s[52:53], 0, v[116:117]
	s_waitcnt vmcnt(0) lgkmcnt(0)
	v_pk_add_f32 v[94:95], v[98:99], v[94:95]
	v_pk_add_f32 v[96:97], v[100:101], v[96:97]
	global_store_dwordx4 v[92:93], v[94:97], off
	v_lshlrev_b64 v[98:99], 11, v[122:123]
	v_lshl_add_u64 v[98:99], v[98:99], 0, v[164:165]
	v_cvt_pk_bf16_f32 v94, v94, v95
	v_cvt_pk_bf16_f32 v95, v96, v97
	global_store_dwordx2 v[90:91], v[94:95], off
	global_load_dwordx4 v[106:109], v[86:87], off
	v_mad_u64_u32 v[96:97], s[12:13], v110, s14, v[166:167]
	ds_read_b128 v[110:113], v96
	v_mad_u64_u32 v[94:95], s[12:13], v114, s2, v[102:103]
	v_mad_i32_i24 v95, v115, s2, v95
	v_lshl_add_u64 v[94:95], v[94:95], 0, v[104:105]
	v_lshl_add_u64 v[100:101], s[20:21], 0, v[116:117]
	v_lshlrev_b64 v[124:125], 2, v[98:99]
	v_lshl_add_u64 v[98:99], v[94:95], 0, v[128:129]
	v_lshl_add_u64 v[94:95], s[52:53], 0, v[124:125]
	s_waitcnt vmcnt(0) lgkmcnt(0)
; template <int EPI, int PN>
; __device__ void gemm_phase(const Params& p, const u16* __restrict__ A, const u16* __restrict__ Bt, int nNt, char* smem) {
;     ...
;         for (int it = 0; it < 16; ++it) {
;           const int c = it * 64 + laneE, row = c >> 3, seg = c & 7;
;           const float4 v = *(const float4*)(et + row * 144 + seg * 16);
;           const size_t g = (row0 + row) * DM + col0 + j * 32 + seg * 4;
;           const float4 xv = *(const float4*)(p.x + g);
;           const float4 hv = make_float4(xv.x + v.x, xv.y + v.y, xv.z + v.z, xv.w + v.w);
;           *(float4*)(p.out + g) = hv;
;           uint2 hb; hb.x = pack2(hv.x, hv.y); hb.y = pack2(hv.z, hv.w);
;           *(uint2*)(p.xn + (row0 + row) * LDK + col0 + j * 32 + seg * 4) = hb;
;         }
	v_pk_add_f32 v[106:107], v[110:111], v[106:107]
	v_pk_add_f32 v[108:109], v[112:113], v[108:109]
	global_store_dwordx4 v[100:101], v[106:109], off
	v_lshlrev_b64 v[110:111], 11, v[172:173]
	v_lshl_add_u64 v[110:111], v[110:111], 0, v[164:165]
	v_cvt_pk_bf16_f32 v106, v106, v107
	v_cvt_pk_bf16_f32 v107, v108, v109
	global_store_dwordx2 v[98:99], v[106:107], off
	global_load_dwordx4 v[114:117], v[94:95], off
	v_mad_u64_u32 v[108:109], s[12:13], v118, s14, v[166:167]
	ds_read_b128 v[118:121], v108
	v_mad_u64_u32 v[106:107], s[12:13], v122, s2, v[102:103]
	v_mad_i32_i24 v107, v123, s2, v107
	v_lshl_add_u64 v[106:107], v[106:107], 0, v[104:105]
	v_lshl_add_u64 v[112:113], s[20:21], 0, v[124:125]
	v_lshlrev_b64 v[174:175], 2, v[110:111]
	v_lshl_add_u64 v[110:111], v[106:107], 0, v[128:129]
	v_lshl_add_u64 v[106:107], s[52:53], 0, v[174:175]
	s_waitcnt vmcnt(0) lgkmcnt(0)
	v_pk_add_f32 v[114:115], v[118:119], v[114:115]
	v_pk_add_f32 v[116:117], v[120:121], v[116:117]
	global_store_dwordx4 v[112:113], v[114:117], off
	v_lshl_add_u64 v[120:121], s[20:21], 0, v[174:175]
	s_nop 0
	v_cvt_pk_bf16_f32 v114, v114, v115
	v_cvt_pk_bf16_f32 v115, v116, v117
	global_store_dwordx2 v[110:111], v[114:115], off
	global_load_dwordx4 v[122:125], v[106:107], off
	v_mad_u64_u32 v[116:117], s[12:13], v126, s14, v[166:167]
	ds_read_b128 v[168:171], v116
	v_lshl_add_u64 v[126:127], v[162:163], 0, v[176:177]
	v_mad_u64_u32 v[114:115], s[12:13], v172, s2, v[102:103]
	v_lshlrev_b64 v[118:119], 11, v[126:127]
	v_mad_i32_i24 v115, v173, s2, v115
	v_lshl_add_u64 v[118:119], v[118:119], 0, v[164:165]
	v_lshl_add_u64 v[114:115], v[114:115], 0, v[104:105]
	v_lshlrev_b64 v[178:179], 2, v[118:119]
	v_lshl_add_u64 v[118:119], v[114:115], 0, v[128:129]
	v_lshl_add_u64 v[114:115], s[52:53], 0, v[178:179]
	v_mad_u64_u32 v[162:163], s[12:13], v248, s2, v[102:103]
	v_mad_i32_i24 v163, v249, s2, v163
	v_lshl_add_u64 v[162:163], v[162:163], 0, v[104:105]
	s_waitcnt vmcnt(0) lgkmcnt(0)
	v_pk_add_f32 v[122:123], v[168:169], v[122:123]
	v_pk_add_f32 v[124:125], v[170:171], v[124:125]
	global_store_dwordx4 v[120:121], v[122:125], off
	v_lshlrev_b64 v[168:169], 11, v[186:187]
	s_nop 0
	v_cvt_pk_bf16_f32 v122, v122, v123
	v_cvt_pk_bf16_f32 v123, v124, v125
	global_store_dwordx2 v[118:119], v[122:123], off
	global_load_dwordx4 v[170:173], v[114:115], off
	v_mad_u64_u32 v[124:125], s[12:13], v176, s14, v[166:167]
	ds_read_b128 v[174:177], v124
	v_mad_u64_u32 v[122:123], s[12:13], v126, s2, v[102:103]
	v_mad_i32_i24 v123, v127, s2, v123
	v_lshl_add_u64 v[126:127], v[168:169], 0, v[164:165]
	v_lshl_add_u64 v[122:123], v[122:123], 0, v[104:105]
	v_lshl_add_u64 v[168:169], s[20:21], 0, v[178:179]
	v_lshlrev_b64 v[188:189], 2, v[126:127]
	v_lshl_add_u64 v[126:127], v[122:123], 0, v[128:129]
	v_lshl_add_u64 v[122:123], s[52:53], 0, v[188:189]
	s_waitcnt vmcnt(0) lgkmcnt(0)
	v_pk_add_f32 v[170:171], v[174:175], v[170:171]
	v_pk_add_f32 v[172:173], v[176:177], v[172:173]
	global_store_dwordx4 v[168:169], v[170:173], off
	v_lshlrev_b64 v[174:175], 11, v[194:195]
	v_lshl_add_u64 v[174:175], v[174:175], 0, v[164:165]
	v_cvt_pk_bf16_f32 v170, v170, v171
	v_cvt_pk_bf16_f32 v171, v172, v173
	global_store_dwordx2 v[126:127], v[170:171], off
	global_load_dwordx4 v[178:181], v[122:123], off
	v_mad_u64_u32 v[172:173], s[12:13], v182, s14, v[166:167]
	ds_read_b128 v[182:185], v172
	v_mad_u64_u32 v[170:171], s[12:13], v186, s2, v[102:103]
	v_mad_i32_i24 v171, v187, s2, v171
	v_lshl_add_u64 v[170:171], v[170:171], 0, v[104:105]
	v_lshl_add_u64 v[176:177], s[20:21], 0, v[188:189]
	v_lshlrev_b64 v[196:197], 2, v[174:175]
	v_lshl_add_u64 v[174:175], v[170:171], 0, v[128:129]
	v_lshl_add_u64 v[170:171], s[52:53], 0, v[196:197]
	s_waitcnt vmcnt(0) lgkmcnt(0)
	v_pk_add_f32 v[178:179], v[182:183], v[178:179]
	v_pk_add_f32 v[180:181], v[184:185], v[180:181]
	global_store_dwordx4 v[176:177], v[178:181], off
	v_lshlrev_b64 v[182:183], 11, v[202:203]
	v_lshl_add_u64 v[182:183], v[182:183], 0, v[164:165]
	v_cvt_pk_bf16_f32 v178, v178, v179
	v_cvt_pk_bf16_f32 v179, v180, v181
	global_store_dwordx2 v[174:175], v[178:179], off
	global_load_dwordx4 v[186:189], v[170:171], off
	v_mad_u64_u32 v[180:181], s[12:13], v190, s14, v[166:167]
	ds_read_b128 v[190:193], v180
	v_mad_u64_u32 v[178:179], s[12:13], v194, s2, v[102:103]
	v_mad_i32_i24 v179, v195, s2, v179
	v_lshl_add_u64 v[178:179], v[178:179], 0, v[104:105]
	v_lshl_add_u64 v[184:185], s[20:21], 0, v[196:197]
	v_lshlrev_b64 v[204:205], 2, v[182:183]
	v_lshl_add_u64 v[182:183], v[178:179], 0, v[128:129]
	v_lshl_add_u64 v[178:179], s[52:53], 0, v[204:205]
	s_waitcnt vmcnt(0) lgkmcnt(0)
	v_pk_add_f32 v[186:187], v[190:191], v[186:187]
	v_pk_add_f32 v[188:189], v[192:193], v[188:189]
	global_store_dwordx4 v[184:185], v[186:189], off
	v_lshlrev_b64 v[190:191], 11, v[210:211]
	v_lshl_add_u64 v[190:191], v[190:191], 0, v[164:165]
	v_cvt_pk_bf16_f32 v186, v186, v187
	v_cvt_pk_bf16_f32 v187, v188, v189
	global_store_dwordx2 v[182:183], v[186:187], off
	global_load_dwordx4 v[194:197], v[178:179], off
	v_mad_u64_u32 v[188:189], s[12:13], v198, s14, v[166:167]
	ds_read_b128 v[198:201], v188
	v_mad_u64_u32 v[186:187], s[12:13], v202, s2, v[102:103]
	v_mad_i32_i24 v187, v203, s2, v187
	v_lshl_add_u64 v[186:187], v[186:187], 0, v[104:105]
	v_lshl_add_u64 v[192:193], s[20:21], 0, v[204:205]
	v_lshlrev_b64 v[212:213], 2, v[190:191]
	v_lshl_add_u64 v[190:191], v[186:187], 0, v[128:129]
	v_lshl_add_u64 v[186:187], s[52:53], 0, v[212:213]
	s_waitcnt vmcnt(0) lgkmcnt(0)
; template <int EPI, int PN>
; __device__ void gemm_phase(const Params& p, const u16* __restrict__ A, const u16* __restrict__ Bt, int nNt, char* smem) {
;     ...
;   for (int q = jb;; q += NJ) {
;     const int pl = q / (4 * PN), w = q % (4 * PN);
;     const int gp = pl * 8 + xcd;
;     if (gp >= npatch) break;
;     ...
;         for (int it = 0; it < 16; ++it) {
;           const int c = it * 64 + laneE, row = c >> 3, seg = c & 7;
;           const float4 v = *(const float4*)(et + row * 144 + seg * 16);
;           const size_t g = (row0 + row) * DM + col0 + j * 32 + seg * 4;
;           const float4 xv = *(const float4*)(p.x + g);
;           const float4 hv = make_float4(xv.x + v.x, xv.y + v.y, xv.z + v.z, xv.w + v.w);
;           *(float4*)(p.out + g) = hv;
;           uint2 hb; hb.x = pack2(hv.x, hv.y); hb.y = pack2(hv.z, hv.w);
;           *(uint2*)(p.xn + (row0 + row) * LDK + col0 + j * 32 + seg * 4) = hb;
;         }
	v_pk_add_f32 v[194:195], v[198:199], v[194:195]
	v_pk_add_f32 v[196:197], v[200:201], v[196:197]
	global_store_dwordx4 v[192:193], v[194:197], off
	v_lshlrev_b64 v[198:199], 11, v[220:221]
	v_lshl_add_u64 v[198:199], v[198:199], 0, v[164:165]
	v_cvt_pk_bf16_f32 v194, v194, v195
	v_cvt_pk_bf16_f32 v195, v196, v197
	global_store_dwordx2 v[190:191], v[194:195], off
	global_load_dwordx4 v[202:205], v[186:187], off
	v_mad_u64_u32 v[196:197], s[12:13], v206, s14, v[166:167]
	ds_read_b128 v[206:209], v196
	v_mad_u64_u32 v[194:195], s[12:13], v210, s2, v[102:103]
	v_mad_i32_i24 v195, v211, s2, v195
	v_lshl_add_u64 v[194:195], v[194:195], 0, v[104:105]
	v_lshl_add_u64 v[200:201], s[20:21], 0, v[212:213]
	v_lshlrev_b64 v[222:223], 2, v[198:199]
	v_lshl_add_u64 v[198:199], v[194:195], 0, v[128:129]
	v_lshl_add_u64 v[194:195], s[52:53], 0, v[222:223]
	s_waitcnt vmcnt(0) lgkmcnt(0)
	v_pk_add_f32 v[202:203], v[206:207], v[202:203]
	v_pk_add_f32 v[204:205], v[208:209], v[204:205]
	global_store_dwordx4 v[200:201], v[202:205], off
	v_lshlrev_b64 v[206:207], 11, v[242:243]
	v_lshl_add_u64 v[206:207], v[206:207], 0, v[164:165]
	v_cvt_pk_bf16_f32 v202, v202, v203
	v_cvt_pk_bf16_f32 v203, v204, v205
	global_store_dwordx2 v[198:199], v[202:203], off
	global_load_dwordx4 v[210:213], v[194:195], off
	v_mad_u64_u32 v[204:205], s[12:13], v214, s14, v[166:167]
	ds_read_b128 v[214:217], v204
	v_mad_u64_u32 v[202:203], s[12:13], v220, s2, v[102:103]
	v_mad_i32_i24 v203, v221, s2, v203
	v_lshl_add_u64 v[202:203], v[202:203], 0, v[104:105]
	v_lshl_add_u64 v[208:209], s[20:21], 0, v[222:223]
	v_lshlrev_b64 v[244:245], 2, v[206:207]
	v_lshl_add_u64 v[206:207], v[202:203], 0, v[128:129]
	v_lshl_add_u64 v[202:203], s[52:53], 0, v[244:245]
	s_waitcnt vmcnt(0) lgkmcnt(0)
	v_pk_add_f32 v[210:211], v[214:215], v[210:211]
	v_pk_add_f32 v[212:213], v[216:217], v[212:213]
	global_store_dwordx4 v[208:209], v[210:213], off
	v_lshlrev_b64 v[214:215], 11, v[248:249]
	v_lshl_add_u64 v[214:215], v[214:215], 0, v[164:165]
	v_cvt_pk_bf16_f32 v210, v210, v211
	v_cvt_pk_bf16_f32 v211, v212, v213
	global_store_dwordx2 v[206:207], v[210:211], off
	global_load_dwordx4 v[220:223], v[202:203], off
	v_mad_u64_u32 v[212:213], s[12:13], v238, s14, v[166:167]
	ds_read_b128 v[238:241], v212
	v_mad_u64_u32 v[210:211], s[12:13], v242, s2, v[102:103]
	v_mad_i32_i24 v211, v243, s2, v211
	v_lshl_add_u64 v[210:211], v[210:211], 0, v[104:105]
	v_lshl_add_u64 v[216:217], s[20:21], 0, v[244:245]
	ds_read_b128 v[242:245], v218
	v_lshlrev_b64 v[250:251], 2, v[214:215]
	v_lshl_add_u64 v[214:215], v[210:211], 0, v[128:129]
	v_lshl_add_u64 v[210:211], s[52:53], 0, v[250:251]
	v_mad_u64_u32 v[102:103], s[12:13], v246, s2, v[102:103]
	v_mad_i32_i24 v103, v247, s2, v103
	v_lshl_add_u64 v[102:103], v[102:103], 0, v[104:105]
	v_lshl_add_u64 v[102:103], v[102:103], 0, v[128:129]
	s_waitcnt vmcnt(0) lgkmcnt(1)
	v_pk_add_f32 v[220:221], v[238:239], v[220:221]
	v_pk_add_f32 v[222:223], v[240:241], v[222:223]
	global_store_dwordx4 v[216:217], v[220:223], off
	s_nop 1
	v_cvt_pk_bf16_f32 v220, v220, v221
	v_cvt_pk_bf16_f32 v221, v222, v223
	global_store_dwordx2 v[214:215], v[220:221], off
	global_load_dwordx4 v[238:241], v[210:211], off
	v_lshlrev_b64 v[220:221], 11, v[246:247]
	v_lshl_add_u64 v[164:165], v[220:221], 0, v[164:165]
	v_lshlrev_b64 v[248:249], 2, v[164:165]
	v_lshl_add_u64 v[222:223], s[20:21], 0, v[250:251]
	v_lshl_add_u64 v[220:221], v[162:163], 0, v[128:129]
	v_lshl_add_u64 v[164:165], s[52:53], 0, v[248:249]
	v_lshl_add_u64 v[104:105], s[20:21], 0, v[248:249]
	s_waitcnt vmcnt(0) lgkmcnt(0)
	v_pk_add_f32 v[238:239], v[242:243], v[238:239]
	v_pk_add_f32 v[240:241], v[244:245], v[240:241]
	v_cvt_pk_bf16_f32 v162, v238, v239
	v_cvt_pk_bf16_f32 v163, v240, v241
	global_store_dwordx4 v[222:223], v[238:241], off
	global_store_dwordx2 v[220:221], v[162:163], off
	global_load_dwordx4 v[238:241], v[164:165], off
	v_mad_u64_u32 v[162:163], s[12:13], v148, s14, v[166:167]
	ds_read_b128 v[242:245], v162
	v_readlane_b32 s12, v254, 28
	s_add_i32 s16, s16, s12
	s_ashr_i32 s12, s16, 31
	s_lshr_b32 s12, s12, 27
	s_add_i32 s12, s16, s12
	s_ashr_i32 s12, s12, 5
	s_lshl_b32 s12, s12, 3
	v_readlane_b32 s13, v254, 24
	s_or_b32 s17, s12, s13
	s_cmp_gt_i32 s17, 31
	s_waitcnt vmcnt(0) lgkmcnt(0)
; __device__ __forceinline__ int accrow(int reg, int lh) { return (reg & 3) + 8 * (reg >> 2) + 4 * lh; }
; template <int EPI, int PN>
; __device__ void gemm_phase(const Params& p, const u16* __restrict__ A, const u16* __restrict__ Bt, int nNt, char* smem) {
;     ...
; #pragma unroll
;       for (int j = 0; j < 2; ++j) {
; #pragma unroll
;         for (int i = 0; i < 4; ++i)
; #pragma unroll
;           for (int r = 0; r < 16; ++r) *(float*)(et + (i * 32 + accrow(r, lhE)) * 144 + lrE * 4) = acc[i][j][r];
; #pragma unroll
;         for (int it = 0; it < 16; ++it) {
;           const int c = it * 64 + laneE, row = c >> 3, seg = c & 7;
;           const float4 v = *(const float4*)(et + row * 144 + seg * 16);
;           const size_t g = (row0 + row) * DM + col0 + j * 32 + seg * 4;
;           const float4 xv = *(const float4*)(p.x + g);
;           const float4 hv = make_float4(xv.x + v.x, xv.y + v.y, xv.z + v.z, xv.w + v.w);
;           *(float4*)(p.out + g) = hv;
;           uint2 hb; hb.x = pack2(hv.x, hv.y); hb.y = pack2(hv.z, hv.w);
;           *(uint2*)(p.xn + (row0 + row) * LDK + col0 + j * 32 + seg * 4) = hb;
;         }
	v_pk_add_f32 v[238:239], v[242:243], v[238:239]
	v_pk_add_f32 v[240:241], v[244:245], v[240:241]
	v_cvt_pk_bf16_f32 v148, v238, v239
	v_cvt_pk_bf16_f32 v149, v240, v241
	global_store_dwordx4 v[104:105], v[238:241], off
	global_store_dwordx2 v[102:103], v[148:149], off
	global_load_dwordx4 v[238:241], v[160:161], off offset:128
	ds_write_b32 v159, v48
	ds_write_b32 v159, v49 offset:144
	ds_write_b32 v159, v50 offset:288
	ds_write_b32 v159, v51 offset:432
	ds_write_b32 v159, v52 offset:1152
	ds_write_b32 v159, v53 offset:1296
	ds_write_b32 v159, v54 offset:1440
	ds_write_b32 v159, v55 offset:1584
	ds_write_b32 v159, v56 offset:2304
	ds_write_b32 v159, v57 offset:2448
	ds_write_b32 v159, v58 offset:2592
	ds_write_b32 v159, v59 offset:2736
	ds_write_b32 v159, v60 offset:3456
	ds_write_b32 v159, v61 offset:3600
	ds_write_b32 v159, v62 offset:3744
	ds_write_b32 v159, v63 offset:3888
	ds_write_b32 v159, v32 offset:4608
	ds_write_b32 v159, v33 offset:4752
	ds_write_b32 v159, v34 offset:4896
	ds_write_b32 v159, v35 offset:5040
	ds_write_b32 v159, v36 offset:5760
	ds_write_b32 v159, v37 offset:5904
	ds_write_b32 v159, v38 offset:6048
	ds_write_b32 v159, v39 offset:6192
	ds_write_b32 v159, v40 offset:6912
	ds_write_b32 v159, v41 offset:7056
	ds_write_b32 v159, v42 offset:7200
	ds_write_b32 v159, v43 offset:7344
	ds_write_b32 v159, v44 offset:8064
	ds_write_b32 v159, v45 offset:8208
	ds_write_b32 v159, v46 offset:8352
	ds_write_b32 v159, v47 offset:8496
	ds_write_b32 v159, v16 offset:9216
	ds_write_b32 v159, v17 offset:9360
	ds_write_b32 v159, v18 offset:9504
	ds_write_b32 v159, v19 offset:9648
	ds_write_b32 v159, v20 offset:10368
	ds_write_b32 v159, v21 offset:10512
	ds_write_b32 v159, v22 offset:10656
	ds_write_b32 v159, v23 offset:10800
	ds_write_b32 v159, v24 offset:11520
	ds_write_b32 v159, v25 offset:11664
	ds_write_b32 v159, v26 offset:11808
	ds_write_b32 v159, v27 offset:11952
	ds_write_b32 v159, v28 offset:12672
	ds_write_b32 v159, v29 offset:12816
	ds_write_b32 v159, v30 offset:12960
	ds_write_b32 v159, v31 offset:13104
	ds_write_b32 v159, v0 offset:13824
	ds_write_b32 v159, v1 offset:13968
	ds_write_b32 v159, v2 offset:14112
	ds_write_b32 v159, v3 offset:14256
	ds_write_b32 v159, v4 offset:14976
	ds_write_b32 v159, v5 offset:15120
	ds_write_b32 v159, v6 offset:15264
	ds_write_b32 v159, v7 offset:15408
	ds_write_b32 v159, v8 offset:16128
	ds_write_b32 v159, v9 offset:16272
	ds_write_b32 v159, v10 offset:16416
	ds_write_b32 v159, v11 offset:16560
	ds_write_b32 v159, v12 offset:17280
	ds_write_b32 v159, v13 offset:17424
	ds_write_b32 v159, v14 offset:17568
	ds_write_b32 v159, v15 offset:17712
	ds_read_b128 v[0:3], v158
	ds_read_b128 v[4:7], v72
	s_waitcnt vmcnt(0) lgkmcnt(1)
	v_pk_add_f32 v[0:1], v[0:1], v[238:239]
	v_pk_add_f32 v[2:3], v[2:3], v[240:241]
	global_store_dwordx4 v[64:65], v[0:3], off offset:128
	s_nop 1
	v_cvt_pk_bf16_f32 v0, v0, v1
	v_cvt_pk_bf16_f32 v1, v2, v3
	global_store_dwordx2 v[66:67], v[0:1], off offset:64
	global_load_dwordx4 v[0:3], v[68:69], off offset:128
	s_waitcnt vmcnt(0) lgkmcnt(0)
	v_pk_add_f32 v[0:1], v[4:5], v[0:1]
	v_pk_add_f32 v[2:3], v[6:7], v[2:3]
	global_store_dwordx4 v[76:77], v[0:3], off offset:128
	ds_read_b128 v[4:7], v80
	s_nop 0
	v_cvt_pk_bf16_f32 v0, v0, v1
	v_cvt_pk_bf16_f32 v1, v2, v3
	global_store_dwordx2 v[74:75], v[0:1], off offset:64
	global_load_dwordx4 v[0:3], v[70:71], off offset:128
	s_waitcnt vmcnt(0) lgkmcnt(0)
	v_pk_add_f32 v[0:1], v[4:5], v[0:1]
	v_pk_add_f32 v[2:3], v[6:7], v[2:3]
	global_store_dwordx4 v[84:85], v[0:3], off offset:128
	ds_read_b128 v[4:7], v88
	s_nop 0
	v_cvt_pk_bf16_f32 v0, v0, v1
	v_cvt_pk_bf16_f32 v1, v2, v3
	global_store_dwordx2 v[82:83], v[0:1], off offset:64
	global_load_dwordx4 v[0:3], v[78:79], off offset:128
	s_waitcnt vmcnt(0) lgkmcnt(0)
	v_pk_add_f32 v[0:1], v[4:5], v[0:1]
	v_pk_add_f32 v[2:3], v[6:7], v[2:3]
	global_store_dwordx4 v[92:93], v[0:3], off offset:128
	ds_read_b128 v[4:7], v96
	s_nop 0
	v_cvt_pk_bf16_f32 v0, v0, v1
	v_cvt_pk_bf16_f32 v1, v2, v3
	global_store_dwordx2 v[90:91], v[0:1], off offset:64
	global_load_dwordx4 v[0:3], v[86:87], off offset:128
	s_waitcnt vmcnt(0) lgkmcnt(0)
; __device__ __forceinline__ int accrow(int reg, int lh) { return (reg & 3) + 8 * (reg >> 2) + 4 * lh; }
; template <int EPI, int PN>
; __device__ void gemm_phase(const Params& p, const u16* __restrict__ A, const u16* __restrict__ Bt, int nNt, char* smem) {
;     ...
;         for (int it = 0; it < 16; ++it) {
;           const int c = it * 64 + laneE, row = c >> 3, seg = c & 7;
;           const float4 v = *(const float4*)(et + row * 144 + seg * 16);
;           const size_t g = (row0 + row) * DM + col0 + j * 32 + seg * 4;
;           const float4 xv = *(const float4*)(p.x + g);
;           const float4 hv = make_float4(xv.x + v.x, xv.y + v.y, xv.z + v.z, xv.w + v.w);
;           *(float4*)(p.out + g) = hv;
;           uint2 hb; hb.x = pack2(hv.x, hv.y); hb.y = pack2(hv.z, hv.w);
;           *(uint2*)(p.xn + (row0 + row) * LDK + col0 + j * 32 + seg * 4) = hb;
;         }
;       }
;     } else if (EPI == 0 && col0 >= NPROJ) {
; #pragma unroll
;       for (int i = 0; i < 4; ++i)
; #pragma unroll
;         for (int r = 0; r < 16; ++r) {
;           const size_t row = row0 + i * 32 + accrow(r, lhE);
;           const int col = col0 + lrE;
;           if (col < NIN) p.dtraw[row * 16 + (col - NPROJ)] = acc[i][0][r];
;         }
;     } else {
; #pragma unroll
;       for (int i = 0; i < 4; ++i)
; #pragma unroll
;         for (int j = 0; j < 2; ++j)
; #pragma unroll
;           for (int r = 0; r < 16; ++r) *(u16*)(et + (i * 32 + accrow(r, lhE)) * 144 + (j * 32 + lrE) * 2) = f2bf(acc[i][j][r]);
; #pragma unroll
;       for (int it = 0; it < 16; ++it) {
;         const int c = it * 64 + laneE, row = c >> 3, seg = c & 7;
;         const uint4 v = *(const uint4*)(et + row * 144 + seg * 16);
;         if (EPI == 0) *(uint4*)(p.proj + (row0 + row) * NPROJ + col0 + seg * 8) = v;
;         else *(uint4*)(p.qp + (row0 + row) * DM + col0 + seg * 8) = v;
;       }
;     }
;     __syncthreads();
;   }
	v_pk_add_f32 v[0:1], v[4:5], v[0:1]
	v_pk_add_f32 v[2:3], v[6:7], v[2:3]
	global_store_dwordx4 v[100:101], v[0:3], off offset:128
	ds_read_b128 v[4:7], v108
	s_nop 0
	v_cvt_pk_bf16_f32 v0, v0, v1
	v_cvt_pk_bf16_f32 v1, v2, v3
	global_store_dwordx2 v[98:99], v[0:1], off offset:64
	global_load_dwordx4 v[0:3], v[94:95], off offset:128
	s_waitcnt vmcnt(0) lgkmcnt(0)
	v_pk_add_f32 v[0:1], v[4:5], v[0:1]
	v_pk_add_f32 v[2:3], v[6:7], v[2:3]
	global_store_dwordx4 v[112:113], v[0:3], off offset:128
	ds_read_b128 v[4:7], v116
	s_nop 0
	v_cvt_pk_bf16_f32 v0, v0, v1
	v_cvt_pk_bf16_f32 v1, v2, v3
	global_store_dwordx2 v[110:111], v[0:1], off offset:64
	global_load_dwordx4 v[0:3], v[106:107], off offset:128
	s_waitcnt vmcnt(0) lgkmcnt(0)
	v_pk_add_f32 v[0:1], v[4:5], v[0:1]
	v_pk_add_f32 v[2:3], v[6:7], v[2:3]
	global_store_dwordx4 v[120:121], v[0:3], off offset:128
	ds_read_b128 v[4:7], v124
	s_nop 0
	v_cvt_pk_bf16_f32 v0, v0, v1
	v_cvt_pk_bf16_f32 v1, v2, v3
	global_store_dwordx2 v[118:119], v[0:1], off offset:64
	global_load_dwordx4 v[0:3], v[114:115], off offset:128
	s_waitcnt vmcnt(0) lgkmcnt(0)
	v_pk_add_f32 v[0:1], v[4:5], v[0:1]
	v_pk_add_f32 v[2:3], v[6:7], v[2:3]
	global_store_dwordx4 v[168:169], v[0:3], off offset:128
	ds_read_b128 v[4:7], v172
	s_nop 0
	v_cvt_pk_bf16_f32 v0, v0, v1
	v_cvt_pk_bf16_f32 v1, v2, v3
	global_store_dwordx2 v[126:127], v[0:1], off offset:64
	global_load_dwordx4 v[0:3], v[122:123], off offset:128
	s_waitcnt vmcnt(0) lgkmcnt(0)
	v_pk_add_f32 v[0:1], v[4:5], v[0:1]
	v_pk_add_f32 v[2:3], v[6:7], v[2:3]
	global_store_dwordx4 v[176:177], v[0:3], off offset:128
	ds_read_b128 v[4:7], v180
	s_nop 0
	v_cvt_pk_bf16_f32 v0, v0, v1
	v_cvt_pk_bf16_f32 v1, v2, v3
	global_store_dwordx2 v[174:175], v[0:1], off offset:64
	global_load_dwordx4 v[0:3], v[170:171], off offset:128
	s_waitcnt vmcnt(0) lgkmcnt(0)
	v_pk_add_f32 v[0:1], v[4:5], v[0:1]
	v_pk_add_f32 v[2:3], v[6:7], v[2:3]
	global_store_dwordx4 v[184:185], v[0:3], off offset:128
	ds_read_b128 v[4:7], v188
	s_nop 0
	v_cvt_pk_bf16_f32 v0, v0, v1
	v_cvt_pk_bf16_f32 v1, v2, v3
	global_store_dwordx2 v[182:183], v[0:1], off offset:64
	global_load_dwordx4 v[0:3], v[178:179], off offset:128
	s_waitcnt vmcnt(0) lgkmcnt(0)
	v_pk_add_f32 v[0:1], v[4:5], v[0:1]
	v_pk_add_f32 v[2:3], v[6:7], v[2:3]
	global_store_dwordx4 v[192:193], v[0:3], off offset:128
	ds_read_b128 v[4:7], v196
	s_nop 0
	v_cvt_pk_bf16_f32 v0, v0, v1
	v_cvt_pk_bf16_f32 v1, v2, v3
	global_store_dwordx2 v[190:191], v[0:1], off offset:64
	global_load_dwordx4 v[0:3], v[186:187], off offset:128
	s_waitcnt vmcnt(0) lgkmcnt(0)
	v_pk_add_f32 v[0:1], v[4:5], v[0:1]
	v_pk_add_f32 v[2:3], v[6:7], v[2:3]
	global_store_dwordx4 v[200:201], v[0:3], off offset:128
	ds_read_b128 v[4:7], v204
	s_nop 0
	v_cvt_pk_bf16_f32 v0, v0, v1
	v_cvt_pk_bf16_f32 v1, v2, v3
	global_store_dwordx2 v[198:199], v[0:1], off offset:64
	global_load_dwordx4 v[0:3], v[194:195], off offset:128
	s_waitcnt vmcnt(0) lgkmcnt(0)
	v_pk_add_f32 v[0:1], v[4:5], v[0:1]
	v_pk_add_f32 v[2:3], v[6:7], v[2:3]
	global_store_dwordx4 v[208:209], v[0:3], off offset:128
	ds_read_b128 v[4:7], v212
	s_nop 0
	v_cvt_pk_bf16_f32 v0, v0, v1
	v_cvt_pk_bf16_f32 v1, v2, v3
	global_store_dwordx2 v[206:207], v[0:1], off offset:64
	global_load_dwordx4 v[0:3], v[202:203], off offset:128
	s_waitcnt vmcnt(0) lgkmcnt(0)
	v_pk_add_f32 v[0:1], v[4:5], v[0:1]
	v_pk_add_f32 v[2:3], v[6:7], v[2:3]
	global_store_dwordx4 v[216:217], v[0:3], off offset:128
	ds_read_b128 v[4:7], v218
	s_nop 0
	v_cvt_pk_bf16_f32 v0, v0, v1
	v_cvt_pk_bf16_f32 v1, v2, v3
	global_store_dwordx2 v[214:215], v[0:1], off offset:64
	global_load_dwordx4 v[0:3], v[210:211], off offset:128
	s_waitcnt vmcnt(0) lgkmcnt(0)
	v_pk_add_f32 v[0:1], v[4:5], v[0:1]
	v_pk_add_f32 v[2:3], v[6:7], v[2:3]
	global_store_dwordx4 v[222:223], v[0:3], off offset:128
	ds_read_b128 v[4:7], v162
	s_nop 0
	v_cvt_pk_bf16_f32 v0, v0, v1
	v_cvt_pk_bf16_f32 v1, v2, v3
	global_store_dwordx2 v[220:221], v[0:1], off offset:64
	global_load_dwordx4 v[0:3], v[164:165], off offset:128
	s_waitcnt vmcnt(0) lgkmcnt(0)
	v_pk_add_f32 v[0:1], v[4:5], v[0:1]
	v_pk_add_f32 v[2:3], v[6:7], v[2:3]
	global_store_dwordx4 v[104:105], v[0:3], off offset:128
	s_nop 1
	v_cvt_pk_bf16_f32 v0, v0, v1
	v_cvt_pk_bf16_f32 v1, v2, v3
	global_store_dwordx2 v[102:103], v[0:1], off offset:64
	s_barrier
	s_cbranch_scc0 .LBB0_665

; template <int EPI, int PN>
; __device__ void gemm_phase(const Params& p, const u16* __restrict__ A, const u16* __restrict__ Bt, int nNt, char* smem) {
;     ...
;   for (int q = jb;; q += NJ) {
;     const int pl = q / (4 * PN), w = q % (4 * PN);
;     const int gp = pl * 8 + xcd;
;     if (gp >= npatch) break;
;     const int mt = (gp / npn) * 4 + (w & 3), nt = (gp % npn) * PN + (w >> 2);
;     const int gch = sch ^ ((srow >> 1) & 7);
;     const u16* Ag0 = A + (size_t)(mt * 256 + srow) * LDK + gch * 8;
;     const u16* Bg0 = Bt + (size_t)(nt * 256 + srow) * LDK + gch * 8;
;     f32x16 acc[4][2];
; #pragma unroll
;     for (int i = 0; i < 4; ++i)
; #pragma unroll
;       for (int j = 0; j < 2; ++j) acc[i][j] = zero16();
;     asm volatile("s_waitcnt vmcnt(0)" ::: "memory");
; #pragma unroll
;     for (int i = 0; i < 4; ++i) {
;       glds16(Ag0 + (size_t)i * 64 * LDK, ring + (srow + 64 * i) * 64 + sch * 8);
;       glds16(Bg0 + (size_t)i * 64 * LDK, ring + 16384 + (srow + 64 * i) * 64 + sch * 8);
;     }
;     ...
;           if (pre && (i & 1) == 0) {
;             const int pi = ks * 2 + (i >> 1);
;             if (pi < 4) glds16(Ag0 + (size_t)pi * 64 * LDK + (kt + 1) * 64, st + (srow + 64 * pi) * 64 + sch * 8);
;             else glds16(Bg0 + (size_t)(pi - 4) * 64 * LDK + (kt + 1) * 64, st + 16384 + (srow + 64 * (pi - 4)) * 64 + sch * 8);
;             __builtin_amdgcn_sched_barrier(0);
.LBB0_722:
	s_ashr_i32 s10, s34, 31
	s_lshr_b32 s10, s10, 27
	s_add_i32 s10, s34, s10
	s_andn2_b32 s10, s10, 31
	s_sub_i32 s14, s34, s10
	s_lshl_b32 s10, s11, 2
	s_and_b32 s15, s14, 3
	s_or_b32 s10, s15, s10
	s_ashr_i32 s14, s14, 2
	v_lshl_add_u32 v0, s10, 8, v141
	v_lshl_add_u32 v6, s14, 8, v141
	v_mad_i64_i32 v[0:1], s[16:17], v0, s0, v[130:131]
	v_mad_i64_i32 v[2:3], s[16:17], v6, s0, v[132:133]
	s_waitcnt vmcnt(0)
	v_readfirstlane_b32 s16, v136
	s_mov_b32 s17, m0
	s_mov_b32 m0, s16
	s_nop 0
	global_load_lds_dwordx4 v[0:1], off
	s_mov_b32 m0, s17
	v_readfirstlane_b32 s16, v138
	s_mov_b32 s17, m0
	s_mov_b32 m0, s16
	s_nop 0
	global_load_lds_dwordx4 v[2:3], off
	s_mov_b32 m0, s17
	v_lshl_add_u64 v[4:5], v[0:1], 0, s[2:3]
	v_readfirstlane_b32 s16, v140
	s_mov_b32 s17, m0
	s_mov_b32 m0, s16
	s_nop 0
	global_load_lds_dwordx4 v[4:5], off
	s_mov_b32 m0, s17
	v_lshl_add_u64 v[4:5], v[2:3], 0, s[2:3]
	v_readfirstlane_b32 s16, v142
	s_mov_b32 s17, m0
	s_mov_b32 m0, s16
	s_nop 0
	global_load_lds_dwordx4 v[4:5], off
	s_mov_b32 m0, s17
	v_lshl_add_u64 v[4:5], v[0:1], 0, s[4:5]
	v_readfirstlane_b32 s16, v144
	s_mov_b32 s17, m0
	s_mov_b32 m0, s16
	s_nop 0
	global_load_lds_dwordx4 v[4:5], off
	s_mov_b32 m0, s17
	v_lshl_add_u64 v[4:5], v[2:3], 0, s[4:5]
	v_readfirstlane_b32 s16, v146
	s_mov_b32 s17, m0
	s_mov_b32 m0, s16
	s_nop 0
	global_load_lds_dwordx4 v[4:5], off
	s_mov_b32 m0, s17
	v_lshl_add_u64 v[0:1], v[0:1], 0, s[6:7]
	v_readfirstlane_b32 s16, v148
	s_mov_b32 s17, m0
	s_mov_b32 m0, s16
	s_nop 0
	global_load_lds_dwordx4 v[0:1], off
	s_mov_b32 m0, s17
	s_lshl_b32 s11, s11, 10
	s_lshl_b32 s15, s15, 8
	v_lshl_add_u64 v[0:1], v[2:3], 0, s[6:7]
	v_readfirstlane_b32 s16, v150
	s_mov_b32 s17, m0
	s_mov_b32 m0, s16
	s_nop 0
	global_load_lds_dwordx4 v[0:1], off
	s_mov_b32 m0, s17
	s_or_b32 s11, s15, s11
	v_add_u32_e32 v0, s11, v141
	v_mad_i64_i32 v[158:159], s[16:17], v0, s0, v[152:153]
	v_mad_i64_i32 v[160:161], s[16:17], v6, s0, v[154:155]
	s_mov_b32 s11, 0x8000
	v_mov_b32_e32 v0, 0
	v_mov_b32_e32 v1, v129
	v_mov_b32_e32 v2, v129
	v_mov_b32_e32 v3, v129
	v_mov_b32_e32 v4, v129
	v_mov_b32_e32 v5, v129
	v_mov_b32_e32 v6, v129
	v_mov_b32_e32 v7, v129
	v_mov_b32_e32 v8, v129
	v_mov_b32_e32 v9, v129
	v_mov_b32_e32 v10, v129
	v_mov_b32_e32 v11, v129
	v_mov_b32_e32 v12, v129
	v_mov_b32_e32 v13, v129
	v_mov_b32_e32 v14, v129
	v_mov_b32_e32 v15, v129
	v_mov_b32_e32 v16, 0
	v_mov_b32_e32 v17, v129
	v_mov_b32_e32 v18, v129
	v_mov_b32_e32 v19, v129
	v_mov_b32_e32 v20, v129
	v_mov_b32_e32 v21, v129
	v_mov_b32_e32 v22, v129
	v_mov_b32_e32 v23, v129
	v_mov_b32_e32 v24, v129
	v_mov_b32_e32 v25, v129
	v_mov_b32_e32 v26, v129
	v_mov_b32_e32 v27, v129
	v_mov_b32_e32 v28, v129
	v_mov_b32_e32 v29, v129
	v_mov_b32_e32 v30, v129
	v_mov_b32_e32 v31, v129
	v_mov_b32_e32 v32, 0
	v_mov_b32_e32 v33, v129
	v_mov_b32_e32 v34, v129
	v_mov_b32_e32 v35, v129
	v_mov_b32_e32 v36, v129
	v_mov_b32_e32 v37, v129
	v_mov_b32_e32 v38, v129
	v_mov_b32_e32 v39, v129
	v_mov_b32_e32 v40, v129
	v_mov_b32_e32 v41, v129
	v_mov_b32_e32 v42, v129
	v_mov_b32_e32 v43, v129
	v_mov_b32_e32 v44, v129
	v_mov_b32_e32 v45, v129
	v_mov_b32_e32 v46, v129
	v_mov_b32_e32 v47, v129
	v_mov_b32_e32 v48, 0
	v_mov_b32_e32 v49, v129
	v_mov_b32_e32 v50, v129
	v_mov_b32_e32 v51, v129
	v_mov_b32_e32 v52, v129
	v_mov_b32_e32 v53, v129
	v_mov_b32_e32 v54, v129
	v_mov_b32_e32 v55, v129
	v_mov_b32_e32 v56, v129
	v_mov_b32_e32 v57, v129
	v_mov_b32_e32 v58, v129
	v_mov_b32_e32 v59, v129
	v_mov_b32_e32 v60, v129
	v_mov_b32_e32 v61, v129
	v_mov_b32_e32 v62, v129
	v_mov_b32_e32 v63, v129
	v_mov_b32_e32 v64, 0
	v_mov_b32_e32 v65, v129
	v_mov_b32_e32 v66, v129
	v_mov_b32_e32 v67, v129
	v_mov_b32_e32 v68, v129
	v_mov_b32_e32 v69, v129
	v_mov_b32_e32 v70, v129
	v_mov_b32_e32 v71, v129
	v_mov_b32_e32 v72, v129
	v_mov_b32_e32 v73, v129
	v_mov_b32_e32 v74, v129
	v_mov_b32_e32 v75, v129
	v_mov_b32_e32 v76, v129
	v_mov_b32_e32 v77, v129
	v_mov_b32_e32 v78, v129
	v_mov_b32_e32 v79, v129
	v_mov_b32_e32 v80, 0
	v_mov_b32_e32 v81, v129
	v_mov_b32_e32 v82, v129
	v_mov_b32_e32 v83, v129
	v_mov_b32_e32 v84, v129
	v_mov_b32_e32 v85, v129
	v_mov_b32_e32 v86, v129
	v_mov_b32_e32 v87, v129
	v_mov_b32_e32 v88, v129
	v_mov_b32_e32 v89, v129
	v_mov_b32_e32 v90, v129
	v_mov_b32_e32 v91, v129
	v_mov_b32_e32 v92, v129
	v_mov_b32_e32 v93, v129
	v_mov_b32_e32 v94, v129
	v_mov_b32_e32 v95, v129
	v_mov_b32_e32 v96, 0
	v_mov_b32_e32 v97, v129
	v_mov_b32_e32 v98, v129
	v_mov_b32_e32 v99, v129
	v_mov_b32_e32 v100, v129
	v_mov_b32_e32 v101, v129
	v_mov_b32_e32 v102, v129
	v_mov_b32_e32 v103, v129
	v_mov_b32_e32 v104, v129
	v_mov_b32_e32 v105, v129
	v_mov_b32_e32 v106, v129
	v_mov_b32_e32 v107, v129
	v_mov_b32_e32 v108, v129
	v_mov_b32_e32 v109, v129
	v_mov_b32_e32 v110, v129
	v_mov_b32_e32 v111, v129
	v_mov_b32_e32 v112, 0
	v_mov_b32_e32 v113, v129
	v_mov_b32_e32 v114, v129
	v_mov_b32_e32 v115, v129
	v_mov_b32_e32 v116, v129
	v_mov_b32_e32 v117, v129
	v_mov_b32_e32 v118, v129
	v_mov_b32_e32 v119, v129
	v_mov_b32_e32 v120, v129
	v_mov_b32_e32 v121, v129
	v_mov_b32_e32 v122, v129
	v_mov_b32_e32 v123, v129
	v_mov_b32_e32 v124, v129
	v_mov_b32_e32 v125, v129
	v_mov_b32_e32 v126, v129
	v_mov_b32_e32 v127, v129
	v_readfirstlane_b32 s99, v136
	s_add_i32 s99, s99, 0x10000
	s_mov_b32 s16, m0
	s_mov_b32 m0, s99
	s_nop 0
	global_load_lds_dwordx4 v[158:159], off
	v_lshl_add_u64 v[232:233], v[158:159], 0, s[2:3]
	s_add_i32 m0, s99, 0x2000
	s_nop 0
	global_load_lds_dwordx4 v[232:233], off
	v_lshl_add_u64 v[234:235], v[158:159], 0, s[4:5]
	s_add_i32 m0, s99, 0x4000
	s_nop 0
	global_load_lds_dwordx4 v[234:235], off
	v_lshl_add_u64 v[232:233], v[158:159], 0, s[6:7]
	s_add_i32 m0, s99, 0x6000
	s_nop 0
	global_load_lds_dwordx4 v[232:233], off
	s_add_i32 m0, s99, 0x8000
	s_nop 0
	global_load_lds_dwordx4 v[160:161], off
	v_lshl_add_u64 v[234:235], v[160:161], 0, s[2:3]
	s_add_i32 m0, s99, 0xa000
	s_nop 0
	global_load_lds_dwordx4 v[234:235], off
	v_lshl_add_u64 v[232:233], v[160:161], 0, s[4:5]
	s_add_i32 m0, s99, 0xc000
	s_nop 0
	global_load_lds_dwordx4 v[232:233], off
	v_lshl_add_u64 v[234:235], v[160:161], 0, s[6:7]
	s_add_i32 m0, s99, 0xe000
	s_nop 0
	global_load_lds_dwordx4 v[234:235], off
	s_mov_b32 m0, s16
	v_lshl_add_u64 v[158:159], v[158:159], 0, s[8:9]
	v_lshl_add_u64 v[160:161], v[160:161], 0, s[8:9]
	s_waitcnt vmcnt(0)
	s_barrier
	v_lshlrev_b32_e32 v227, 1, v143
	v_lshlrev_b32_e32 v229, 1, v147
	v_add_u32_e32 v228, v227, v173
	v_add_u32_e32 v230, v229, v173
	ds_read_b128 v[178:181], v228
	ds_read_b128 v[182:185], v228 offset:4096
	ds_read_b128 v[186:189], v228 offset:8192
	ds_read_b128 v[190:193], v228 offset:12288
	ds_read_b128 v[194:197], v230 offset:32768
	ds_read_b128 v[198:201], v230 offset:36864
	v_add_u32_e32 v228, v227, v174
	v_add_u32_e32 v230, v229, v174
	ds_read_b128 v[202:205], v228
	ds_read_b128 v[206:209], v228 offset:4096
	ds_read_b128 v[210:213], v228 offset:8192
	ds_read_b128 v[214:217], v228 offset:12288
	ds_read_b128 v[218:221], v230 offset:32768
	ds_read_b128 v[222:225], v230 offset:36864
; template <int EPI, int PN>
; __device__ void gemm_phase(const Params& p, const u16* __restrict__ A, const u16* __restrict__ Bt, int nNt, char* smem) {
;     ...
;     for (int kt = 0; kt < 32; ++kt) {
;       asm volatile("s_waitcnt vmcnt(0)" ::: "memory");
;       __builtin_amdgcn_s_barrier();
;       const u16* Ab = ring + (kt & 1) * STG;
;       const u16* Bb = Ab + 16384;
;       u16* st = ring + ((kt + 1) & 1) * STG;
;       const bool pre = (kt + 1 < 32);
;       s16x8 af[2][4], bf[2][2];
;       auto ldfrag = [&](int ks, int slot) {
; #pragma unroll
;         for (int i = 0; i < 4; ++i) {
;           const int row = wr * 128 + i * 32 + lr;
;           af[slot][i] = *(const s16x8*)(Ab + row * 64 + (((ks * 2 + lh) ^ ((row >> 1) & 7)) * 8));
;         }
; #pragma unroll
;         for (int j = 0; j < 2; ++j) {
;           const int rowb = nh * 128 + wc * 64 + j * 32 + lr;
;           bf[slot][j] = *(const s16x8*)(Bb + rowb * 64 + (((ks * 2 + lh) ^ ((rowb >> 1) & 7)) * 8));
;         }
;       };
;       ldfrag(0, 0);
;       ldfrag(1, 1);
;       __builtin_amdgcn_sched_barrier(0);
; #pragma unroll
;       for (int ks = 0; ks < 4; ++ks) {
;         const int slot = ks & 1;
; #pragma unroll
;         for (int i = 0; i < 4; ++i) {
;           acc[i][0] = mfma32(af[slot][i], bf[slot][0], acc[i][0]);
;           acc[i][1] = mfma32(af[slot][i], bf[slot][1], acc[i][1]);
;           __builtin_amdgcn_sched_barrier(0);
;           if (pre && (i & 1) == 0) {
;             const int pi = ks * 2 + (i >> 1);
;             if (pi < 4) glds16(Ag0 + (size_t)pi * 64 * LDK + (kt + 1) * 64, st + (srow + 64 * pi) * 64 + sch * 8);
;             else glds16(Bg0 + (size_t)(pi - 4) * 64 * LDK + (kt + 1) * 64, st + 16384 + (srow + 64 * (pi - 4)) * 64 + sch * 8);
;             __builtin_amdgcn_sched_barrier(0);
;           }
;         }
;         if (ks + 2 < 4) { ldfrag(ks + 2, slot); __builtin_amdgcn_sched_barrier(0); }
;       }
.Lrot723_loop:
	s_add_i32 s15, s11, 0xffff8000
	s_and_b32 s15, s15, 0x8000
	s_lshl_b32 s15, s15, 1
	v_lshl_or_b32 v128, v143, 1, s15
	v_lshl_add_u32 v149, v147, 1, s15
	s_waitcnt lgkmcnt(7)
	v_mfma_f32_32x32x16_bf16 v[112:127], v[178:181], v[194:197], v[112:127]
	s_waitcnt lgkmcnt(6)
	v_mfma_f32_32x32x16_bf16 v[96:111], v[178:181], v[198:201], v[96:111]
	v_mfma_f32_32x32x16_bf16 v[80:95], v[182:185], v[194:197], v[80:95]
	v_mfma_f32_32x32x16_bf16 v[64:79], v[182:185], v[198:201], v[64:79]
	v_mfma_f32_32x32x16_bf16 v[48:63], v[186:189], v[194:197], v[48:63]
	v_mfma_f32_32x32x16_bf16 v[32:47], v[186:189], v[198:201], v[32:47]
	v_mfma_f32_32x32x16_bf16 v[16:31], v[190:193], v[194:197], v[16:31]
	v_mfma_f32_32x32x16_bf16 v[0:15], v[190:193], v[198:201], v[0:15]
	v_add_u32_e32 v177, v128, v175
	ds_read_b128 v[178:181], v177
	ds_read_b128 v[182:185], v177 offset:4096
	ds_read_b128 v[186:189], v177 offset:8192
	ds_read_b128 v[190:193], v177 offset:12288
	v_add_u32_e32 v177, v149, v175
	ds_read_b128 v[194:197], v177 offset:32768
	ds_read_b128 v[198:201], v177 offset:36864
	s_waitcnt lgkmcnt(7)
	v_mfma_f32_32x32x16_bf16 v[112:127], v[202:205], v[218:221], v[112:127]
	s_waitcnt lgkmcnt(6)
	v_mfma_f32_32x32x16_bf16 v[96:111], v[202:205], v[222:225], v[96:111]
	v_mfma_f32_32x32x16_bf16 v[80:95], v[206:209], v[218:221], v[80:95]
	v_mfma_f32_32x32x16_bf16 v[64:79], v[206:209], v[222:225], v[64:79]
	v_mfma_f32_32x32x16_bf16 v[48:63], v[210:213], v[218:221], v[48:63]
	v_mfma_f32_32x32x16_bf16 v[32:47], v[210:213], v[222:225], v[32:47]
	v_mfma_f32_32x32x16_bf16 v[16:31], v[214:217], v[218:221], v[16:31]
	v_mfma_f32_32x32x16_bf16 v[0:15], v[214:217], v[222:225], v[0:15]
	v_add_u32_e32 v128, v128, v176
	ds_read_b128 v[202:205], v128
	ds_read_b128 v[206:209], v128 offset:4096
	ds_read_b128 v[210:213], v128 offset:8192
	ds_read_b128 v[214:217], v128 offset:12288
	v_add_u32_e32 v128, v149, v176
	ds_read_b128 v[218:221], v128 offset:32768
	ds_read_b128 v[222:225], v128 offset:36864
	s_waitcnt lgkmcnt(7)
	v_mfma_f32_32x32x16_bf16 v[112:127], v[178:181], v[194:197], v[112:127]
	s_waitcnt lgkmcnt(6)
	v_mfma_f32_32x32x16_bf16 v[96:111], v[178:181], v[198:201], v[96:111]
	v_mfma_f32_32x32x16_bf16 v[80:95], v[182:185], v[194:197], v[80:95]
	v_mfma_f32_32x32x16_bf16 v[64:79], v[182:185], v[198:201], v[64:79]
	v_mfma_f32_32x32x16_bf16 v[48:63], v[186:189], v[194:197], v[48:63]
	v_mfma_f32_32x32x16_bf16 v[32:47], v[186:189], v[198:201], v[32:47]
	v_mfma_f32_32x32x16_bf16 v[16:31], v[190:193], v[194:197], v[16:31]
	v_mfma_f32_32x32x16_bf16 v[0:15], v[190:193], v[198:201], v[0:15]
	s_waitcnt vmcnt(0) lgkmcnt(0)
	s_barrier
	s_and_b32 s98, s11, 0x8000
	s_lshl_b32 s98, s98, 1
	v_lshl_or_b32 v227, v143, 1, s98
	v_lshl_add_u32 v229, v147, 1, s98
	v_add_u32_e32 v228, v227, v173
	v_add_u32_e32 v230, v229, v173
	ds_read_b128 v[178:181], v228
	ds_read_b128 v[182:185], v228 offset:4096
	ds_read_b128 v[186:189], v228 offset:8192
	ds_read_b128 v[190:193], v228 offset:12288
	ds_read_b128 v[194:197], v230 offset:32768
	ds_read_b128 v[198:201], v230 offset:36864
	v_add3_u32 v226, s15, v162, v156
	v_mfma_f32_32x32x16_bf16 v[112:127], v[202:205], v[218:221], v[112:127]
	v_readfirstlane_b32 s99, v226
	s_mov_b32 s16, m0
	s_mov_b32 m0, s99
	s_nop 0
	global_load_lds_dwordx4 v[158:159], off
	v_mfma_f32_32x32x16_bf16 v[96:111], v[202:205], v[222:225], v[96:111]
	v_lshl_add_u64 v[232:233], v[158:159], 0, s[2:3]
	s_add_i32 m0, s99, 0x2000
	s_nop 0
	global_load_lds_dwordx4 v[232:233], off
	v_mfma_f32_32x32x16_bf16 v[80:95], v[206:209], v[218:221], v[80:95]
	v_lshl_add_u64 v[234:235], v[158:159], 0, s[4:5]
	s_add_i32 m0, s99, 0x4000
	s_nop 0
	global_load_lds_dwordx4 v[234:235], off
	v_mfma_f32_32x32x16_bf16 v[64:79], v[206:209], v[222:225], v[64:79]
	v_lshl_add_u64 v[232:233], v[158:159], 0, s[6:7]
	s_add_i32 m0, s99, 0x6000
	s_nop 0
	global_load_lds_dwordx4 v[232:233], off
	v_mfma_f32_32x32x16_bf16 v[48:63], v[210:213], v[218:221], v[48:63]
	s_add_i32 m0, s99, 0x8000
	s_nop 0
	global_load_lds_dwordx4 v[160:161], off
	v_mfma_f32_32x32x16_bf16 v[32:47], v[210:213], v[222:225], v[32:47]
	v_lshl_add_u64 v[234:235], v[160:161], 0, s[2:3]
	s_add_i32 m0, s99, 0xa000
	s_nop 0
	global_load_lds_dwordx4 v[234:235], off
	v_mfma_f32_32x32x16_bf16 v[16:31], v[214:217], v[218:221], v[16:31]
	v_lshl_add_u64 v[232:233], v[160:161], 0, s[4:5]
	s_add_i32 m0, s99, 0xc000
	s_nop 0
	global_load_lds_dwordx4 v[232:233], off
	v_mfma_f32_32x32x16_bf16 v[0:15], v[214:217], v[222:225], v[0:15]
	v_lshl_add_u64 v[234:235], v[160:161], 0, s[6:7]
	s_add_i32 m0, s99, 0xe000
	s_nop 0
	global_load_lds_dwordx4 v[234:235], off
	s_mov_b32 m0, s16
	v_add_u32_e32 v228, v227, v174
	v_add_u32_e32 v230, v229, v174
	ds_read_b128 v[202:205], v228
	ds_read_b128 v[206:209], v228 offset:4096
	ds_read_b128 v[210:213], v228 offset:8192
	ds_read_b128 v[214:217], v228 offset:12288
	ds_read_b128 v[218:221], v230 offset:32768
	ds_read_b128 v[222:225], v230 offset:36864
	s_add_i32 s11, s11, 0x8000
	v_lshl_add_u64 v[158:159], v[158:159], 0, s[8:9]
	s_cmp_eq_u32 s11, 0xf8000
	v_lshl_add_u64 v[160:161], v[160:161], 0, s[8:9]
	s_cbranch_scc0 .Lrot723_loop
; template <int EPI, int PN>
; __device__ void gemm_phase(const Params& p, const u16* __restrict__ A, const u16* __restrict__ Bt, int nNt, char* smem) {
;     ...
;       for (int ks = 0; ks < 4; ++ks) {
;         const int slot = ks & 1;
; #pragma unroll
;         for (int i = 0; i < 4; ++i) {
;           acc[i][0] = mfma32(af[slot][i], bf[slot][0], acc[i][0]);
;           acc[i][1] = mfma32(af[slot][i], bf[slot][1], acc[i][1]);
;           __builtin_amdgcn_sched_barrier(0);
;           if (pre && (i & 1) == 0) {
;             const int pi = ks * 2 + (i >> 1);
;             if (pi < 4) glds16(Ag0 + (size_t)pi * 64 * LDK + (kt + 1) * 64, st + (srow + 64 * pi) * 64 + sch * 8);
;             else glds16(Bg0 + (size_t)(pi - 4) * 64 * LDK + (kt + 1) * 64, st + 16384 + (srow + 64 * (pi - 4)) * 64 + sch * 8);
;             __builtin_amdgcn_sched_barrier(0);
;           }
;         }
;         if (ks + 2 < 4) { ldfrag(ks + 2, slot); __builtin_amdgcn_sched_barrier(0); }
;       }
;     }
;     __syncthreads();
	s_add_i32 s15, s11, 0xffff8000
	s_and_b32 s15, s15, 0x8000
	s_lshl_b32 s15, s15, 1
	v_lshl_or_b32 v128, v143, 1, s15
	v_lshl_add_u32 v149, v147, 1, s15
	s_waitcnt lgkmcnt(7)
	v_mfma_f32_32x32x16_bf16 v[112:127], v[178:181], v[194:197], v[112:127]
	s_waitcnt lgkmcnt(6)
	v_mfma_f32_32x32x16_bf16 v[96:111], v[178:181], v[198:201], v[96:111]
	v_mfma_f32_32x32x16_bf16 v[80:95], v[182:185], v[194:197], v[80:95]
	v_mfma_f32_32x32x16_bf16 v[64:79], v[182:185], v[198:201], v[64:79]
	v_mfma_f32_32x32x16_bf16 v[48:63], v[186:189], v[194:197], v[48:63]
	v_mfma_f32_32x32x16_bf16 v[32:47], v[186:189], v[198:201], v[32:47]
	v_mfma_f32_32x32x16_bf16 v[16:31], v[190:193], v[194:197], v[16:31]
	v_mfma_f32_32x32x16_bf16 v[0:15], v[190:193], v[198:201], v[0:15]
	v_add_u32_e32 v177, v128, v175
	ds_read_b128 v[178:181], v177
	ds_read_b128 v[182:185], v177 offset:4096
	ds_read_b128 v[186:189], v177 offset:8192
	ds_read_b128 v[190:193], v177 offset:12288
	v_add_u32_e32 v177, v149, v175
	ds_read_b128 v[194:197], v177 offset:32768
	ds_read_b128 v[198:201], v177 offset:36864
	s_waitcnt lgkmcnt(7)
	v_mfma_f32_32x32x16_bf16 v[112:127], v[202:205], v[218:221], v[112:127]
	s_waitcnt lgkmcnt(6)
	v_mfma_f32_32x32x16_bf16 v[96:111], v[202:205], v[222:225], v[96:111]
	v_mfma_f32_32x32x16_bf16 v[80:95], v[206:209], v[218:221], v[80:95]
	v_mfma_f32_32x32x16_bf16 v[64:79], v[206:209], v[222:225], v[64:79]
	v_mfma_f32_32x32x16_bf16 v[48:63], v[210:213], v[218:221], v[48:63]
	v_mfma_f32_32x32x16_bf16 v[32:47], v[210:213], v[222:225], v[32:47]
	v_mfma_f32_32x32x16_bf16 v[16:31], v[214:217], v[218:221], v[16:31]
	v_mfma_f32_32x32x16_bf16 v[0:15], v[214:217], v[222:225], v[0:15]
	v_add_u32_e32 v128, v128, v176
	ds_read_b128 v[202:205], v128
	ds_read_b128 v[206:209], v128 offset:4096
	ds_read_b128 v[210:213], v128 offset:8192
	ds_read_b128 v[214:217], v128 offset:12288
	v_add_u32_e32 v128, v149, v176
	ds_read_b128 v[218:221], v128 offset:32768
	ds_read_b128 v[222:225], v128 offset:36864
	s_waitcnt lgkmcnt(7)
	v_mfma_f32_32x32x16_bf16 v[112:127], v[178:181], v[194:197], v[112:127]
	s_waitcnt lgkmcnt(6)
	v_mfma_f32_32x32x16_bf16 v[96:111], v[178:181], v[198:201], v[96:111]
	v_mfma_f32_32x32x16_bf16 v[80:95], v[182:185], v[194:197], v[80:95]
	v_mfma_f32_32x32x16_bf16 v[64:79], v[182:185], v[198:201], v[64:79]
	v_mfma_f32_32x32x16_bf16 v[48:63], v[186:189], v[194:197], v[48:63]
	v_mfma_f32_32x32x16_bf16 v[32:47], v[186:189], v[198:201], v[32:47]
	v_mfma_f32_32x32x16_bf16 v[16:31], v[190:193], v[194:197], v[16:31]
	v_mfma_f32_32x32x16_bf16 v[0:15], v[190:193], v[198:201], v[0:15]
	s_waitcnt lgkmcnt(1)
	v_mfma_f32_32x32x16_bf16 v[112:127], v[202:205], v[218:221], v[112:127]
	s_waitcnt lgkmcnt(0)
	v_mfma_f32_32x32x16_bf16 v[96:111], v[202:205], v[222:225], v[96:111]
	v_mfma_f32_32x32x16_bf16 v[80:95], v[206:209], v[218:221], v[80:95]
	v_mfma_f32_32x32x16_bf16 v[64:79], v[206:209], v[222:225], v[64:79]
	v_mfma_f32_32x32x16_bf16 v[48:63], v[210:213], v[218:221], v[48:63]
	v_mfma_f32_32x32x16_bf16 v[32:47], v[210:213], v[222:225], v[32:47]
	v_mfma_f32_32x32x16_bf16 v[16:31], v[214:217], v[218:221], v[16:31]
	v_mfma_f32_32x32x16_bf16 v[0:15], v[214:217], v[222:225], v[0:15]
	s_waitcnt vmcnt(0)
	s_barrier
	ds_read_b128 v[158:161], v164
	ds_read_b128 v[178:181], v164 offset:4096
	ds_read_b128 v[182:185], v164 offset:8192
	ds_read_b128 v[186:189], v164 offset:12288
	ds_read_b128 v[190:193], v165
	ds_read_b128 v[194:197], v165 offset:4096
	ds_read_b128 v[198:201], v166
	ds_read_b128 v[202:205], v166 offset:4096
	ds_read_b128 v[206:209], v166 offset:8192
	ds_read_b128 v[210:213], v166 offset:12288
	ds_read_b128 v[214:217], v168
	ds_read_b128 v[218:221], v168 offset:4096
	s_waitcnt lgkmcnt(7)
	v_mfma_f32_32x32x16_bf16 v[112:127], v[158:161], v[190:193], v[112:127]
	s_waitcnt lgkmcnt(6)
	v_mfma_f32_32x32x16_bf16 v[96:111], v[158:161], v[194:197], v[96:111]
	v_mfma_f32_32x32x16_bf16 v[80:95], v[178:181], v[190:193], v[80:95]
	v_mfma_f32_32x32x16_bf16 v[64:79], v[178:181], v[194:197], v[64:79]
	v_mfma_f32_32x32x16_bf16 v[48:63], v[182:185], v[190:193], v[48:63]
	v_mfma_f32_32x32x16_bf16 v[32:47], v[182:185], v[194:197], v[32:47]
	v_mfma_f32_32x32x16_bf16 v[16:31], v[186:189], v[190:193], v[16:31]
	v_mfma_f32_32x32x16_bf16 v[0:15], v[186:189], v[194:197], v[0:15]
	ds_read_b128 v[158:161], v169
	ds_read_b128 v[178:181], v169 offset:4096
	ds_read_b128 v[182:185], v169 offset:8192
	ds_read_b128 v[186:189], v169 offset:12288
	ds_read_b128 v[190:193], v170
	ds_read_b128 v[194:197], v170 offset:4096
	s_waitcnt lgkmcnt(7)
	v_mfma_f32_32x32x16_bf16 v[112:127], v[198:201], v[214:217], v[112:127]
	s_waitcnt lgkmcnt(6)
	v_mfma_f32_32x32x16_bf16 v[96:111], v[198:201], v[218:221], v[96:111]
	v_mfma_f32_32x32x16_bf16 v[80:95], v[202:205], v[214:217], v[80:95]
	v_mfma_f32_32x32x16_bf16 v[64:79], v[202:205], v[218:221], v[64:79]
	v_mfma_f32_32x32x16_bf16 v[48:63], v[206:209], v[214:217], v[48:63]
	v_mfma_f32_32x32x16_bf16 v[32:47], v[206:209], v[218:221], v[32:47]
	v_mfma_f32_32x32x16_bf16 v[16:31], v[210:213], v[214:217], v[16:31]
	v_mfma_f32_32x32x16_bf16 v[0:15], v[210:213], v[218:221], v[0:15]
	ds_read_b128 v[198:201], v171
	ds_read_b128 v[202:205], v171 offset:4096
	ds_read_b128 v[206:209], v171 offset:8192
	ds_read_b128 v[210:213], v171 offset:12288
	ds_read_b128 v[214:217], v172
	ds_read_b128 v[218:221], v172 offset:4096
	s_waitcnt lgkmcnt(7)
	v_mfma_f32_32x32x16_bf16 v[112:127], v[158:161], v[190:193], v[112:127]
	s_waitcnt lgkmcnt(6)
	v_mfma_f32_32x32x16_bf16 v[96:111], v[158:161], v[194:197], v[96:111]
	v_mfma_f32_32x32x16_bf16 v[80:95], v[178:181], v[190:193], v[80:95]
	v_mfma_f32_32x32x16_bf16 v[64:79], v[178:181], v[194:197], v[64:79]
	v_mfma_f32_32x32x16_bf16 v[48:63], v[182:185], v[190:193], v[48:63]
	v_mfma_f32_32x32x16_bf16 v[32:47], v[182:185], v[194:197], v[32:47]
	v_mfma_f32_32x32x16_bf16 v[16:31], v[186:189], v[190:193], v[16:31]
	v_mfma_f32_32x32x16_bf16 v[0:15], v[186:189], v[194:197], v[0:15]
	s_waitcnt lgkmcnt(1)
	v_mfma_f32_32x32x16_bf16 v[112:127], v[198:201], v[214:217], v[112:127]
	s_waitcnt lgkmcnt(0)
	v_mfma_f32_32x32x16_bf16 v[96:111], v[198:201], v[218:221], v[96:111]
	v_mfma_f32_32x32x16_bf16 v[80:95], v[202:205], v[214:217], v[80:95]
	v_mfma_f32_32x32x16_bf16 v[64:79], v[202:205], v[218:221], v[64:79]
	v_mfma_f32_32x32x16_bf16 v[48:63], v[206:209], v[214:217], v[48:63]
	v_mfma_f32_32x32x16_bf16 v[32:47], v[206:209], v[218:221], v[32:47]
	v_mfma_f32_32x32x16_bf16 v[16:31], v[210:213], v[214:217], v[16:31]
	v_mfma_f32_32x32x16_bf16 v[0:15], v[210:213], v[218:221], v[0:15]
	v_mov_b32_e32 v149, v135
	v_mov_b32_e32 v128, v139
	v_mov_b32_e32 v158, v137
	s_barrier
; __device__ __forceinline__ int accrow(int reg, int lh) { return (reg & 3) + 8 * (reg >> 2) + 4 * lh; }
; template <int EPI, int PN>
; __device__ void gemm_phase(const Params& p, const u16* __restrict__ A, const u16* __restrict__ Bt, int nNt, char* smem) {
;     ...
; #pragma unroll
;       for (int i = 0; i < 4; ++i)
; #pragma unroll
;         for (int j = 0; j < 2; ++j)
; #pragma unroll
;           for (int r = 0; r < 16; ++r) *(u16*)(et + (i * 32 + accrow(r, lhE)) * 144 + (j * 32 + lrE) * 2) = f2bf(acc[i][j][r]);
	s_nop 7
	v_cvt_pk_bf16_f32 v0, v0, s0
	v_lshlrev_b32_e32 v158, 1, v158
	v_mul_lo_u32 v128, v128, s12
	v_add3_u32 v128, v163, v158, v128
	v_cvt_pk_bf16_f32 v112, v112, s0
	v_cvt_pk_bf16_f32 v96, v96, s0
	v_cvt_pk_bf16_f32 v80, v80, s0
	v_cvt_pk_bf16_f32 v64, v64, s0
	v_cvt_pk_bf16_f32 v48, v48, s0
	v_cvt_pk_bf16_f32 v32, v32, s0
	v_cvt_pk_bf16_f32 v16, v16, s0
	ds_write_b16 v128, v0 offset:13888
	v_cvt_pk_bf16_f32 v0, v1, s0
	ds_write_b16 v128, v112
	v_cvt_pk_bf16_f32 v112, v113, s0
	ds_write_b16 v128, v96 offset:64
	v_cvt_pk_bf16_f32 v96, v97, s0
	ds_write_b16 v128, v80 offset:4608
	v_cvt_pk_bf16_f32 v80, v81, s0
	ds_write_b16 v128, v64 offset:4672
	v_cvt_pk_bf16_f32 v64, v65, s0
	ds_write_b16 v128, v48 offset:9216
	v_cvt_pk_bf16_f32 v48, v49, s0
	ds_write_b16 v128, v32 offset:9280
	v_cvt_pk_bf16_f32 v32, v33, s0
	ds_write_b16 v128, v16 offset:13824
	v_cvt_pk_bf16_f32 v16, v17, s0
	ds_write_b16 v128, v0 offset:14032
	v_cvt_pk_bf16_f32 v0, v2, s0
	ds_write_b16 v128, v112 offset:144
	v_cvt_pk_bf16_f32 v112, v114, s0
	ds_write_b16 v128, v96 offset:208
	v_cvt_pk_bf16_f32 v96, v98, s0
	ds_write_b16 v128, v80 offset:4752
	v_cvt_pk_bf16_f32 v80, v82, s0
	ds_write_b16 v128, v64 offset:4816
	v_cvt_pk_bf16_f32 v64, v66, s0
	ds_write_b16 v128, v48 offset:9360
	v_cvt_pk_bf16_f32 v48, v50, s0
	ds_write_b16 v128, v32 offset:9424
	v_cvt_pk_bf16_f32 v32, v34, s0
	ds_write_b16 v128, v16 offset:13968
	v_cvt_pk_bf16_f32 v16, v18, s0
	ds_write_b16 v128, v0 offset:14176
	v_cvt_pk_bf16_f32 v0, v3, s0
	ds_write_b16 v128, v112 offset:288
	v_cvt_pk_bf16_f32 v112, v115, s0
	ds_write_b16 v128, v96 offset:352
	v_cvt_pk_bf16_f32 v96, v99, s0
	ds_write_b16 v128, v80 offset:4896
	v_cvt_pk_bf16_f32 v80, v83, s0
	ds_write_b16 v128, v64 offset:4960
	v_cvt_pk_bf16_f32 v64, v67, s0
	ds_write_b16 v128, v48 offset:9504
	v_cvt_pk_bf16_f32 v48, v51, s0
	ds_write_b16 v128, v32 offset:9568
	v_cvt_pk_bf16_f32 v32, v35, s0
	ds_write_b16 v128, v16 offset:14112
	v_cvt_pk_bf16_f32 v16, v19, s0
	ds_write_b16 v128, v0 offset:14320
	v_cvt_pk_bf16_f32 v0, v4, s0
	ds_write_b16 v128, v112 offset:432
	v_cvt_pk_bf16_f32 v112, v116, s0
	ds_write_b16 v128, v96 offset:496
	v_cvt_pk_bf16_f32 v96, v100, s0
	ds_write_b16 v128, v80 offset:5040
	v_cvt_pk_bf16_f32 v80, v84, s0
	ds_write_b16 v128, v64 offset:5104
	v_cvt_pk_bf16_f32 v64, v68, s0
	ds_write_b16 v128, v48 offset:9648
	v_cvt_pk_bf16_f32 v48, v52, s0
	ds_write_b16 v128, v32 offset:9712
	v_cvt_pk_bf16_f32 v32, v36, s0
	ds_write_b16 v128, v16 offset:14256
	v_cvt_pk_bf16_f32 v16, v20, s0
	ds_write_b16 v128, v0 offset:15040
	v_cvt_pk_bf16_f32 v0, v5, s0
	ds_write_b16 v128, v112 offset:1152
	v_cvt_pk_bf16_f32 v112, v117, s0
	ds_write_b16 v128, v96 offset:1216
	v_cvt_pk_bf16_f32 v96, v101, s0
	ds_write_b16 v128, v80 offset:5760
	v_cvt_pk_bf16_f32 v80, v85, s0
	ds_write_b16 v128, v64 offset:5824
	v_cvt_pk_bf16_f32 v64, v69, s0
	ds_write_b16 v128, v48 offset:10368
	v_cvt_pk_bf16_f32 v48, v53, s0
	ds_write_b16 v128, v32 offset:10432
	v_cvt_pk_bf16_f32 v32, v37, s0
	ds_write_b16 v128, v16 offset:14976
	v_cvt_pk_bf16_f32 v16, v21, s0
	ds_write_b16 v128, v0 offset:15184
	v_cvt_pk_bf16_f32 v0, v6, s0
	ds_write_b16 v128, v112 offset:1296
	v_cvt_pk_bf16_f32 v112, v118, s0
	ds_write_b16 v128, v96 offset:1360
	v_cvt_pk_bf16_f32 v96, v102, s0
	ds_write_b16 v128, v80 offset:5904
	v_cvt_pk_bf16_f32 v80, v86, s0
	ds_write_b16 v128, v64 offset:5968
	v_cvt_pk_bf16_f32 v64, v70, s0
	ds_write_b16 v128, v48 offset:10512
	v_cvt_pk_bf16_f32 v48, v54, s0
	ds_write_b16 v128, v32 offset:10576
	v_cvt_pk_bf16_f32 v32, v38, s0
	ds_write_b16 v128, v16 offset:15120
	v_cvt_pk_bf16_f32 v16, v22, s0
	ds_write_b16 v128, v0 offset:15328
	v_cvt_pk_bf16_f32 v0, v7, s0
	ds_write_b16 v128, v112 offset:1440
	v_cvt_pk_bf16_f32 v112, v119, s0
	ds_write_b16 v128, v96 offset:1504
	v_cvt_pk_bf16_f32 v96, v103, s0
	ds_write_b16 v128, v80 offset:6048
	v_cvt_pk_bf16_f32 v80, v87, s0
	ds_write_b16 v128, v64 offset:6112
	v_cvt_pk_bf16_f32 v64, v71, s0
	ds_write_b16 v128, v48 offset:10656
	v_cvt_pk_bf16_f32 v48, v55, s0
	ds_write_b16 v128, v32 offset:10720
	v_cvt_pk_bf16_f32 v32, v39, s0
	ds_write_b16 v128, v16 offset:15264
	v_cvt_pk_bf16_f32 v16, v23, s0
	ds_write_b16 v128, v0 offset:15472
	v_cvt_pk_bf16_f32 v0, v8, s0
	ds_write_b16 v128, v112 offset:1584
	v_cvt_pk_bf16_f32 v112, v120, s0
	ds_write_b16 v128, v96 offset:1648
	v_cvt_pk_bf16_f32 v96, v104, s0
	ds_write_b16 v128, v80 offset:6192
	v_cvt_pk_bf16_f32 v80, v88, s0
	ds_write_b16 v128, v64 offset:6256
	v_cvt_pk_bf16_f32 v64, v72, s0
	ds_write_b16 v128, v48 offset:10800
	v_cvt_pk_bf16_f32 v48, v56, s0
	ds_write_b16 v128, v32 offset:10864
	v_cvt_pk_bf16_f32 v32, v40, s0
	ds_write_b16 v128, v16 offset:15408
	v_cvt_pk_bf16_f32 v16, v24, s0
	ds_write_b16 v128, v0 offset:16192
	v_cvt_pk_bf16_f32 v0, v9, s0
	ds_write_b16 v128, v112 offset:2304
	v_cvt_pk_bf16_f32 v112, v121, s0
	ds_write_b16 v128, v96 offset:2368
	v_cvt_pk_bf16_f32 v96, v105, s0
	ds_write_b16 v128, v80 offset:6912
	v_cvt_pk_bf16_f32 v80, v89, s0
	ds_write_b16 v128, v64 offset:6976
	v_cvt_pk_bf16_f32 v64, v73, s0
	ds_write_b16 v128, v48 offset:11520
	v_cvt_pk_bf16_f32 v48, v57, s0
	ds_write_b16 v128, v32 offset:11584
	v_cvt_pk_bf16_f32 v32, v41, s0
	ds_write_b16 v128, v16 offset:16128
	v_cvt_pk_bf16_f32 v16, v25, s0
	ds_write_b16 v128, v0 offset:16336
	v_cvt_pk_bf16_f32 v0, v10, s0
	ds_write_b16 v128, v112 offset:2448
	v_cvt_pk_bf16_f32 v112, v122, s0
	ds_write_b16 v128, v96 offset:2512
	v_cvt_pk_bf16_f32 v96, v106, s0
	ds_write_b16 v128, v80 offset:7056
	v_cvt_pk_bf16_f32 v80, v90, s0
	ds_write_b16 v128, v64 offset:7120
	v_cvt_pk_bf16_f32 v64, v74, s0
	ds_write_b16 v128, v48 offset:11664
; __device__ __forceinline__ int accrow(int reg, int lh) { return (reg & 3) + 8 * (reg >> 2) + 4 * lh; }
; template <int EPI, int PN>
; __device__ void gemm_phase(const Params& p, const u16* __restrict__ A, const u16* __restrict__ Bt, int nNt, char* smem) {
;     ...
;           for (int r = 0; r < 16; ++r) *(u16*)(et + (i * 32 + accrow(r, lhE)) * 144 + (j * 32 + lrE) * 2) = f2bf(acc[i][j][r]);
; #pragma unroll
;       for (int it = 0; it < 16; ++it) {
;         const int c = it * 64 + laneE, row = c >> 3, seg = c & 7;
;         const uint4 v = *(const uint4*)(et + row * 144 + seg * 16);
;         if (EPI == 0) *(uint4*)(p.proj + (row0 + row) * NPROJ + col0 + seg * 8) = v;
;         else *(uint4*)(p.qp + (row0 + row) * DM + col0 + seg * 8) = v;
;       }
	v_cvt_pk_bf16_f32 v48, v58, s0
	ds_write_b16 v128, v32 offset:11728
	v_cvt_pk_bf16_f32 v32, v42, s0
	ds_write_b16 v128, v16 offset:16272
	v_cvt_pk_bf16_f32 v16, v26, s0
	ds_write_b16 v128, v0 offset:16480
	v_cvt_pk_bf16_f32 v0, v11, s0
	ds_write_b16 v128, v112 offset:2592
	v_cvt_pk_bf16_f32 v112, v123, s0
	ds_write_b16 v128, v96 offset:2656
	v_cvt_pk_bf16_f32 v96, v107, s0
	ds_write_b16 v128, v80 offset:7200
	v_cvt_pk_bf16_f32 v80, v91, s0
	ds_write_b16 v128, v64 offset:7264
	v_cvt_pk_bf16_f32 v64, v75, s0
	ds_write_b16 v128, v48 offset:11808
	v_cvt_pk_bf16_f32 v48, v59, s0
	ds_write_b16 v128, v32 offset:11872
	v_cvt_pk_bf16_f32 v32, v43, s0
	ds_write_b16 v128, v16 offset:16416
	v_cvt_pk_bf16_f32 v16, v27, s0
	ds_write_b16 v128, v0 offset:16624
	v_cvt_pk_bf16_f32 v0, v12, s0
	ds_write_b16 v128, v112 offset:2736
	v_cvt_pk_bf16_f32 v112, v124, s0
	ds_write_b16 v128, v96 offset:2800
	v_cvt_pk_bf16_f32 v96, v108, s0
	ds_write_b16 v128, v80 offset:7344
	v_cvt_pk_bf16_f32 v80, v92, s0
	ds_write_b16 v128, v64 offset:7408
	v_cvt_pk_bf16_f32 v64, v76, s0
	ds_write_b16 v128, v48 offset:11952
	v_cvt_pk_bf16_f32 v48, v60, s0
	ds_write_b16 v128, v32 offset:12016
	v_cvt_pk_bf16_f32 v32, v44, s0
	ds_write_b16 v128, v16 offset:16560
	v_cvt_pk_bf16_f32 v16, v28, s0
	ds_write_b16 v128, v0 offset:17344
	v_cvt_pk_bf16_f32 v0, v13, s0
	ds_write_b16 v128, v112 offset:3456
	v_cvt_pk_bf16_f32 v112, v125, s0
	ds_write_b16 v128, v96 offset:3520
	v_cvt_pk_bf16_f32 v96, v109, s0
	ds_write_b16 v128, v80 offset:8064
	v_cvt_pk_bf16_f32 v80, v93, s0
	ds_write_b16 v128, v64 offset:8128
	v_cvt_pk_bf16_f32 v64, v77, s0
	ds_write_b16 v128, v48 offset:12672
	v_cvt_pk_bf16_f32 v48, v61, s0
	ds_write_b16 v128, v32 offset:12736
	v_cvt_pk_bf16_f32 v32, v45, s0
	ds_write_b16 v128, v16 offset:17280
	v_cvt_pk_bf16_f32 v16, v29, s0
	ds_write_b16 v128, v0 offset:17488
	v_cvt_pk_bf16_f32 v0, v14, s0
	ds_write_b16 v128, v112 offset:3600
	v_cvt_pk_bf16_f32 v112, v126, s0
	ds_write_b16 v128, v96 offset:3664
	v_cvt_pk_bf16_f32 v96, v110, s0
	ds_write_b16 v128, v80 offset:8208
	v_cvt_pk_bf16_f32 v80, v94, s0
	ds_write_b16 v128, v64 offset:8272
	v_cvt_pk_bf16_f32 v64, v78, s0
	ds_write_b16 v128, v48 offset:12816
	v_cvt_pk_bf16_f32 v48, v62, s0
	ds_write_b16 v128, v32 offset:12880
	v_cvt_pk_bf16_f32 v32, v46, s0
	ds_write_b16 v128, v16 offset:17424
	v_cvt_pk_bf16_f32 v16, v30, s0
	ds_write_b16 v128, v0 offset:17632
	v_cvt_pk_bf16_f32 v0, v15, s0
	s_ashr_i32 s11, s10, 31
	ds_write_b16 v128, v112 offset:3744
	v_cvt_pk_bf16_f32 v112, v127, s0
	ds_write_b16 v128, v96 offset:3808
	v_cvt_pk_bf16_f32 v96, v111, s0
	ds_write_b16 v128, v80 offset:8352
	v_cvt_pk_bf16_f32 v80, v95, s0
	ds_write_b16 v128, v64 offset:8416
	v_cvt_pk_bf16_f32 v64, v79, s0
	ds_write_b16 v128, v48 offset:12960
	v_cvt_pk_bf16_f32 v48, v63, s0
	ds_write_b16 v128, v32 offset:13024
	v_cvt_pk_bf16_f32 v32, v47, s0
	ds_write_b16 v128, v16 offset:17568
	v_cvt_pk_bf16_f32 v16, v31, s0
	ds_write_b16 v128, v0 offset:17776
	v_lshlrev_b32_e32 v0, 4, v149
	s_lshl_b64 s[10:11], s[10:11], 8
	ds_write_b16 v128, v112 offset:3888
	ds_write_b16 v128, v96 offset:3952
	ds_write_b16 v128, v80 offset:8496
	ds_write_b16 v128, v64 offset:8560
	ds_write_b16 v128, v48 offset:13104
	ds_write_b16 v128, v32 offset:13168
	ds_write_b16 v128, v16 offset:17712
	v_and_b32_e32 v128, 0x70, v0
	v_ashrrev_i32_e32 v6, 3, v149
	v_mov_b32_e32 v9, s11
	v_or_b32_e32 v8, s10, v134
	v_add_u32_e32 v10, v163, v128
	v_ashrrev_i32_e32 v7, 31, v6
	v_lshl_add_u32 v4, s14, 8, v145
	v_mad_u64_u32 v[0:1], s[10:11], v6, s13, v[10:11]
	v_lshl_add_u64 v[6:7], v[8:9], 0, v[6:7]
	v_readlane_b32 s16, v253, 39
	v_ashrrev_i32_e32 v5, 31, v4
	v_lshlrev_b64 v[6:7], 12, v[6:7]
	v_readlane_b32 s26, v253, 49
	v_readlane_b32 s27, v253, 50
	ds_read_b128 v[0:3], v0
	v_lshlrev_b64 v[12:13], 1, v[4:5]
	v_lshl_add_u64 v[6:7], s[26:27], 0, v[6:7]
	v_lshl_add_u64 v[4:5], v[6:7], 0, v[12:13]
	v_lshl_add_u64 v[14:15], v[4:5], 0, v[128:129]
	v_add_u32_e32 v4, 64, v149
	v_ashrrev_i32_e32 v16, 3, v4
	v_mad_u64_u32 v[4:5], s[10:11], v16, s13, v[10:11]
	v_ashrrev_i32_e32 v17, 31, v16
	ds_read_b128 v[4:7], v4
	s_waitcnt lgkmcnt(1)
	global_store_dwordx4 v[14:15], v[0:3], off
	v_readlane_b32 s17, v253, 40
	v_readlane_b32 s18, v253, 41
	v_lshl_add_u64 v[0:1], v[8:9], 0, v[16:17]
	v_lshlrev_b64 v[0:1], 12, v[0:1]
	v_lshl_add_u64 v[0:1], s[26:27], 0, v[0:1]
	v_lshl_add_u64 v[0:1], v[0:1], 0, v[12:13]
	v_lshl_add_u64 v[0:1], v[0:1], 0, v[128:129]
	s_waitcnt lgkmcnt(0)
	global_store_dwordx4 v[0:1], v[4:7], off
	v_add_u32_e32 v0, 0x80, v149
	v_readlane_b32 s19, v253, 42
	v_ashrrev_i32_e32 v4, 3, v0
	v_ashrrev_i32_e32 v5, 31, v4
	v_mad_u64_u32 v[0:1], s[10:11], v4, s13, v[10:11]
	v_lshl_add_u64 v[4:5], v[8:9], 0, v[4:5]
	v_lshlrev_b64 v[4:5], 12, v[4:5]
	ds_read_b128 v[0:3], v0
	v_lshl_add_u64 v[4:5], s[26:27], 0, v[4:5]
	v_lshl_add_u64 v[4:5], v[4:5], 0, v[12:13]
	v_lshl_add_u64 v[14:15], v[4:5], 0, v[128:129]
	v_add_u32_e32 v4, 0xc0, v149
	v_ashrrev_i32_e32 v16, 3, v4
	v_mad_u64_u32 v[4:5], s[10:11], v16, s13, v[10:11]
	v_ashrrev_i32_e32 v17, 31, v16
	ds_read_b128 v[4:7], v4
	s_waitcnt lgkmcnt(1)
	global_store_dwordx4 v[14:15], v[0:3], off
	v_readlane_b32 s20, v253, 43
	v_readlane_b32 s21, v253, 44
	v_lshl_add_u64 v[0:1], v[8:9], 0, v[16:17]
	v_lshlrev_b64 v[0:1], 12, v[0:1]
	v_lshl_add_u64 v[0:1], s[26:27], 0, v[0:1]
	v_lshl_add_u64 v[0:1], v[0:1], 0, v[12:13]
	v_lshl_add_u64 v[0:1], v[0:1], 0, v[128:129]
	s_waitcnt lgkmcnt(0)
; template <int EPI, int PN>
; __device__ void gemm_phase(const Params& p, const u16* __restrict__ A, const u16* __restrict__ Bt, int nNt, char* smem) {
;     ...
;   for (int q = jb;; q += NJ) {
;     const int pl = q / (4 * PN), w = q % (4 * PN);
;     const int gp = pl * 8 + xcd;
;     if (gp >= npatch) break;
;     ...
;       for (int it = 0; it < 16; ++it) {
;         const int c = it * 64 + laneE, row = c >> 3, seg = c & 7;
;         const uint4 v = *(const uint4*)(et + row * 144 + seg * 16);
;         if (EPI == 0) *(uint4*)(p.proj + (row0 + row) * NPROJ + col0 + seg * 8) = v;
;         else *(uint4*)(p.qp + (row0 + row) * DM + col0 + seg * 8) = v;
;       }
;     }
;     __syncthreads();
	global_store_dwordx4 v[0:1], v[4:7], off
	v_add_u32_e32 v0, 0x100, v149
	v_readlane_b32 s22, v253, 45
	v_ashrrev_i32_e32 v4, 3, v0
	v_ashrrev_i32_e32 v5, 31, v4
	v_mad_u64_u32 v[0:1], s[10:11], v4, s13, v[10:11]
	v_lshl_add_u64 v[4:5], v[8:9], 0, v[4:5]
	v_lshlrev_b64 v[4:5], 12, v[4:5]
	ds_read_b128 v[0:3], v0
	v_lshl_add_u64 v[4:5], s[26:27], 0, v[4:5]
	v_lshl_add_u64 v[4:5], v[4:5], 0, v[12:13]
	v_lshl_add_u64 v[14:15], v[4:5], 0, v[128:129]
	v_add_u32_e32 v4, 0x140, v149
	v_ashrrev_i32_e32 v16, 3, v4
	v_mad_u64_u32 v[4:5], s[10:11], v16, s13, v[10:11]
	v_ashrrev_i32_e32 v17, 31, v16
	ds_read_b128 v[4:7], v4
	s_waitcnt lgkmcnt(1)
	global_store_dwordx4 v[14:15], v[0:3], off
	v_readlane_b32 s23, v253, 46
	v_readlane_b32 s24, v253, 47
	v_lshl_add_u64 v[0:1], v[8:9], 0, v[16:17]
	v_lshlrev_b64 v[0:1], 12, v[0:1]
	v_lshl_add_u64 v[0:1], s[26:27], 0, v[0:1]
	v_lshl_add_u64 v[0:1], v[0:1], 0, v[12:13]
	v_lshl_add_u64 v[0:1], v[0:1], 0, v[128:129]
	s_waitcnt lgkmcnt(0)
	global_store_dwordx4 v[0:1], v[4:7], off
	v_add_u32_e32 v0, 0x180, v149
	v_readlane_b32 s25, v253, 48
	v_ashrrev_i32_e32 v4, 3, v0
	v_ashrrev_i32_e32 v5, 31, v4
	v_mad_u64_u32 v[0:1], s[10:11], v4, s13, v[10:11]
	v_lshl_add_u64 v[4:5], v[8:9], 0, v[4:5]
	v_lshlrev_b64 v[4:5], 12, v[4:5]
	ds_read_b128 v[0:3], v0
	v_lshl_add_u64 v[4:5], s[26:27], 0, v[4:5]
	v_lshl_add_u64 v[4:5], v[4:5], 0, v[12:13]
	v_lshl_add_u64 v[14:15], v[4:5], 0, v[128:129]
	v_add_u32_e32 v4, 0x1c0, v149
	v_ashrrev_i32_e32 v16, 3, v4
	v_mad_u64_u32 v[4:5], s[10:11], v16, s13, v[10:11]
	v_ashrrev_i32_e32 v17, 31, v16
	ds_read_b128 v[4:7], v4
	s_waitcnt lgkmcnt(1)
	global_store_dwordx4 v[14:15], v[0:3], off
	v_readlane_b32 s28, v253, 51
	v_readlane_b32 s29, v253, 52
	v_lshl_add_u64 v[0:1], v[8:9], 0, v[16:17]
	v_lshlrev_b64 v[0:1], 12, v[0:1]
	v_lshl_add_u64 v[0:1], s[26:27], 0, v[0:1]
	v_lshl_add_u64 v[0:1], v[0:1], 0, v[12:13]
	v_lshl_add_u64 v[0:1], v[0:1], 0, v[128:129]
	s_waitcnt lgkmcnt(0)
	global_store_dwordx4 v[0:1], v[4:7], off
	v_add_u32_e32 v0, 0x200, v149
	v_readlane_b32 s30, v253, 53
	v_ashrrev_i32_e32 v4, 3, v0
	v_ashrrev_i32_e32 v5, 31, v4
	v_mad_u64_u32 v[0:1], s[10:11], v4, s13, v[10:11]
	v_lshl_add_u64 v[4:5], v[8:9], 0, v[4:5]
	v_lshlrev_b64 v[4:5], 12, v[4:5]
	ds_read_b128 v[0:3], v0
	v_lshl_add_u64 v[4:5], s[26:27], 0, v[4:5]
	v_lshl_add_u64 v[4:5], v[4:5], 0, v[12:13]
	v_lshl_add_u64 v[14:15], v[4:5], 0, v[128:129]
	v_add_u32_e32 v4, 0x240, v149
	v_ashrrev_i32_e32 v16, 3, v4
	v_mad_u64_u32 v[4:5], s[10:11], v16, s13, v[10:11]
	v_ashrrev_i32_e32 v17, 31, v16
	ds_read_b128 v[4:7], v4
	s_waitcnt lgkmcnt(1)
	global_store_dwordx4 v[14:15], v[0:3], off
	v_readlane_b32 s31, v253, 54
	s_nop 0
	v_lshl_add_u64 v[0:1], v[8:9], 0, v[16:17]
	v_lshlrev_b64 v[0:1], 12, v[0:1]
	v_lshl_add_u64 v[0:1], s[26:27], 0, v[0:1]
	v_lshl_add_u64 v[0:1], v[0:1], 0, v[12:13]
	v_lshl_add_u64 v[0:1], v[0:1], 0, v[128:129]
	s_waitcnt lgkmcnt(0)
	global_store_dwordx4 v[0:1], v[4:7], off
	v_add_u32_e32 v0, 0x280, v149
	s_nop 0
	v_ashrrev_i32_e32 v4, 3, v0
	v_ashrrev_i32_e32 v5, 31, v4
	v_mad_u64_u32 v[0:1], s[10:11], v4, s13, v[10:11]
	v_lshl_add_u64 v[4:5], v[8:9], 0, v[4:5]
	v_lshlrev_b64 v[4:5], 12, v[4:5]
	ds_read_b128 v[0:3], v0
	v_lshl_add_u64 v[4:5], s[26:27], 0, v[4:5]
	v_lshl_add_u64 v[4:5], v[4:5], 0, v[12:13]
	v_lshl_add_u64 v[14:15], v[4:5], 0, v[128:129]
	v_add_u32_e32 v4, 0x2c0, v149
	v_ashrrev_i32_e32 v16, 3, v4
	v_mad_u64_u32 v[4:5], s[10:11], v16, s13, v[10:11]
	v_ashrrev_i32_e32 v17, 31, v16
	ds_read_b128 v[4:7], v4
	s_waitcnt lgkmcnt(1)
	global_store_dwordx4 v[14:15], v[0:3], off
	s_nop 1
	v_lshl_add_u64 v[0:1], v[8:9], 0, v[16:17]
	v_lshlrev_b64 v[0:1], 12, v[0:1]
	v_lshl_add_u64 v[0:1], s[26:27], 0, v[0:1]
	v_lshl_add_u64 v[0:1], v[0:1], 0, v[12:13]
	v_lshl_add_u64 v[0:1], v[0:1], 0, v[128:129]
	s_waitcnt lgkmcnt(0)
	global_store_dwordx4 v[0:1], v[4:7], off
	v_add_u32_e32 v0, 0x300, v149
	s_nop 0
	v_ashrrev_i32_e32 v4, 3, v0
	v_ashrrev_i32_e32 v5, 31, v4
	v_mad_u64_u32 v[0:1], s[10:11], v4, s13, v[10:11]
	v_lshl_add_u64 v[4:5], v[8:9], 0, v[4:5]
	v_lshlrev_b64 v[4:5], 12, v[4:5]
	ds_read_b128 v[0:3], v0
	v_lshl_add_u64 v[4:5], s[26:27], 0, v[4:5]
	v_lshl_add_u64 v[4:5], v[4:5], 0, v[12:13]
	v_lshl_add_u64 v[14:15], v[4:5], 0, v[128:129]
	v_add_u32_e32 v4, 0x340, v149
	v_ashrrev_i32_e32 v16, 3, v4
	v_mad_u64_u32 v[4:5], s[10:11], v16, s13, v[10:11]
	v_ashrrev_i32_e32 v17, 31, v16
	ds_read_b128 v[4:7], v4
	s_waitcnt lgkmcnt(1)
	global_store_dwordx4 v[14:15], v[0:3], off
	s_nop 1
	v_lshl_add_u64 v[0:1], v[8:9], 0, v[16:17]
	v_lshlrev_b64 v[0:1], 12, v[0:1]
	v_lshl_add_u64 v[0:1], s[26:27], 0, v[0:1]
	v_lshl_add_u64 v[0:1], v[0:1], 0, v[12:13]
	v_lshl_add_u64 v[0:1], v[0:1], 0, v[128:129]
	s_waitcnt lgkmcnt(0)
	global_store_dwordx4 v[0:1], v[4:7], off
	v_add_u32_e32 v0, 0x380, v149
	s_nop 0
	v_ashrrev_i32_e32 v4, 3, v0
	v_ashrrev_i32_e32 v5, 31, v4
	v_mad_u64_u32 v[0:1], s[10:11], v4, s13, v[10:11]
	v_lshl_add_u64 v[4:5], v[8:9], 0, v[4:5]
	v_lshlrev_b64 v[4:5], 12, v[4:5]
	v_lshl_add_u64 v[4:5], s[26:27], 0, v[4:5]
	v_lshl_add_u64 v[4:5], v[4:5], 0, v[12:13]
	v_lshl_add_u64 v[14:15], v[4:5], 0, v[128:129]
	v_add_u32_e32 v4, 0x3c0, v149
	v_ashrrev_i32_e32 v16, 3, v4
	ds_read_b128 v[0:3], v0
	v_mad_u64_u32 v[4:5], s[10:11], v16, s13, v[10:11]
	v_readlane_b32 s10, v254, 28
	s_add_i32 s34, s34, s10
	s_ashr_i32 s10, s34, 31
	v_ashrrev_i32_e32 v17, 31, v16
	s_lshr_b32 s10, s10, 27
	ds_read_b128 v[4:7], v4
	s_waitcnt lgkmcnt(1)
	global_store_dwordx4 v[14:15], v[0:3], off
	s_add_i32 s10, s34, s10
	s_ashr_i32 s10, s10, 5
	v_lshl_add_u64 v[0:1], v[8:9], 0, v[16:17]
	v_lshlrev_b64 v[0:1], 12, v[0:1]
	v_lshl_add_u64 v[0:1], s[26:27], 0, v[0:1]
	s_lshl_b32 s10, s10, 3
	v_readlane_b32 s11, v254, 24
	v_lshl_add_u64 v[0:1], v[0:1], 0, v[12:13]
	s_or_b32 s11, s10, s11
	v_lshl_add_u64 v[0:1], v[0:1], 0, v[128:129]
	s_cmp_gt_i32 s11, 31
	s_waitcnt lgkmcnt(0)
	global_store_dwordx4 v[0:1], v[4:7], off
	s_waitcnt vmcnt(63) expcnt(7) lgkmcnt(15)
	s_barrier
	s_cbranch_scc0 .LBB0_722
